# v22 with s_setprio 1 issued before the pre-MFMA barrier so the MFMA block starts directly after barrier release
# speedup vs baseline: 1.0002x; 1.0002x over previous
; #define PG8_STAGE(bufoff, gbase, voff) do { _Pragma("unroll") for (int _i = 0; _i < 2; ++_i) \
;         __builtin_amdgcn_global_load_lds((const unsigned*)((const char*)(gbase) + (voff)[_i]), (PG8_LAS unsigned*)(lds + (bufoff) + ldsw + _i * 8192), 16, 0, 0); } while (0)
; #define PG8_LDA(dst, b, h) do { _Pragma("unroll") for (int m = 0; m < 4; ++m) _Pragma("unroll") for (int k = 0; k < 2; ++k) dst[m][k] = *(const PG8_LAS bf16x8*)(lds + PG8_SA(b, h) + aoff + m * 2048 + k * 1024); } while (0)
; #define PG8_LDB(dst, b, h) do { _Pragma("unroll") for (int n = 0; n < 2; ++n) _Pragma("unroll") for (int k = 0; k < 2; ++k) dst[n][k] = *(const PG8_LAS bf16x8*)(lds + PG8_SB(b, h) + boff + n * 2048 + k * 1024); } while (0)
; #define PG8_MMA(ai, bj, At, Bt) do { __builtin_amdgcn_s_setprio(1); _Pragma("unroll") for (int m = 0; m < 4; ++m) _Pragma("unroll") for (int n = 0; n < 2; ++n) _Pragma("unroll") for (int k = 0; k < 2; ++k) \
;         acc[ai][bj][m][n] = __builtin_amdgcn_mfma_f32_16x16x32_bf16(Bt[n][k], At[m][k], acc[ai][bj][m][n], 0, 0, 0); __builtin_amdgcn_s_setprio(0); } while (0)
; #define PG8_WAIT_V(n) asm volatile("s_waitcnt vmcnt(" #n ")" ::: "memory")
; #define PG8_WAIT_L(n) asm volatile("s_waitcnt lgkmcnt(" #n ")" ::: "memory")
; #define PG8_BAR __builtin_amdgcn_s_barrier()
; template <class Epi, class Sched, bool ALIGN_EPI = false, bool SP2 = false>
; __device__ __forceinline__ void gemm_phase(PG8_LAS unsigned char* lds, const Gemm g, const Sched& S, const Epi& E, const int wave_id) {
;     ...
;             const char* a1 = cA + (size_t)(t + 1) * kstep;
;             const char* a2 = last ? nA : cA + (size_t)(t + 2) * kstep; const char* b2 = last ? nB : cB + (size_t)(t + 2) * kstep;
;             const char* a3 = a2 + kstep; const char* b3 = b2 + kstep;
;             if (last && has_next) S.a_ready(nxt);
;             if constexpr (SP2) {
;             PG8_LDB(B0, 0, 0); PG8_LDB(B1, 0, 1); PG8_SCHED; PG8_LDA(At, 0, 0); PG8_STAGE(PG8_SA(1, 1), a1 + hstepA, voffA);
;             PG8_WAIT_V(8); PG8_WAIT_L(0); PG8_BAR; PG8_MMA(0, 0, At, B0); PG8_MMA(0, 1, At, B1); PG8_BAR; PG8_SCHED;
;             PG8_LDA(At, 0, 1); PG8_STAGE(PG8_SB(0, 0), b2, voffB); PG8_STAGE(PG8_SB(0, 1), b2 + hstepB, voffB); PG8_STAGE(PG8_SA(0, 0), a2, voffA);
;             PG8_WAIT_V(8); PG8_WAIT_L(0); PG8_BAR; PG8_MMA(1, 0, At, B0); PG8_MMA(1, 1, At, B1); PG8_BAR; PG8_SCHED;
.LBB0_35:
	s_add_u32 s28, s26, 0xfff00080
	s_addc_u32 s29, s27, -1
	s_add_i32 s86, 0, 0x10000
	s_cmp_eq_u32 s83, 60
	s_cselect_b32 s31, s0, s29
	s_cselect_b32 s30, s1, s28
	v_add_u32_e32 v0, s86, v188
	s_cselect_b32 s29, s3, s38
	s_cselect_b32 s28, s19, s21
	s_add_i32 s91, 0, 0x14000
	ds_read_b128 v[130:133], v0
	ds_read_b128 v[134:137], v0 offset:1024
	ds_read_b128 v[138:141], v0 offset:2048
	ds_read_b128 v[142:145], v0 offset:3072
	v_add_u32_e32 v0, s91, v188
	ds_read_b128 v[146:149], v0
	ds_read_b128 v[150:153], v0 offset:1024
	ds_read_b128 v[166:169], v0 offset:2048
	ds_read_b128 v[178:181], v0 offset:3072
	v_lshl_add_u64 v[186:187], s[26:27], 0, v[162:163]
	s_add_i32 m0, s9, 0xc000
	ds_read_b128 v[182:185], v194
	ds_read_b128 v[196:199], v194 offset:1024
	ds_read_b128 v[200:203], v194 offset:2048
	ds_read_b128 v[204:207], v194 offset:3072
	ds_read_b128 v[208:211], v194 offset:4096
	ds_read_b128 v[212:215], v194 offset:5120
	ds_read_b128 v[216:219], v194 offset:6144
	ds_read_b128 v[220:223], v194 offset:7168
	global_load_lds_dwordx4 v[186:187], off
	v_lshl_add_u64 v[186:187], s[26:27], 0, v[164:165]
	s_add_i32 m0, s9, 0xe000
	s_nop 0
	global_load_lds_dwordx4 v[186:187], off
	s_waitcnt vmcnt(8)
	s_waitcnt lgkmcnt(0)
	s_setprio 1
	s_barrier
	v_mfma_f32_16x16x32_bf16 v[126:129], v[130:133], v[182:185], v[126:129]
	v_mfma_f32_16x16x32_bf16 v[122:125], v[138:141], v[182:185], v[122:125]
	v_mfma_f32_16x16x32_bf16 v[110:113], v[130:133], v[200:203], v[110:113]
	v_mfma_f32_16x16x32_bf16 v[106:109], v[138:141], v[200:203], v[106:109]
	v_mfma_f32_16x16x32_bf16 v[94:97], v[130:133], v[208:211], v[94:97]
	v_mfma_f32_16x16x32_bf16 v[90:93], v[138:141], v[208:211], v[90:93]
	v_mfma_f32_16x16x32_bf16 v[78:81], v[130:133], v[216:219], v[78:81]
	v_mfma_f32_16x16x32_bf16 v[74:77], v[138:141], v[216:219], v[74:77]
	v_mfma_f32_16x16x32_bf16 v[126:129], v[134:137], v[196:199], v[126:129]
	v_mfma_f32_16x16x32_bf16 v[122:125], v[142:145], v[196:199], v[122:125]
	v_mfma_f32_16x16x32_bf16 v[110:113], v[134:137], v[204:207], v[110:113]
	v_mfma_f32_16x16x32_bf16 v[106:109], v[142:145], v[204:207], v[106:109]
	v_mfma_f32_16x16x32_bf16 v[94:97], v[134:137], v[212:215], v[94:97]
	v_mfma_f32_16x16x32_bf16 v[90:93], v[142:145], v[212:215], v[90:93]
	v_mfma_f32_16x16x32_bf16 v[78:81], v[134:137], v[220:223], v[78:81]
	v_mfma_f32_16x16x32_bf16 v[74:77], v[142:145], v[220:223], v[74:77]
	v_mfma_f32_16x16x32_bf16 v[118:121], v[146:149], v[182:185], v[118:121]
	v_mfma_f32_16x16x32_bf16 v[114:117], v[166:169], v[182:185], v[114:117]
	v_mfma_f32_16x16x32_bf16 v[102:105], v[146:149], v[200:203], v[102:105]
	v_mfma_f32_16x16x32_bf16 v[98:101], v[166:169], v[200:203], v[98:101]
	v_mfma_f32_16x16x32_bf16 v[86:89], v[146:149], v[208:211], v[86:89]
	v_mfma_f32_16x16x32_bf16 v[82:85], v[166:169], v[208:211], v[82:85]
	v_mfma_f32_16x16x32_bf16 v[70:73], v[146:149], v[216:219], v[70:73]
	v_mfma_f32_16x16x32_bf16 v[66:69], v[166:169], v[216:219], v[66:69]
	v_mfma_f32_16x16x32_bf16 v[118:121], v[150:153], v[196:199], v[118:121]
	v_mfma_f32_16x16x32_bf16 v[114:117], v[178:181], v[196:199], v[114:117]
	v_mfma_f32_16x16x32_bf16 v[102:105], v[150:153], v[204:207], v[102:105]
	v_mfma_f32_16x16x32_bf16 v[98:101], v[178:181], v[204:207], v[98:101]
	v_mfma_f32_16x16x32_bf16 v[86:89], v[150:153], v[212:215], v[86:89]
	v_mfma_f32_16x16x32_bf16 v[82:85], v[178:181], v[212:215], v[82:85]
	v_mfma_f32_16x16x32_bf16 v[70:73], v[150:153], v[220:223], v[70:73]
	v_mfma_f32_16x16x32_bf16 v[66:69], v[178:181], v[220:223], v[66:69]
	s_setprio 0
	s_barrier
	s_add_i32 s86, s86, s14
	v_lshl_add_u64 v[186:187], s[28:29], 0, v[156:157]
	s_mov_b32 m0, s86
	ds_read_b128 v[182:185], v194 offset:16384
	ds_read_b128 v[196:199], v194 offset:17408
	ds_read_b128 v[200:203], v194 offset:18432
	ds_read_b128 v[204:207], v194 offset:19456
	ds_read_b128 v[208:211], v194 offset:20480
	ds_read_b128 v[212:215], v194 offset:21504
	ds_read_b128 v[216:219], v194 offset:22528
	ds_read_b128 v[220:223], v194 offset:23552
	global_load_lds_dwordx4 v[186:187], off
	s_add_i32 m0, s86, 0x2000
	s_add_u32 s86, s28, 0x100000
	v_lshl_add_u64 v[224:225], s[28:29], 0, v[160:161]
	s_addc_u32 s87, s29, 0
	s_add_i32 s91, s91, s14
	global_load_lds_dwordx4 v[224:225], off
	v_lshl_add_u64 v[234:235], s[86:87], 0, v[156:157]
	s_mov_b32 m0, s91
	v_lshl_add_u64 v[236:237], s[30:31], 0, v[158:159]
	global_load_lds_dwordx4 v[234:235], off
	v_lshl_add_u64 v[234:235], s[86:87], 0, v[160:161]
	s_add_i32 m0, s91, 0x2000
	s_nop 0
	global_load_lds_dwordx4 v[234:235], off
	v_lshl_add_u64 v[234:235], s[30:31], 0, v[154:155]
	s_mov_b32 m0, s9
	s_nop 0
	global_load_lds_dwordx4 v[234:235], off
	s_mov_b32 m0, s15
	s_nop 0
	global_load_lds_dwordx4 v[236:237], off
	s_waitcnt vmcnt(8)
	s_waitcnt lgkmcnt(0)
	s_setprio 1
	s_barrier
; #define PG8_STAGE(bufoff, gbase, voff) do { _Pragma("unroll") for (int _i = 0; _i < 2; ++_i) \
;         __builtin_amdgcn_global_load_lds((const unsigned*)((const char*)(gbase) + (voff)[_i]), (PG8_LAS unsigned*)(lds + (bufoff) + ldsw + _i * 8192), 16, 0, 0); } while (0)
; #define PG8_LDA(dst, b, h) do { _Pragma("unroll") for (int m = 0; m < 4; ++m) _Pragma("unroll") for (int k = 0; k < 2; ++k) dst[m][k] = *(const PG8_LAS bf16x8*)(lds + PG8_SA(b, h) + aoff + m * 2048 + k * 1024); } while (0)
; #define PG8_LDB(dst, b, h) do { _Pragma("unroll") for (int n = 0; n < 2; ++n) _Pragma("unroll") for (int k = 0; k < 2; ++k) dst[n][k] = *(const PG8_LAS bf16x8*)(lds + PG8_SB(b, h) + boff + n * 2048 + k * 1024); } while (0)
; #define PG8_MMA(ai, bj, At, Bt) do { __builtin_amdgcn_s_setprio(1); _Pragma("unroll") for (int m = 0; m < 4; ++m) _Pragma("unroll") for (int n = 0; n < 2; ++n) _Pragma("unroll") for (int k = 0; k < 2; ++k) \
;         acc[ai][bj][m][n] = __builtin_amdgcn_mfma_f32_16x16x32_bf16(Bt[n][k], At[m][k], acc[ai][bj][m][n], 0, 0, 0); __builtin_amdgcn_s_setprio(0); } while (0)
; #define PG8_WAIT_V(n) asm volatile("s_waitcnt vmcnt(" #n ")" ::: "memory")
; #define PG8_WAIT_L(n) asm volatile("s_waitcnt lgkmcnt(" #n ")" ::: "memory")
; #define PG8_BAR __builtin_amdgcn_s_barrier()
; #define PG8_SCHED __builtin_amdgcn_sched_barrier(0)
; template <class Epi, class Sched, bool ALIGN_EPI = false, bool SP2 = false>
; __device__ __forceinline__ void gemm_phase(PG8_LAS unsigned char* lds, const Gemm g, const Sched& S, const Epi& E, const int wave_id) {
;     ...
;             PG8_WAIT_V(8); PG8_WAIT_L(0); PG8_BAR; PG8_MMA(1, 0, At, B0); PG8_MMA(1, 1, At, B1); PG8_BAR; PG8_SCHED;
;             PG8_LDB(B0, 1, 0); PG8_LDB(B1, 1, 1); PG8_SCHED; PG8_LDA(At, 1, 0); PG8_STAGE(PG8_SA(0, 1), a2 + hstepA, voffA);
;             PG8_WAIT_V(8); PG8_WAIT_L(0); PG8_BAR; PG8_MMA(0, 0, At, B0); PG8_MMA(0, 1, At, B1); PG8_BAR; PG8_SCHED;
	v_mfma_f32_16x16x32_bf16 v[62:65], v[130:133], v[182:185], v[62:65]
	v_mfma_f32_16x16x32_bf16 v[58:61], v[138:141], v[182:185], v[58:61]
	v_mfma_f32_16x16x32_bf16 v[46:49], v[130:133], v[200:203], v[46:49]
	v_mfma_f32_16x16x32_bf16 v[42:45], v[138:141], v[200:203], v[42:45]
	v_mfma_f32_16x16x32_bf16 v[30:33], v[130:133], v[208:211], v[30:33]
	v_mfma_f32_16x16x32_bf16 v[26:29], v[138:141], v[208:211], v[26:29]
	v_mfma_f32_16x16x32_bf16 v[14:17], v[130:133], v[216:219], v[14:17]
	v_mfma_f32_16x16x32_bf16 v[10:13], v[138:141], v[216:219], v[10:13]
	v_mfma_f32_16x16x32_bf16 v[62:65], v[134:137], v[196:199], v[62:65]
	v_mfma_f32_16x16x32_bf16 v[58:61], v[142:145], v[196:199], v[58:61]
	v_mfma_f32_16x16x32_bf16 v[46:49], v[134:137], v[204:207], v[46:49]
	v_mfma_f32_16x16x32_bf16 v[42:45], v[142:145], v[204:207], v[42:45]
	v_mfma_f32_16x16x32_bf16 v[30:33], v[134:137], v[212:215], v[30:33]
	v_mfma_f32_16x16x32_bf16 v[26:29], v[142:145], v[212:215], v[26:29]
	v_mfma_f32_16x16x32_bf16 v[14:17], v[134:137], v[220:223], v[14:17]
	v_mfma_f32_16x16x32_bf16 v[10:13], v[142:145], v[220:223], v[10:13]
	v_mfma_f32_16x16x32_bf16 v[54:57], v[146:149], v[182:185], v[54:57]
	v_mfma_f32_16x16x32_bf16 v[50:53], v[166:169], v[182:185], v[50:53]
	v_mfma_f32_16x16x32_bf16 v[38:41], v[146:149], v[200:203], v[38:41]
	v_mfma_f32_16x16x32_bf16 v[34:37], v[166:169], v[200:203], v[34:37]
	v_mfma_f32_16x16x32_bf16 v[22:25], v[146:149], v[208:211], v[22:25]
	v_mfma_f32_16x16x32_bf16 v[18:21], v[166:169], v[208:211], v[18:21]
	v_mfma_f32_16x16x32_bf16 v[6:9], v[146:149], v[216:219], v[6:9]
	v_mfma_f32_16x16x32_bf16 v[2:5], v[166:169], v[216:219], v[2:5]
	v_mfma_f32_16x16x32_bf16 v[54:57], v[150:153], v[196:199], v[54:57]
	v_mfma_f32_16x16x32_bf16 v[50:53], v[178:181], v[196:199], v[50:53]
	v_mfma_f32_16x16x32_bf16 v[38:41], v[150:153], v[204:207], v[38:41]
	v_mfma_f32_16x16x32_bf16 v[34:37], v[178:181], v[204:207], v[34:37]
	v_mfma_f32_16x16x32_bf16 v[22:25], v[150:153], v[212:215], v[22:25]
	v_mfma_f32_16x16x32_bf16 v[18:21], v[178:181], v[212:215], v[18:21]
	v_mfma_f32_16x16x32_bf16 v[6:9], v[150:153], v[220:223], v[6:9]
	v_mfma_f32_16x16x32_bf16 v[2:5], v[178:181], v[220:223], v[2:5]
	s_setprio 0
	s_barrier
	s_add_i32 s86, 0, 0x18000
	v_add_u32_e32 v0, s86, v188
	s_add_i32 s87, 0, 0x1c000
	ds_read_b128 v[130:133], v0
	ds_read_b128 v[134:137], v0 offset:1024
	ds_read_b128 v[138:141], v0 offset:2048
	ds_read_b128 v[142:145], v0 offset:3072
	v_add_u32_e32 v0, s87, v188
	ds_read_b128 v[146:149], v0
	ds_read_b128 v[150:153], v0 offset:1024
	ds_read_b128 v[166:169], v0 offset:2048
	ds_read_b128 v[178:181], v0 offset:3072
	s_add_u32 s30, s30, 0x100000
	s_addc_u32 s31, s31, 0
	s_mov_b32 m0, s34
	v_lshl_add_u64 v[240:241], s[30:31], 0, v[154:155]
	ds_read_b128 v[182:185], v194 offset:32768
	ds_read_b128 v[196:199], v194 offset:33792
	ds_read_b128 v[200:203], v194 offset:34816
	ds_read_b128 v[204:207], v194 offset:35840
	ds_read_b128 v[208:211], v194 offset:36864
	ds_read_b128 v[212:215], v194 offset:37888
	ds_read_b128 v[216:219], v194 offset:38912
	ds_read_b128 v[220:223], v194 offset:39936
	global_load_lds_dwordx4 v[240:241], off
	v_lshl_add_u64 v[240:241], s[30:31], 0, v[158:159]
	s_mov_b32 m0, s35
	s_nop 0
	global_load_lds_dwordx4 v[240:241], off
	s_waitcnt vmcnt(8)
	s_waitcnt lgkmcnt(0)
	s_setprio 1
	s_barrier
	v_mfma_f32_16x16x32_bf16 v[126:129], v[130:133], v[182:185], v[126:129]
	v_mfma_f32_16x16x32_bf16 v[122:125], v[138:141], v[182:185], v[122:125]
	v_mfma_f32_16x16x32_bf16 v[110:113], v[130:133], v[200:203], v[110:113]
	v_mfma_f32_16x16x32_bf16 v[106:109], v[138:141], v[200:203], v[106:109]
	v_mfma_f32_16x16x32_bf16 v[94:97], v[130:133], v[208:211], v[94:97]
	v_mfma_f32_16x16x32_bf16 v[90:93], v[138:141], v[208:211], v[90:93]
	v_mfma_f32_16x16x32_bf16 v[78:81], v[130:133], v[216:219], v[78:81]
	v_mfma_f32_16x16x32_bf16 v[74:77], v[138:141], v[216:219], v[74:77]
	v_mfma_f32_16x16x32_bf16 v[126:129], v[134:137], v[196:199], v[126:129]
	v_mfma_f32_16x16x32_bf16 v[122:125], v[142:145], v[196:199], v[122:125]
	v_mfma_f32_16x16x32_bf16 v[110:113], v[134:137], v[204:207], v[110:113]
	v_mfma_f32_16x16x32_bf16 v[106:109], v[142:145], v[204:207], v[106:109]
	v_mfma_f32_16x16x32_bf16 v[94:97], v[134:137], v[212:215], v[94:97]
	v_mfma_f32_16x16x32_bf16 v[90:93], v[142:145], v[212:215], v[90:93]
	v_mfma_f32_16x16x32_bf16 v[78:81], v[134:137], v[220:223], v[78:81]
	v_mfma_f32_16x16x32_bf16 v[74:77], v[142:145], v[220:223], v[74:77]
	v_mfma_f32_16x16x32_bf16 v[118:121], v[146:149], v[182:185], v[118:121]
	v_mfma_f32_16x16x32_bf16 v[114:117], v[166:169], v[182:185], v[114:117]
	v_mfma_f32_16x16x32_bf16 v[102:105], v[146:149], v[200:203], v[102:105]
	v_mfma_f32_16x16x32_bf16 v[98:101], v[166:169], v[200:203], v[98:101]
	v_mfma_f32_16x16x32_bf16 v[86:89], v[146:149], v[208:211], v[86:89]
	v_mfma_f32_16x16x32_bf16 v[82:85], v[166:169], v[208:211], v[82:85]
	v_mfma_f32_16x16x32_bf16 v[70:73], v[146:149], v[216:219], v[70:73]
	v_mfma_f32_16x16x32_bf16 v[66:69], v[166:169], v[216:219], v[66:69]
	v_mfma_f32_16x16x32_bf16 v[118:121], v[150:153], v[196:199], v[118:121]
	v_mfma_f32_16x16x32_bf16 v[114:117], v[178:181], v[196:199], v[114:117]
	v_mfma_f32_16x16x32_bf16 v[102:105], v[150:153], v[204:207], v[102:105]
	v_mfma_f32_16x16x32_bf16 v[98:101], v[178:181], v[204:207], v[98:101]
	v_mfma_f32_16x16x32_bf16 v[86:89], v[150:153], v[212:215], v[86:89]
	v_mfma_f32_16x16x32_bf16 v[82:85], v[178:181], v[212:215], v[82:85]
	v_mfma_f32_16x16x32_bf16 v[70:73], v[150:153], v[220:223], v[70:73]
	v_mfma_f32_16x16x32_bf16 v[66:69], v[178:181], v[220:223], v[66:69]
	s_setprio 0
	s_barrier
; #define PG8_STAGE(bufoff, gbase, voff) do { _Pragma("unroll") for (int _i = 0; _i < 2; ++_i) \
;         __builtin_amdgcn_global_load_lds((const unsigned*)((const char*)(gbase) + (voff)[_i]), (PG8_LAS unsigned*)(lds + (bufoff) + ldsw + _i * 8192), 16, 0, 0); } while (0)
; #define PG8_LDA(dst, b, h) do { _Pragma("unroll") for (int m = 0; m < 4; ++m) _Pragma("unroll") for (int k = 0; k < 2; ++k) dst[m][k] = *(const PG8_LAS bf16x8*)(lds + PG8_SA(b, h) + aoff + m * 2048 + k * 1024); } while (0)
; #define PG8_MMA(ai, bj, At, Bt) do { __builtin_amdgcn_s_setprio(1); _Pragma("unroll") for (int m = 0; m < 4; ++m) _Pragma("unroll") for (int n = 0; n < 2; ++n) _Pragma("unroll") for (int k = 0; k < 2; ++k) \
;         acc[ai][bj][m][n] = __builtin_amdgcn_mfma_f32_16x16x32_bf16(Bt[n][k], At[m][k], acc[ai][bj][m][n], 0, 0, 0); __builtin_amdgcn_s_setprio(0); } while (0)
; #define PG8_WAIT_V(n) asm volatile("s_waitcnt vmcnt(" #n ")" ::: "memory")
; #define PG8_WAIT_L(n) asm volatile("s_waitcnt lgkmcnt(" #n ")" ::: "memory")
; #define PG8_BAR __builtin_amdgcn_s_barrier()
; #define PG8_SCHED __builtin_amdgcn_sched_barrier(0)
; template <class Epi, class Sched, bool ALIGN_EPI = false, bool SP2 = false>
; __device__ __forceinline__ void gemm_phase(PG8_LAS unsigned char* lds, const Gemm g, const Sched& S, const Epi& E, const int wave_id) {
;     ...
;         for (int t = 0; t < nt; t += 2) {
;     ...
;             PG8_LDA(At, 1, 1); PG8_STAGE(PG8_SB(1, 0), b3, voffB); PG8_STAGE(PG8_SB(1, 1), b3 + hstepB, voffB); PG8_STAGE(PG8_SA(1, 0), a3, voffA);
;             PG8_WAIT_V(8); PG8_WAIT_L(0); PG8_BAR; PG8_MMA(1, 0, At, B0); PG8_MMA(1, 1, At, B1); PG8_BAR; PG8_SCHED;
	s_add_i32 s30, s86, s14
	v_lshl_add_u64 v[186:187], v[186:187], 0, s[62:63]
	s_mov_b32 m0, s30
	ds_read_b128 v[182:185], v194 offset:49152
	ds_read_b128 v[196:199], v194 offset:50176
	ds_read_b128 v[200:203], v194 offset:51200
	ds_read_b128 v[204:207], v194 offset:52224
	ds_read_b128 v[208:211], v194 offset:53248
	ds_read_b128 v[212:215], v194 offset:54272
	ds_read_b128 v[216:219], v194 offset:55296
	ds_read_b128 v[220:223], v194 offset:56320
	global_load_lds_dwordx4 v[186:187], off
	s_add_i32 m0, s30, 0x2000
	s_add_u32 s28, s28, 0x100080
	v_lshl_add_u64 v[186:187], v[224:225], 0, s[62:63]
	s_addc_u32 s29, s29, 0
	s_add_i32 s30, s87, s14
	global_load_lds_dwordx4 v[186:187], off
	v_lshl_add_u64 v[186:187], s[28:29], 0, v[156:157]
	s_mov_b32 m0, s30
	s_nop 0
	global_load_lds_dwordx4 v[186:187], off
	v_lshl_add_u64 v[186:187], s[28:29], 0, v[160:161]
	s_add_i32 m0, s30, 0x2000
	s_nop 0
	global_load_lds_dwordx4 v[186:187], off
	v_lshl_add_u64 v[186:187], v[234:235], 0, s[62:63]
	s_mov_b32 m0, s50
	s_nop 0
	global_load_lds_dwordx4 v[186:187], off
	v_lshl_add_u64 v[186:187], v[236:237], 0, s[62:63]
	s_mov_b32 m0, s76
	s_nop 0
	global_load_lds_dwordx4 v[186:187], off
	s_waitcnt vmcnt(8)
	s_waitcnt lgkmcnt(0)
	s_setprio 1
	s_barrier
	v_mfma_f32_16x16x32_bf16 v[62:65], v[130:133], v[182:185], v[62:65]
	v_mfma_f32_16x16x32_bf16 v[58:61], v[138:141], v[182:185], v[58:61]
	v_mfma_f32_16x16x32_bf16 v[46:49], v[130:133], v[200:203], v[46:49]
	v_mfma_f32_16x16x32_bf16 v[42:45], v[138:141], v[200:203], v[42:45]
	v_mfma_f32_16x16x32_bf16 v[30:33], v[130:133], v[208:211], v[30:33]
	v_mfma_f32_16x16x32_bf16 v[26:29], v[138:141], v[208:211], v[26:29]
	v_mfma_f32_16x16x32_bf16 v[14:17], v[130:133], v[216:219], v[14:17]
	v_mfma_f32_16x16x32_bf16 v[10:13], v[138:141], v[216:219], v[10:13]
	v_mfma_f32_16x16x32_bf16 v[62:65], v[134:137], v[196:199], v[62:65]
	v_mfma_f32_16x16x32_bf16 v[58:61], v[142:145], v[196:199], v[58:61]
	v_mfma_f32_16x16x32_bf16 v[46:49], v[134:137], v[204:207], v[46:49]
	v_mfma_f32_16x16x32_bf16 v[42:45], v[142:145], v[204:207], v[42:45]
	v_mfma_f32_16x16x32_bf16 v[30:33], v[134:137], v[212:215], v[30:33]
	v_mfma_f32_16x16x32_bf16 v[26:29], v[142:145], v[212:215], v[26:29]
	v_mfma_f32_16x16x32_bf16 v[14:17], v[134:137], v[220:223], v[14:17]
	v_mfma_f32_16x16x32_bf16 v[10:13], v[142:145], v[220:223], v[10:13]
	v_mfma_f32_16x16x32_bf16 v[54:57], v[146:149], v[182:185], v[54:57]
	v_mfma_f32_16x16x32_bf16 v[50:53], v[166:169], v[182:185], v[50:53]
	v_mfma_f32_16x16x32_bf16 v[38:41], v[146:149], v[200:203], v[38:41]
	v_mfma_f32_16x16x32_bf16 v[34:37], v[166:169], v[200:203], v[34:37]
	v_mfma_f32_16x16x32_bf16 v[22:25], v[146:149], v[208:211], v[22:25]
	v_mfma_f32_16x16x32_bf16 v[18:21], v[166:169], v[208:211], v[18:21]
	v_mfma_f32_16x16x32_bf16 v[6:9], v[146:149], v[216:219], v[6:9]
	v_mfma_f32_16x16x32_bf16 v[2:5], v[166:169], v[216:219], v[2:5]
	v_mfma_f32_16x16x32_bf16 v[54:57], v[150:153], v[196:199], v[54:57]
	v_mfma_f32_16x16x32_bf16 v[50:53], v[178:181], v[196:199], v[50:53]
	v_mfma_f32_16x16x32_bf16 v[38:41], v[150:153], v[204:207], v[38:41]
	v_mfma_f32_16x16x32_bf16 v[34:37], v[178:181], v[204:207], v[34:37]
	v_mfma_f32_16x16x32_bf16 v[22:25], v[150:153], v[212:215], v[22:25]
	v_mfma_f32_16x16x32_bf16 v[18:21], v[178:181], v[212:215], v[18:21]
	v_mfma_f32_16x16x32_bf16 v[6:9], v[150:153], v[220:223], v[6:9]
	v_mfma_f32_16x16x32_bf16 v[2:5], v[178:181], v[220:223], v[2:5]
	s_setprio 0
	s_barrier
	s_add_i32 s83, s83, 2
	s_add_u32 s26, s26, 0x100
	s_addc_u32 s27, s27, 0
	s_add_u32 s21, s21, 0x100
	s_addc_u32 s38, s38, 0
	s_cmp_gt_u32 s83, 61
	s_cbranch_scc0 .LBB0_35
	s_and_b64 vcc, exec, s[16:17]
	s_cbranch_vccz .LBB0_38
	s_barrier

; #define PG8_STAGE(bufoff, gbase, voff) do { _Pragma("unroll") for (int _i = 0; _i < 2; ++_i) \
;         __builtin_amdgcn_global_load_lds((const unsigned*)((const char*)(gbase) + (voff)[_i]), (PG8_LAS unsigned*)(lds + (bufoff) + ldsw + _i * 8192), 16, 0, 0); } while (0)
; #define PG8_LDA(dst, b, h) do { _Pragma("unroll") for (int m = 0; m < 4; ++m) _Pragma("unroll") for (int k = 0; k < 2; ++k) dst[m][k] = *(const PG8_LAS bf16x8*)(lds + PG8_SA(b, h) + aoff + m * 2048 + k * 1024); } while (0)
; #define PG8_LDB(dst, b, h) do { _Pragma("unroll") for (int n = 0; n < 2; ++n) _Pragma("unroll") for (int k = 0; k < 2; ++k) dst[n][k] = *(const PG8_LAS bf16x8*)(lds + PG8_SB(b, h) + boff + n * 2048 + k * 1024); } while (0)
; #define PG8_MMA(ai, bj, At, Bt) do { __builtin_amdgcn_s_setprio(1); _Pragma("unroll") for (int m = 0; m < 4; ++m) _Pragma("unroll") for (int n = 0; n < 2; ++n) _Pragma("unroll") for (int k = 0; k < 2; ++k) \
;         acc[ai][bj][m][n] = __builtin_amdgcn_mfma_f32_16x16x32_bf16(Bt[n][k], At[m][k], acc[ai][bj][m][n], 0, 0, 0); __builtin_amdgcn_s_setprio(0); } while (0)
; #define PG8_WAIT_V(n) asm volatile("s_waitcnt vmcnt(" #n ")" ::: "memory")
; #define PG8_WAIT_L(n) asm volatile("s_waitcnt lgkmcnt(" #n ")" ::: "memory")
; #define PG8_BAR __builtin_amdgcn_s_barrier()
; template <class Epi, class Sched, bool ALIGN_EPI = false, bool SP2 = false>
; __device__ __forceinline__ void gemm_phase(PG8_LAS unsigned char* lds, const Gemm g, const Sched& S, const Epi& E, const int wave_id) {
;     ...
;             const char* a1 = cA + (size_t)(t + 1) * kstep;
;             const char* a2 = last ? nA : cA + (size_t)(t + 2) * kstep; const char* b2 = last ? nB : cB + (size_t)(t + 2) * kstep;
;             const char* a3 = a2 + kstep; const char* b3 = b2 + kstep;
;             if (last && has_next) S.a_ready(nxt);
;             if constexpr (SP2) {
;             PG8_LDB(B0, 0, 0); PG8_LDB(B1, 0, 1); PG8_SCHED; PG8_LDA(At, 0, 0); PG8_STAGE(PG8_SA(1, 1), a1 + hstepA, voffA);
;             PG8_WAIT_V(8); PG8_WAIT_L(0); PG8_BAR; PG8_MMA(0, 0, At, B0); PG8_MMA(0, 1, At, B1); PG8_BAR; PG8_SCHED;
;             PG8_LDA(At, 0, 1); PG8_STAGE(PG8_SB(0, 0), b2, voffB); PG8_STAGE(PG8_SB(0, 1), b2 + hstepB, voffB); PG8_STAGE(PG8_SA(0, 0), a2, voffA);
;             PG8_WAIT_V(8); PG8_WAIT_L(0); PG8_BAR; PG8_MMA(1, 0, At, B0); PG8_MMA(1, 1, At, B1); PG8_BAR; PG8_SCHED;
.LBB0_69:
	s_add_u32 s18, s16, 0xfff00080
	s_addc_u32 s19, s17, -1
	s_add_i32 s39, 0, 0x10000
	s_cmp_eq_u32 s38, 4
	s_cselect_b32 s21, s30, s19
	s_cselect_b32 s20, s31, s18
	v_add_u32_e32 v0, s39, v139
	s_cselect_b32 s19, s34, s37
	s_cselect_b32 s18, s35, s36
	s_add_i32 s50, 0, 0x14000
	ds_read_b128 v[142:145], v0
	ds_read_b128 v[146:149], v0 offset:1024
	ds_read_b128 v[150:153], v0 offset:2048
	ds_read_b128 v[154:157], v0 offset:3072
	v_add_u32_e32 v0, s50, v139
	ds_read_b128 v[158:161], v0
	ds_read_b128 v[162:165], v0 offset:1024
	ds_read_b128 v[166:169], v0 offset:2048
	ds_read_b128 v[178:181], v0 offset:3072
	v_lshl_add_u64 v[214:215], s[16:17], 0, v[134:135]
	s_add_i32 m0, s3, 0xc000
	ds_read_b128 v[182:185], v141
	ds_read_b128 v[186:189], v141 offset:1024
	ds_read_b128 v[190:193], v141 offset:2048
	ds_read_b128 v[194:197], v141 offset:3072
	ds_read_b128 v[198:201], v141 offset:4096
	ds_read_b128 v[202:205], v141 offset:5120
	ds_read_b128 v[206:209], v141 offset:6144
	ds_read_b128 v[210:213], v141 offset:7168
	global_load_lds_dwordx4 v[214:215], off
	v_lshl_add_u64 v[214:215], s[16:17], 0, v[136:137]
	s_add_i32 m0, s3, 0xe000
	s_nop 0
	global_load_lds_dwordx4 v[214:215], off
	s_waitcnt vmcnt(8)
	s_waitcnt lgkmcnt(0)
	s_setprio 1
	s_barrier
	v_mfma_f32_16x16x32_bf16 v[126:129], v[142:145], v[182:185], v[126:129]
	v_mfma_f32_16x16x32_bf16 v[122:125], v[150:153], v[182:185], v[122:125]
	v_mfma_f32_16x16x32_bf16 v[118:121], v[142:145], v[190:193], v[118:121]
	v_mfma_f32_16x16x32_bf16 v[114:117], v[150:153], v[190:193], v[114:117]
	v_mfma_f32_16x16x32_bf16 v[106:109], v[142:145], v[198:201], v[106:109]
	v_mfma_f32_16x16x32_bf16 v[98:101], v[150:153], v[198:201], v[98:101]
	v_mfma_f32_16x16x32_bf16 v[90:93], v[142:145], v[206:209], v[90:93]
	v_mfma_f32_16x16x32_bf16 v[82:85], v[150:153], v[206:209], v[82:85]
	v_mfma_f32_16x16x32_bf16 v[126:129], v[146:149], v[186:189], v[126:129]
	v_mfma_f32_16x16x32_bf16 v[122:125], v[154:157], v[186:189], v[122:125]
	v_mfma_f32_16x16x32_bf16 v[118:121], v[146:149], v[194:197], v[118:121]
	v_mfma_f32_16x16x32_bf16 v[114:117], v[154:157], v[194:197], v[114:117]
	v_mfma_f32_16x16x32_bf16 v[106:109], v[146:149], v[202:205], v[106:109]
	v_mfma_f32_16x16x32_bf16 v[98:101], v[154:157], v[202:205], v[98:101]
	v_mfma_f32_16x16x32_bf16 v[90:93], v[146:149], v[210:213], v[90:93]
	v_mfma_f32_16x16x32_bf16 v[82:85], v[154:157], v[210:213], v[82:85]
	v_mfma_f32_16x16x32_bf16 v[110:113], v[158:161], v[182:185], v[110:113]
	v_mfma_f32_16x16x32_bf16 v[102:105], v[166:169], v[182:185], v[102:105]
	v_mfma_f32_16x16x32_bf16 v[94:97], v[158:161], v[190:193], v[94:97]
	v_mfma_f32_16x16x32_bf16 v[86:89], v[166:169], v[190:193], v[86:89]
	v_mfma_f32_16x16x32_bf16 v[78:81], v[158:161], v[198:201], v[78:81]
	v_mfma_f32_16x16x32_bf16 v[74:77], v[166:169], v[198:201], v[74:77]
	v_mfma_f32_16x16x32_bf16 v[70:73], v[158:161], v[206:209], v[70:73]
	v_mfma_f32_16x16x32_bf16 v[66:69], v[166:169], v[206:209], v[66:69]
	v_mfma_f32_16x16x32_bf16 v[110:113], v[162:165], v[186:189], v[110:113]
	v_mfma_f32_16x16x32_bf16 v[102:105], v[178:181], v[186:189], v[102:105]
	v_mfma_f32_16x16x32_bf16 v[94:97], v[162:165], v[194:197], v[94:97]
	v_mfma_f32_16x16x32_bf16 v[86:89], v[178:181], v[194:197], v[86:89]
	v_mfma_f32_16x16x32_bf16 v[78:81], v[162:165], v[202:205], v[78:81]
	v_mfma_f32_16x16x32_bf16 v[74:77], v[178:181], v[202:205], v[74:77]
	v_mfma_f32_16x16x32_bf16 v[70:73], v[162:165], v[210:213], v[70:73]
	v_mfma_f32_16x16x32_bf16 v[66:69], v[178:181], v[210:213], v[66:69]
	s_setprio 0
	s_barrier
	s_add_i32 s39, s39, s0
	v_lshl_add_u64 v[214:215], s[18:19], 0, v[132:133]
	s_mov_b32 m0, s39
	ds_read_b128 v[182:185], v141 offset:16384
	ds_read_b128 v[186:189], v141 offset:17408
	ds_read_b128 v[190:193], v141 offset:18432
	ds_read_b128 v[194:197], v141 offset:19456
	ds_read_b128 v[198:201], v141 offset:20480
	ds_read_b128 v[202:205], v141 offset:21504
	ds_read_b128 v[206:209], v141 offset:22528
	ds_read_b128 v[210:213], v141 offset:23552
	global_load_lds_dwordx4 v[214:215], off
	s_add_i32 m0, s39, 0x2000
	s_add_u32 s44, s18, 0x100000
	v_lshl_add_u64 v[216:217], s[18:19], 0, v[130:131]
	s_addc_u32 s45, s19, 0
	s_add_i32 s39, s50, s0
	global_load_lds_dwordx4 v[216:217], off
	v_lshl_add_u64 v[218:219], s[44:45], 0, v[132:133]
	s_mov_b32 m0, s39
	v_lshl_add_u64 v[220:221], s[20:21], 0, v[130:131]
	global_load_lds_dwordx4 v[218:219], off
	v_lshl_add_u64 v[218:219], s[44:45], 0, v[130:131]
	s_add_i32 m0, s39, 0x2000
	s_nop 0
	global_load_lds_dwordx4 v[218:219], off
	v_lshl_add_u64 v[218:219], s[20:21], 0, v[132:133]
	s_mov_b32 m0, s3
	s_nop 0
	global_load_lds_dwordx4 v[218:219], off
	s_mov_b32 m0, s15
	s_nop 0
	global_load_lds_dwordx4 v[220:221], off
	s_waitcnt vmcnt(8)
	s_waitcnt lgkmcnt(0)
	s_setprio 1
	s_barrier
; #define PG8_STAGE(bufoff, gbase, voff) do { _Pragma("unroll") for (int _i = 0; _i < 2; ++_i) \
;         __builtin_amdgcn_global_load_lds((const unsigned*)((const char*)(gbase) + (voff)[_i]), (PG8_LAS unsigned*)(lds + (bufoff) + ldsw + _i * 8192), 16, 0, 0); } while (0)
; #define PG8_LDA(dst, b, h) do { _Pragma("unroll") for (int m = 0; m < 4; ++m) _Pragma("unroll") for (int k = 0; k < 2; ++k) dst[m][k] = *(const PG8_LAS bf16x8*)(lds + PG8_SA(b, h) + aoff + m * 2048 + k * 1024); } while (0)
; #define PG8_LDB(dst, b, h) do { _Pragma("unroll") for (int n = 0; n < 2; ++n) _Pragma("unroll") for (int k = 0; k < 2; ++k) dst[n][k] = *(const PG8_LAS bf16x8*)(lds + PG8_SB(b, h) + boff + n * 2048 + k * 1024); } while (0)
; #define PG8_MMA(ai, bj, At, Bt) do { __builtin_amdgcn_s_setprio(1); _Pragma("unroll") for (int m = 0; m < 4; ++m) _Pragma("unroll") for (int n = 0; n < 2; ++n) _Pragma("unroll") for (int k = 0; k < 2; ++k) \
;         acc[ai][bj][m][n] = __builtin_amdgcn_mfma_f32_16x16x32_bf16(Bt[n][k], At[m][k], acc[ai][bj][m][n], 0, 0, 0); __builtin_amdgcn_s_setprio(0); } while (0)
; #define PG8_WAIT_V(n) asm volatile("s_waitcnt vmcnt(" #n ")" ::: "memory")
; #define PG8_WAIT_L(n) asm volatile("s_waitcnt lgkmcnt(" #n ")" ::: "memory")
; #define PG8_BAR __builtin_amdgcn_s_barrier()
; #define PG8_SCHED __builtin_amdgcn_sched_barrier(0)
; template <class Epi, class Sched, bool ALIGN_EPI = false, bool SP2 = false>
; __device__ __forceinline__ void gemm_phase(PG8_LAS unsigned char* lds, const Gemm g, const Sched& S, const Epi& E, const int wave_id) {
;     ...
;             PG8_WAIT_V(8); PG8_WAIT_L(0); PG8_BAR; PG8_MMA(1, 0, At, B0); PG8_MMA(1, 1, At, B1); PG8_BAR; PG8_SCHED;
;             PG8_LDB(B0, 1, 0); PG8_LDB(B1, 1, 1); PG8_SCHED; PG8_LDA(At, 1, 0); PG8_STAGE(PG8_SA(0, 1), a2 + hstepA, voffA);
;             PG8_WAIT_V(8); PG8_WAIT_L(0); PG8_BAR; PG8_MMA(0, 0, At, B0); PG8_MMA(0, 1, At, B1); PG8_BAR; PG8_SCHED;
	v_mfma_f32_16x16x32_bf16 v[62:65], v[142:145], v[182:185], v[62:65]
	v_mfma_f32_16x16x32_bf16 v[58:61], v[150:153], v[182:185], v[58:61]
	v_mfma_f32_16x16x32_bf16 v[54:57], v[142:145], v[190:193], v[54:57]
	v_mfma_f32_16x16x32_bf16 v[50:53], v[150:153], v[190:193], v[50:53]
	v_mfma_f32_16x16x32_bf16 v[42:45], v[142:145], v[198:201], v[42:45]
	v_mfma_f32_16x16x32_bf16 v[34:37], v[150:153], v[198:201], v[34:37]
	v_mfma_f32_16x16x32_bf16 v[26:29], v[142:145], v[206:209], v[26:29]
	v_mfma_f32_16x16x32_bf16 v[18:21], v[150:153], v[206:209], v[18:21]
	v_mfma_f32_16x16x32_bf16 v[62:65], v[146:149], v[186:189], v[62:65]
	v_mfma_f32_16x16x32_bf16 v[58:61], v[154:157], v[186:189], v[58:61]
	v_mfma_f32_16x16x32_bf16 v[54:57], v[146:149], v[194:197], v[54:57]
	v_mfma_f32_16x16x32_bf16 v[50:53], v[154:157], v[194:197], v[50:53]
	v_mfma_f32_16x16x32_bf16 v[42:45], v[146:149], v[202:205], v[42:45]
	v_mfma_f32_16x16x32_bf16 v[34:37], v[154:157], v[202:205], v[34:37]
	v_mfma_f32_16x16x32_bf16 v[26:29], v[146:149], v[210:213], v[26:29]
	v_mfma_f32_16x16x32_bf16 v[18:21], v[154:157], v[210:213], v[18:21]
	v_mfma_f32_16x16x32_bf16 v[46:49], v[158:161], v[182:185], v[46:49]
	v_mfma_f32_16x16x32_bf16 v[38:41], v[166:169], v[182:185], v[38:41]
	v_mfma_f32_16x16x32_bf16 v[30:33], v[158:161], v[190:193], v[30:33]
	v_mfma_f32_16x16x32_bf16 v[22:25], v[166:169], v[190:193], v[22:25]
	v_mfma_f32_16x16x32_bf16 v[14:17], v[158:161], v[198:201], v[14:17]
	v_mfma_f32_16x16x32_bf16 v[10:13], v[166:169], v[198:201], v[10:13]
	v_mfma_f32_16x16x32_bf16 v[6:9], v[158:161], v[206:209], v[6:9]
	v_mfma_f32_16x16x32_bf16 v[2:5], v[166:169], v[206:209], v[2:5]
	v_mfma_f32_16x16x32_bf16 v[46:49], v[162:165], v[186:189], v[46:49]
	v_mfma_f32_16x16x32_bf16 v[38:41], v[178:181], v[186:189], v[38:41]
	v_mfma_f32_16x16x32_bf16 v[30:33], v[162:165], v[194:197], v[30:33]
	v_mfma_f32_16x16x32_bf16 v[22:25], v[178:181], v[194:197], v[22:25]
	v_mfma_f32_16x16x32_bf16 v[14:17], v[162:165], v[202:205], v[14:17]
	v_mfma_f32_16x16x32_bf16 v[10:13], v[178:181], v[202:205], v[10:13]
	v_mfma_f32_16x16x32_bf16 v[6:9], v[162:165], v[210:213], v[6:9]
	v_mfma_f32_16x16x32_bf16 v[2:5], v[178:181], v[210:213], v[2:5]
	s_setprio 0
	s_barrier
	s_add_i32 s39, 0, 0x18000
	v_add_u32_e32 v0, s39, v139
	s_add_i32 s44, 0, 0x1c000
	ds_read_b128 v[142:145], v0
	ds_read_b128 v[146:149], v0 offset:1024
	ds_read_b128 v[150:153], v0 offset:2048
	ds_read_b128 v[154:157], v0 offset:3072
	v_add_u32_e32 v0, s44, v139
	ds_read_b128 v[158:161], v0
	ds_read_b128 v[162:165], v0 offset:1024
	ds_read_b128 v[166:169], v0 offset:2048
	ds_read_b128 v[178:181], v0 offset:3072
	s_add_u32 s20, s20, 0x100000
	s_addc_u32 s21, s21, 0
	s_mov_b32 m0, s22
	v_lshl_add_u64 v[222:223], s[20:21], 0, v[132:133]
	ds_read_b128 v[182:185], v141 offset:32768
	ds_read_b128 v[186:189], v141 offset:33792
	ds_read_b128 v[190:193], v141 offset:34816
	ds_read_b128 v[194:197], v141 offset:35840
	ds_read_b128 v[198:201], v141 offset:36864
	ds_read_b128 v[202:205], v141 offset:37888
	ds_read_b128 v[206:209], v141 offset:38912
	ds_read_b128 v[210:213], v141 offset:39936
	global_load_lds_dwordx4 v[222:223], off
	v_lshl_add_u64 v[222:223], s[20:21], 0, v[130:131]
	s_mov_b32 m0, s23
	s_nop 0
	global_load_lds_dwordx4 v[222:223], off
	s_waitcnt vmcnt(8)
	s_waitcnt lgkmcnt(0)
	s_setprio 1
	s_barrier
	v_mfma_f32_16x16x32_bf16 v[126:129], v[142:145], v[182:185], v[126:129]
	v_mfma_f32_16x16x32_bf16 v[122:125], v[150:153], v[182:185], v[122:125]
	v_mfma_f32_16x16x32_bf16 v[118:121], v[142:145], v[190:193], v[118:121]
	v_mfma_f32_16x16x32_bf16 v[114:117], v[150:153], v[190:193], v[114:117]
	v_mfma_f32_16x16x32_bf16 v[106:109], v[142:145], v[198:201], v[106:109]
	v_mfma_f32_16x16x32_bf16 v[98:101], v[150:153], v[198:201], v[98:101]
	v_mfma_f32_16x16x32_bf16 v[90:93], v[142:145], v[206:209], v[90:93]
	v_mfma_f32_16x16x32_bf16 v[82:85], v[150:153], v[206:209], v[82:85]
	v_mfma_f32_16x16x32_bf16 v[126:129], v[146:149], v[186:189], v[126:129]
	v_mfma_f32_16x16x32_bf16 v[122:125], v[154:157], v[186:189], v[122:125]
	v_mfma_f32_16x16x32_bf16 v[118:121], v[146:149], v[194:197], v[118:121]
	v_mfma_f32_16x16x32_bf16 v[114:117], v[154:157], v[194:197], v[114:117]
	v_mfma_f32_16x16x32_bf16 v[106:109], v[146:149], v[202:205], v[106:109]
	v_mfma_f32_16x16x32_bf16 v[98:101], v[154:157], v[202:205], v[98:101]
	v_mfma_f32_16x16x32_bf16 v[90:93], v[146:149], v[210:213], v[90:93]
	v_mfma_f32_16x16x32_bf16 v[82:85], v[154:157], v[210:213], v[82:85]
	v_mfma_f32_16x16x32_bf16 v[110:113], v[158:161], v[182:185], v[110:113]
	v_mfma_f32_16x16x32_bf16 v[102:105], v[166:169], v[182:185], v[102:105]
	v_mfma_f32_16x16x32_bf16 v[94:97], v[158:161], v[190:193], v[94:97]
	v_mfma_f32_16x16x32_bf16 v[86:89], v[166:169], v[190:193], v[86:89]
	v_mfma_f32_16x16x32_bf16 v[78:81], v[158:161], v[198:201], v[78:81]
	v_mfma_f32_16x16x32_bf16 v[74:77], v[166:169], v[198:201], v[74:77]
	v_mfma_f32_16x16x32_bf16 v[70:73], v[158:161], v[206:209], v[70:73]
	v_mfma_f32_16x16x32_bf16 v[66:69], v[166:169], v[206:209], v[66:69]
	v_mfma_f32_16x16x32_bf16 v[110:113], v[162:165], v[186:189], v[110:113]
	v_mfma_f32_16x16x32_bf16 v[102:105], v[178:181], v[186:189], v[102:105]
	v_mfma_f32_16x16x32_bf16 v[94:97], v[162:165], v[194:197], v[94:97]
	v_mfma_f32_16x16x32_bf16 v[86:89], v[178:181], v[194:197], v[86:89]
	v_mfma_f32_16x16x32_bf16 v[78:81], v[162:165], v[202:205], v[78:81]
	v_mfma_f32_16x16x32_bf16 v[74:77], v[178:181], v[202:205], v[74:77]
	v_mfma_f32_16x16x32_bf16 v[70:73], v[162:165], v[210:213], v[70:73]
	v_mfma_f32_16x16x32_bf16 v[66:69], v[178:181], v[210:213], v[66:69]
	s_setprio 0
	s_barrier
; #define PG8_STAGE(bufoff, gbase, voff) do { _Pragma("unroll") for (int _i = 0; _i < 2; ++_i) \
;         __builtin_amdgcn_global_load_lds((const unsigned*)((const char*)(gbase) + (voff)[_i]), (PG8_LAS unsigned*)(lds + (bufoff) + ldsw + _i * 8192), 16, 0, 0); } while (0)
; #define PG8_LDA(dst, b, h) do { _Pragma("unroll") for (int m = 0; m < 4; ++m) _Pragma("unroll") for (int k = 0; k < 2; ++k) dst[m][k] = *(const PG8_LAS bf16x8*)(lds + PG8_SA(b, h) + aoff + m * 2048 + k * 1024); } while (0)
; #define PG8_MMA(ai, bj, At, Bt) do { __builtin_amdgcn_s_setprio(1); _Pragma("unroll") for (int m = 0; m < 4; ++m) _Pragma("unroll") for (int n = 0; n < 2; ++n) _Pragma("unroll") for (int k = 0; k < 2; ++k) \
;         acc[ai][bj][m][n] = __builtin_amdgcn_mfma_f32_16x16x32_bf16(Bt[n][k], At[m][k], acc[ai][bj][m][n], 0, 0, 0); __builtin_amdgcn_s_setprio(0); } while (0)
; #define PG8_WAIT_V(n) asm volatile("s_waitcnt vmcnt(" #n ")" ::: "memory")
; #define PG8_WAIT_L(n) asm volatile("s_waitcnt lgkmcnt(" #n ")" ::: "memory")
; #define PG8_BAR __builtin_amdgcn_s_barrier()
; #define PG8_SCHED __builtin_amdgcn_sched_barrier(0)
; template <class Epi, class Sched, bool ALIGN_EPI = false, bool SP2 = false>
; __device__ __forceinline__ void gemm_phase(PG8_LAS unsigned char* lds, const Gemm g, const Sched& S, const Epi& E, const int wave_id) {
;     ...
;         for (int t = 0; t < nt; t += 2) {
;     ...
;             PG8_LDA(At, 1, 1); PG8_STAGE(PG8_SB(1, 0), b3, voffB); PG8_STAGE(PG8_SB(1, 1), b3 + hstepB, voffB); PG8_STAGE(PG8_SA(1, 0), a3, voffA);
;             PG8_WAIT_V(8); PG8_WAIT_L(0); PG8_BAR; PG8_MMA(1, 0, At, B0); PG8_MMA(1, 1, At, B1); PG8_BAR; PG8_SCHED;
	s_add_i32 s20, s39, s0
	v_lshl_add_u64 v[214:215], v[214:215], 0, s[62:63]
	s_mov_b32 m0, s20
	ds_read_b128 v[182:185], v141 offset:49152
	ds_read_b128 v[186:189], v141 offset:50176
	ds_read_b128 v[190:193], v141 offset:51200
	ds_read_b128 v[194:197], v141 offset:52224
	ds_read_b128 v[198:201], v141 offset:53248
	ds_read_b128 v[202:205], v141 offset:54272
	ds_read_b128 v[206:209], v141 offset:55296
	ds_read_b128 v[210:213], v141 offset:56320
	global_load_lds_dwordx4 v[214:215], off
	s_add_i32 m0, s20, 0x2000
	s_add_u32 s18, s18, 0x100080
	v_lshl_add_u64 v[214:215], v[216:217], 0, s[62:63]
	s_addc_u32 s19, s19, 0
	s_add_i32 s20, s44, s0
	global_load_lds_dwordx4 v[214:215], off
	v_lshl_add_u64 v[214:215], s[18:19], 0, v[132:133]
	s_mov_b32 m0, s20
	s_nop 0
	global_load_lds_dwordx4 v[214:215], off
	v_lshl_add_u64 v[214:215], s[18:19], 0, v[130:131]
	s_add_i32 m0, s20, 0x2000
	s_nop 0
	global_load_lds_dwordx4 v[214:215], off
	v_lshl_add_u64 v[214:215], v[218:219], 0, s[62:63]
	s_mov_b32 m0, s24
	s_nop 0
	global_load_lds_dwordx4 v[214:215], off
	v_lshl_add_u64 v[214:215], v[220:221], 0, s[62:63]
	s_mov_b32 m0, s25
	s_nop 0
	global_load_lds_dwordx4 v[214:215], off
	s_waitcnt vmcnt(8)
	s_waitcnt lgkmcnt(0)
	s_setprio 1
	s_barrier
	v_mfma_f32_16x16x32_bf16 v[62:65], v[142:145], v[182:185], v[62:65]
	v_mfma_f32_16x16x32_bf16 v[58:61], v[150:153], v[182:185], v[58:61]
	v_mfma_f32_16x16x32_bf16 v[54:57], v[142:145], v[190:193], v[54:57]
	v_mfma_f32_16x16x32_bf16 v[50:53], v[150:153], v[190:193], v[50:53]
	v_mfma_f32_16x16x32_bf16 v[42:45], v[142:145], v[198:201], v[42:45]
	v_mfma_f32_16x16x32_bf16 v[34:37], v[150:153], v[198:201], v[34:37]
	v_mfma_f32_16x16x32_bf16 v[26:29], v[142:145], v[206:209], v[26:29]
	v_mfma_f32_16x16x32_bf16 v[18:21], v[150:153], v[206:209], v[18:21]
	v_mfma_f32_16x16x32_bf16 v[62:65], v[146:149], v[186:189], v[62:65]
	v_mfma_f32_16x16x32_bf16 v[58:61], v[154:157], v[186:189], v[58:61]
	v_mfma_f32_16x16x32_bf16 v[54:57], v[146:149], v[194:197], v[54:57]
	v_mfma_f32_16x16x32_bf16 v[50:53], v[154:157], v[194:197], v[50:53]
	v_mfma_f32_16x16x32_bf16 v[42:45], v[146:149], v[202:205], v[42:45]
	v_mfma_f32_16x16x32_bf16 v[34:37], v[154:157], v[202:205], v[34:37]
	v_mfma_f32_16x16x32_bf16 v[26:29], v[146:149], v[210:213], v[26:29]
	v_mfma_f32_16x16x32_bf16 v[18:21], v[154:157], v[210:213], v[18:21]
	v_mfma_f32_16x16x32_bf16 v[46:49], v[158:161], v[182:185], v[46:49]
	v_mfma_f32_16x16x32_bf16 v[38:41], v[166:169], v[182:185], v[38:41]
	v_mfma_f32_16x16x32_bf16 v[30:33], v[158:161], v[190:193], v[30:33]
	v_mfma_f32_16x16x32_bf16 v[22:25], v[166:169], v[190:193], v[22:25]
	v_mfma_f32_16x16x32_bf16 v[14:17], v[158:161], v[198:201], v[14:17]
	v_mfma_f32_16x16x32_bf16 v[10:13], v[166:169], v[198:201], v[10:13]
	v_mfma_f32_16x16x32_bf16 v[6:9], v[158:161], v[206:209], v[6:9]
	v_mfma_f32_16x16x32_bf16 v[2:5], v[166:169], v[206:209], v[2:5]
	v_mfma_f32_16x16x32_bf16 v[46:49], v[162:165], v[186:189], v[46:49]
	v_mfma_f32_16x16x32_bf16 v[38:41], v[178:181], v[186:189], v[38:41]
	v_mfma_f32_16x16x32_bf16 v[30:33], v[162:165], v[194:197], v[30:33]
	v_mfma_f32_16x16x32_bf16 v[22:25], v[178:181], v[194:197], v[22:25]
	v_mfma_f32_16x16x32_bf16 v[14:17], v[162:165], v[202:205], v[14:17]
	v_mfma_f32_16x16x32_bf16 v[10:13], v[178:181], v[202:205], v[10:13]
	v_mfma_f32_16x16x32_bf16 v[6:9], v[162:165], v[210:213], v[6:9]
	v_mfma_f32_16x16x32_bf16 v[2:5], v[178:181], v[210:213], v[2:5]
	s_setprio 0
	s_barrier
	s_add_i32 s38, s38, 2
	s_add_u32 s16, s16, 0x100
	s_addc_u32 s17, s17, 0
	s_add_u32 s36, s36, 0x100
	s_addc_u32 s37, s37, 0
	s_cmp_gt_u32 s38, 5
	s_cbranch_scc0 .LBB0_69
	s_and_b64 vcc, exec, s[10:11]
	s_cbranch_vccz .LBB0_72
	s_barrier

; #define PG8_STAGE(bufoff, gbase, voff) do { _Pragma("unroll") for (int _i = 0; _i < 2; ++_i) \
;         __builtin_amdgcn_global_load_lds((const unsigned*)((const char*)(gbase) + (voff)[_i]), (PG8_LAS unsigned*)(lds + (bufoff) + ldsw + _i * 8192), 16, 0, 0); } while (0)
; #define PG8_LDA(dst, b, h) do { _Pragma("unroll") for (int m = 0; m < 4; ++m) _Pragma("unroll") for (int k = 0; k < 2; ++k) dst[m][k] = *(const PG8_LAS bf16x8*)(lds + PG8_SA(b, h) + aoff + m * 2048 + k * 1024); } while (0)
; #define PG8_MMA(ai, bj, At, Bt) do { __builtin_amdgcn_s_setprio(1); _Pragma("unroll") for (int m = 0; m < 4; ++m) _Pragma("unroll") for (int n = 0; n < 2; ++n) _Pragma("unroll") for (int k = 0; k < 2; ++k) \
;         acc[ai][bj][m][n] = __builtin_amdgcn_mfma_f32_16x16x32_bf16(Bt[n][k], At[m][k], acc[ai][bj][m][n], 0, 0, 0); __builtin_amdgcn_s_setprio(0); } while (0)
; #define PG8_WAIT_V(n) asm volatile("s_waitcnt vmcnt(" #n ")" ::: "memory")
; #define PG8_WAIT_L(n) asm volatile("s_waitcnt lgkmcnt(" #n ")" ::: "memory")
; #define PG8_BAR __builtin_amdgcn_s_barrier()
; #define PG8_SCHED __builtin_amdgcn_sched_barrier(0)
; template <class Epi, class Sched, bool ALIGN_EPI = false, bool SP2 = false>
; __device__ __forceinline__ void gemm_phase(PG8_LAS unsigned char* lds, const Gemm g, const Sched& S, const Epi& E, const int wave_id) {
;     ...
;             PG8_WAIT_V(8); PG8_WAIT_L(0); PG8_BAR; PG8_MMA(0, 0, At, B0); PG8_MMA(0, 1, At, B1); PG8_BAR; PG8_SCHED;
;             PG8_LDA(At, 0, 1); PG8_STAGE(PG8_SB(0, 0), b2, voffB); PG8_STAGE(PG8_SB(0, 1), b2 + hstepB, voffB); PG8_STAGE(PG8_SA(0, 0), a2, voffA);
;             PG8_WAIT_V(8); PG8_WAIT_L(0); PG8_BAR; PG8_MMA(1, 0, At, B0); PG8_MMA(1, 1, At, B1); PG8_BAR; PG8_SCHED;
.Lrw_1:
	s_waitcnt lgkmcnt(0)
	s_setprio 1
	s_barrier
	v_mfma_f32_16x16x32_bf16 v[134:137], v[138:141], v[190:193], v[134:137]
	v_mfma_f32_16x16x32_bf16 v[130:133], v[146:149], v[190:193], v[130:133]
	v_mfma_f32_16x16x32_bf16 v[118:121], v[138:141], v[198:201], v[118:121]
	v_mfma_f32_16x16x32_bf16 v[114:117], v[146:149], v[198:201], v[114:117]
	v_mfma_f32_16x16x32_bf16 v[102:105], v[138:141], v[214:217], v[102:105]
	v_mfma_f32_16x16x32_bf16 v[98:101], v[146:149], v[214:217], v[98:101]
	v_mfma_f32_16x16x32_bf16 v[86:89], v[138:141], v[222:225], v[86:89]
	v_mfma_f32_16x16x32_bf16 v[82:85], v[146:149], v[222:225], v[82:85]
	v_mfma_f32_16x16x32_bf16 v[134:137], v[142:145], v[194:197], v[134:137]
	v_mfma_f32_16x16x32_bf16 v[130:133], v[150:153], v[194:197], v[130:133]
	v_mfma_f32_16x16x32_bf16 v[118:121], v[142:145], v[210:213], v[118:121]
	v_mfma_f32_16x16x32_bf16 v[114:117], v[150:153], v[210:213], v[114:117]
	v_mfma_f32_16x16x32_bf16 v[102:105], v[142:145], v[218:221], v[102:105]
	v_mfma_f32_16x16x32_bf16 v[98:101], v[150:153], v[218:221], v[98:101]
	v_mfma_f32_16x16x32_bf16 v[86:89], v[142:145], v[234:237], v[86:89]
	v_mfma_f32_16x16x32_bf16 v[82:85], v[150:153], v[234:237], v[82:85]
	v_mfma_f32_16x16x32_bf16 v[126:129], v[154:157], v[190:193], v[126:129]
	v_mfma_f32_16x16x32_bf16 v[122:125], v[162:165], v[190:193], v[122:125]
	v_mfma_f32_16x16x32_bf16 v[110:113], v[154:157], v[198:201], v[110:113]
	v_mfma_f32_16x16x32_bf16 v[106:109], v[162:165], v[198:201], v[106:109]
	v_mfma_f32_16x16x32_bf16 v[94:97], v[154:157], v[214:217], v[94:97]
	v_mfma_f32_16x16x32_bf16 v[90:93], v[162:165], v[214:217], v[90:93]
	v_mfma_f32_16x16x32_bf16 v[78:81], v[154:157], v[222:225], v[78:81]
	v_mfma_f32_16x16x32_bf16 v[74:77], v[162:165], v[222:225], v[74:77]
	v_mfma_f32_16x16x32_bf16 v[126:129], v[158:161], v[194:197], v[126:129]
	v_mfma_f32_16x16x32_bf16 v[122:125], v[166:169], v[194:197], v[122:125]
	v_mfma_f32_16x16x32_bf16 v[110:113], v[158:161], v[210:213], v[110:113]
	v_mfma_f32_16x16x32_bf16 v[106:109], v[166:169], v[210:213], v[106:109]
	v_mfma_f32_16x16x32_bf16 v[94:97], v[158:161], v[218:221], v[94:97]
	v_mfma_f32_16x16x32_bf16 v[90:93], v[166:169], v[218:221], v[90:93]
	v_mfma_f32_16x16x32_bf16 v[78:81], v[158:161], v[234:237], v[78:81]
	v_mfma_f32_16x16x32_bf16 v[74:77], v[166:169], v[234:237], v[74:77]
	s_setprio 0
	s_barrier
	s_add_i32 s10, s37, s15
	v_lshl_add_u64 v[240:241], s[28:29], 0, v[180:181]
	s_mov_b32 m0, s10
	ds_read_b128 v[190:193], v208 offset:16384
	ds_read_b128 v[194:197], v208 offset:17408
	ds_read_b128 v[198:201], v208 offset:18432
	ds_read_b128 v[210:213], v208 offset:19456
	ds_read_b128 v[214:217], v208 offset:20480
	ds_read_b128 v[218:221], v208 offset:21504
	ds_read_b128 v[222:225], v208 offset:22528
	ds_read_b128 v[234:237], v208 offset:23552
	global_load_lds_dwordx4 v[240:241], off
	s_add_i32 m0, s10, 0x2000
	s_add_u32 s10, s28, 0x40000
	v_lshl_add_u64 v[242:243], s[28:29], 0, v[184:185]
	s_addc_u32 s11, s29, 0
	s_add_i32 s37, s39, s15
	global_load_lds_dwordx4 v[242:243], off
	v_lshl_add_u64 v[244:245], s[10:11], 0, v[180:181]
	s_mov_b32 m0, s37
	v_lshl_add_u64 v[246:247], s[30:31], 0, v[182:183]
	global_load_lds_dwordx4 v[244:245], off
	v_lshl_add_u64 v[244:245], s[10:11], 0, v[184:185]
	s_add_i32 m0, s37, 0x2000
	s_nop 0
	global_load_lds_dwordx4 v[244:245], off
	v_lshl_add_u64 v[244:245], s[30:31], 0, v[178:179]
	s_mov_b32 m0, s27
	s_nop 0
	global_load_lds_dwordx4 v[244:245], off
	s_mov_b32 m0, s34
	s_nop 0
	global_load_lds_dwordx4 v[246:247], off
	s_waitcnt vmcnt(24)
	s_cmp_eq_u32 s98, 1
	s_cbranch_scc1 .Lrw_2
	s_waitcnt vmcnt(8)
.Lrw_2:
	s_mov_b32 s98, 0
	s_waitcnt lgkmcnt(0)
	s_setprio 1
	s_barrier
	v_mfma_f32_16x16x32_bf16 v[70:73], v[138:141], v[190:193], v[70:73]
	v_mfma_f32_16x16x32_bf16 v[66:69], v[146:149], v[190:193], v[66:69]
	v_mfma_f32_16x16x32_bf16 v[54:57], v[138:141], v[198:201], v[54:57]
	v_mfma_f32_16x16x32_bf16 v[50:53], v[146:149], v[198:201], v[50:53]
	v_mfma_f32_16x16x32_bf16 v[38:41], v[138:141], v[214:217], v[38:41]
	v_mfma_f32_16x16x32_bf16 v[34:37], v[146:149], v[214:217], v[34:37]
	v_mfma_f32_16x16x32_bf16 v[22:25], v[138:141], v[222:225], v[22:25]
	v_mfma_f32_16x16x32_bf16 v[18:21], v[146:149], v[222:225], v[18:21]
	v_mfma_f32_16x16x32_bf16 v[70:73], v[142:145], v[194:197], v[70:73]
	v_mfma_f32_16x16x32_bf16 v[66:69], v[150:153], v[194:197], v[66:69]
	v_mfma_f32_16x16x32_bf16 v[54:57], v[142:145], v[210:213], v[54:57]
	v_mfma_f32_16x16x32_bf16 v[50:53], v[150:153], v[210:213], v[50:53]
	v_mfma_f32_16x16x32_bf16 v[38:41], v[142:145], v[218:221], v[38:41]
	v_mfma_f32_16x16x32_bf16 v[34:37], v[150:153], v[218:221], v[34:37]
	v_mfma_f32_16x16x32_bf16 v[22:25], v[142:145], v[234:237], v[22:25]
	v_mfma_f32_16x16x32_bf16 v[18:21], v[150:153], v[234:237], v[18:21]
	v_mfma_f32_16x16x32_bf16 v[62:65], v[154:157], v[190:193], v[62:65]
	v_mfma_f32_16x16x32_bf16 v[58:61], v[162:165], v[190:193], v[58:61]
	v_mfma_f32_16x16x32_bf16 v[46:49], v[154:157], v[198:201], v[46:49]
	v_mfma_f32_16x16x32_bf16 v[42:45], v[162:165], v[198:201], v[42:45]
	v_mfma_f32_16x16x32_bf16 v[30:33], v[154:157], v[214:217], v[30:33]
	v_mfma_f32_16x16x32_bf16 v[26:29], v[162:165], v[214:217], v[26:29]
	v_mfma_f32_16x16x32_bf16 v[14:17], v[154:157], v[222:225], v[14:17]
	v_mfma_f32_16x16x32_bf16 v[10:13], v[162:165], v[222:225], v[10:13]
	v_mfma_f32_16x16x32_bf16 v[62:65], v[158:161], v[194:197], v[62:65]
	v_mfma_f32_16x16x32_bf16 v[58:61], v[166:169], v[194:197], v[58:61]
	v_mfma_f32_16x16x32_bf16 v[46:49], v[158:161], v[210:213], v[46:49]
	v_mfma_f32_16x16x32_bf16 v[42:45], v[166:169], v[210:213], v[42:45]
	v_mfma_f32_16x16x32_bf16 v[30:33], v[158:161], v[218:221], v[30:33]
	v_mfma_f32_16x16x32_bf16 v[26:29], v[166:169], v[218:221], v[26:29]
	v_mfma_f32_16x16x32_bf16 v[14:17], v[158:161], v[234:237], v[14:17]
	v_mfma_f32_16x16x32_bf16 v[10:13], v[166:169], v[234:237], v[10:13]
	s_setprio 0
	s_barrier
; #define PG8_STAGE(bufoff, gbase, voff) do { _Pragma("unroll") for (int _i = 0; _i < 2; ++_i) \
;         __builtin_amdgcn_global_load_lds((const unsigned*)((const char*)(gbase) + (voff)[_i]), (PG8_LAS unsigned*)(lds + (bufoff) + ldsw + _i * 8192), 16, 0, 0); } while (0)
; #define PG8_LDA(dst, b, h) do { _Pragma("unroll") for (int m = 0; m < 4; ++m) _Pragma("unroll") for (int k = 0; k < 2; ++k) dst[m][k] = *(const PG8_LAS bf16x8*)(lds + PG8_SA(b, h) + aoff + m * 2048 + k * 1024); } while (0)
; #define PG8_LDB(dst, b, h) do { _Pragma("unroll") for (int n = 0; n < 2; ++n) _Pragma("unroll") for (int k = 0; k < 2; ++k) dst[n][k] = *(const PG8_LAS bf16x8*)(lds + PG8_SB(b, h) + boff + n * 2048 + k * 1024); } while (0)
; #define PG8_MMA(ai, bj, At, Bt) do { __builtin_amdgcn_s_setprio(1); _Pragma("unroll") for (int m = 0; m < 4; ++m) _Pragma("unroll") for (int n = 0; n < 2; ++n) _Pragma("unroll") for (int k = 0; k < 2; ++k) \
;         acc[ai][bj][m][n] = __builtin_amdgcn_mfma_f32_16x16x32_bf16(Bt[n][k], At[m][k], acc[ai][bj][m][n], 0, 0, 0); __builtin_amdgcn_s_setprio(0); } while (0)
; #define PG8_WAIT_V(n) asm volatile("s_waitcnt vmcnt(" #n ")" ::: "memory")
; #define PG8_WAIT_L(n) asm volatile("s_waitcnt lgkmcnt(" #n ")" ::: "memory")
; #define PG8_BAR __builtin_amdgcn_s_barrier()
; #define PG8_SCHED __builtin_amdgcn_sched_barrier(0)
; template <class Epi, class Sched, bool ALIGN_EPI = false, bool SP2 = false>
; __device__ __forceinline__ void gemm_phase(PG8_LAS unsigned char* lds, const Gemm g, const Sched& S, const Epi& E, const int wave_id) {
;     ...
;             PG8_LDB(B0, 1, 0); PG8_LDB(B1, 1, 1); PG8_SCHED; PG8_LDA(At, 1, 0); PG8_STAGE(PG8_SA(0, 1), a2 + hstepA, voffA);
;             PG8_WAIT_V(8); PG8_WAIT_L(0); PG8_BAR; PG8_MMA(0, 0, At, B0); PG8_MMA(0, 1, At, B1); PG8_BAR; PG8_SCHED;
	s_add_i32 s37, 0, 0x18000
	v_add_u32_e32 v0, s37, v203
	s_add_i32 s39, 0, 0x1c000
	ds_read_b128 v[138:141], v0
	ds_read_b128 v[142:145], v0 offset:1024
	ds_read_b128 v[146:149], v0 offset:2048
	ds_read_b128 v[150:153], v0 offset:3072
	v_add_u32_e32 v0, s39, v203
	ds_read_b128 v[154:157], v0
	ds_read_b128 v[158:161], v0 offset:1024
	ds_read_b128 v[162:165], v0 offset:2048
	ds_read_b128 v[166:169], v0 offset:3072
	s_add_u32 s10, s30, 0x40000
	s_addc_u32 s11, s31, 0
	s_mov_b32 m0, s35
	v_lshl_add_u64 v[248:249], s[10:11], 0, v[178:179]
	ds_read_b128 v[190:193], v208 offset:32768
	ds_read_b128 v[194:197], v208 offset:33792
	ds_read_b128 v[198:201], v208 offset:34816
	ds_read_b128 v[210:213], v208 offset:35840
	ds_read_b128 v[214:217], v208 offset:36864
	ds_read_b128 v[218:221], v208 offset:37888
	ds_read_b128 v[222:225], v208 offset:38912
	ds_read_b128 v[234:237], v208 offset:39936
	global_load_lds_dwordx4 v[248:249], off
	v_lshl_add_u64 v[248:249], s[10:11], 0, v[182:183]
	s_mov_b32 m0, s36
	s_nop 0
	global_load_lds_dwordx4 v[248:249], off
	s_waitcnt vmcnt(8)
	s_waitcnt lgkmcnt(0)
	s_setprio 1
	s_barrier
	v_mfma_f32_16x16x32_bf16 v[134:137], v[138:141], v[190:193], v[134:137]
	v_mfma_f32_16x16x32_bf16 v[130:133], v[146:149], v[190:193], v[130:133]
	v_mfma_f32_16x16x32_bf16 v[118:121], v[138:141], v[198:201], v[118:121]
	v_mfma_f32_16x16x32_bf16 v[114:117], v[146:149], v[198:201], v[114:117]
	v_mfma_f32_16x16x32_bf16 v[102:105], v[138:141], v[214:217], v[102:105]
	v_mfma_f32_16x16x32_bf16 v[98:101], v[146:149], v[214:217], v[98:101]
	v_mfma_f32_16x16x32_bf16 v[86:89], v[138:141], v[222:225], v[86:89]
	v_mfma_f32_16x16x32_bf16 v[82:85], v[146:149], v[222:225], v[82:85]
	v_mfma_f32_16x16x32_bf16 v[134:137], v[142:145], v[194:197], v[134:137]
	v_mfma_f32_16x16x32_bf16 v[130:133], v[150:153], v[194:197], v[130:133]
	v_mfma_f32_16x16x32_bf16 v[118:121], v[142:145], v[210:213], v[118:121]
	v_mfma_f32_16x16x32_bf16 v[114:117], v[150:153], v[210:213], v[114:117]
	v_mfma_f32_16x16x32_bf16 v[102:105], v[142:145], v[218:221], v[102:105]
	v_mfma_f32_16x16x32_bf16 v[98:101], v[150:153], v[218:221], v[98:101]
	v_mfma_f32_16x16x32_bf16 v[86:89], v[142:145], v[234:237], v[86:89]
	v_mfma_f32_16x16x32_bf16 v[82:85], v[150:153], v[234:237], v[82:85]
	v_mfma_f32_16x16x32_bf16 v[126:129], v[154:157], v[190:193], v[126:129]
	v_mfma_f32_16x16x32_bf16 v[122:125], v[162:165], v[190:193], v[122:125]
	v_mfma_f32_16x16x32_bf16 v[110:113], v[154:157], v[198:201], v[110:113]
	v_mfma_f32_16x16x32_bf16 v[106:109], v[162:165], v[198:201], v[106:109]
	v_mfma_f32_16x16x32_bf16 v[94:97], v[154:157], v[214:217], v[94:97]
	v_mfma_f32_16x16x32_bf16 v[90:93], v[162:165], v[214:217], v[90:93]
	v_mfma_f32_16x16x32_bf16 v[78:81], v[154:157], v[222:225], v[78:81]
	v_mfma_f32_16x16x32_bf16 v[74:77], v[162:165], v[222:225], v[74:77]
	v_mfma_f32_16x16x32_bf16 v[126:129], v[158:161], v[194:197], v[126:129]
	v_mfma_f32_16x16x32_bf16 v[122:125], v[166:169], v[194:197], v[122:125]
	v_mfma_f32_16x16x32_bf16 v[110:113], v[158:161], v[210:213], v[110:113]
	v_mfma_f32_16x16x32_bf16 v[106:109], v[166:169], v[210:213], v[106:109]
	v_mfma_f32_16x16x32_bf16 v[94:97], v[158:161], v[218:221], v[94:97]
	v_mfma_f32_16x16x32_bf16 v[90:93], v[166:169], v[218:221], v[90:93]
	v_mfma_f32_16x16x32_bf16 v[78:81], v[158:161], v[234:237], v[78:81]
	v_mfma_f32_16x16x32_bf16 v[74:77], v[166:169], v[234:237], v[74:77]
	s_setprio 0
	s_barrier
; #define PG8_STAGE(bufoff, gbase, voff) do { _Pragma("unroll") for (int _i = 0; _i < 2; ++_i) \
;         __builtin_amdgcn_global_load_lds((const unsigned*)((const char*)(gbase) + (voff)[_i]), (PG8_LAS unsigned*)(lds + (bufoff) + ldsw + _i * 8192), 16, 0, 0); } while (0)
; #define PG8_LDA(dst, b, h) do { _Pragma("unroll") for (int m = 0; m < 4; ++m) _Pragma("unroll") for (int k = 0; k < 2; ++k) dst[m][k] = *(const PG8_LAS bf16x8*)(lds + PG8_SA(b, h) + aoff + m * 2048 + k * 1024); } while (0)
; #define PG8_MMA(ai, bj, At, Bt) do { __builtin_amdgcn_s_setprio(1); _Pragma("unroll") for (int m = 0; m < 4; ++m) _Pragma("unroll") for (int n = 0; n < 2; ++n) _Pragma("unroll") for (int k = 0; k < 2; ++k) \
;         acc[ai][bj][m][n] = __builtin_amdgcn_mfma_f32_16x16x32_bf16(Bt[n][k], At[m][k], acc[ai][bj][m][n], 0, 0, 0); __builtin_amdgcn_s_setprio(0); } while (0)
; #define PG8_WAIT_V(n) asm volatile("s_waitcnt vmcnt(" #n ")" ::: "memory")
; #define PG8_WAIT_L(n) asm volatile("s_waitcnt lgkmcnt(" #n ")" ::: "memory")
; #define PG8_BAR __builtin_amdgcn_s_barrier()
; #define PG8_SCHED __builtin_amdgcn_sched_barrier(0)
; template <class Epi, class Sched, bool ALIGN_EPI = false, bool SP2 = false>
; __device__ __forceinline__ void gemm_phase(PG8_LAS unsigned char* lds, const Gemm g, const Sched& S, const Epi& E, const int wave_id) {
;     ...
;         for (int t = 0; t < nt; t += 2) {
;     ...
;             PG8_LDA(At, 1, 1); PG8_STAGE(PG8_SB(1, 0), b3, voffB); PG8_STAGE(PG8_SB(1, 1), b3 + hstepB, voffB); PG8_STAGE(PG8_SA(1, 0), a3, voffA);
;             PG8_WAIT_V(8); PG8_WAIT_L(0); PG8_BAR; PG8_MMA(1, 0, At, B0); PG8_MMA(1, 1, At, B1); PG8_BAR; PG8_SCHED;
	s_add_i32 s10, s37, s15
	v_lshl_add_u64 v[240:241], v[240:241], 0, s[62:63]
	s_mov_b32 m0, s10
	ds_read_b128 v[190:193], v208 offset:49152
	ds_read_b128 v[194:197], v208 offset:50176
	ds_read_b128 v[198:201], v208 offset:51200
	ds_read_b128 v[210:213], v208 offset:52224
	ds_read_b128 v[214:217], v208 offset:53248
	ds_read_b128 v[218:221], v208 offset:54272
	ds_read_b128 v[222:225], v208 offset:55296
	ds_read_b128 v[234:237], v208 offset:56320
	global_load_lds_dwordx4 v[240:241], off
	s_add_i32 m0, s10, 0x2000
	s_add_u32 s10, s28, 0x40080
	v_lshl_add_u64 v[240:241], v[242:243], 0, s[62:63]
	s_addc_u32 s11, s29, 0
	s_add_i32 s28, s39, s15
	global_load_lds_dwordx4 v[240:241], off
	v_lshl_add_u64 v[240:241], s[10:11], 0, v[180:181]
	s_mov_b32 m0, s28
	s_nop 0
	global_load_lds_dwordx4 v[240:241], off
	v_lshl_add_u64 v[240:241], s[10:11], 0, v[184:185]
	s_add_i32 m0, s28, 0x2000
	s_nop 0
	global_load_lds_dwordx4 v[240:241], off
	v_lshl_add_u64 v[240:241], v[244:245], 0, s[62:63]
	s_mov_b32 m0, s76
	s_nop 0
	global_load_lds_dwordx4 v[240:241], off
	v_lshl_add_u64 v[240:241], v[246:247], 0, s[62:63]
	s_mov_b32 m0, s77
	s_nop 0
	global_load_lds_dwordx4 v[240:241], off
	s_waitcnt vmcnt(8)
	s_waitcnt lgkmcnt(0)
	s_setprio 1
	s_barrier
	v_mfma_f32_16x16x32_bf16 v[70:73], v[138:141], v[190:193], v[70:73]
	v_mfma_f32_16x16x32_bf16 v[66:69], v[146:149], v[190:193], v[66:69]
	v_mfma_f32_16x16x32_bf16 v[54:57], v[138:141], v[198:201], v[54:57]
	v_mfma_f32_16x16x32_bf16 v[50:53], v[146:149], v[198:201], v[50:53]
	v_mfma_f32_16x16x32_bf16 v[38:41], v[138:141], v[214:217], v[38:41]
	v_mfma_f32_16x16x32_bf16 v[34:37], v[146:149], v[214:217], v[34:37]
	v_mfma_f32_16x16x32_bf16 v[22:25], v[138:141], v[222:225], v[22:25]
	v_mfma_f32_16x16x32_bf16 v[18:21], v[146:149], v[222:225], v[18:21]
	v_mfma_f32_16x16x32_bf16 v[70:73], v[142:145], v[194:197], v[70:73]
	v_mfma_f32_16x16x32_bf16 v[66:69], v[150:153], v[194:197], v[66:69]
	v_mfma_f32_16x16x32_bf16 v[54:57], v[142:145], v[210:213], v[54:57]
	v_mfma_f32_16x16x32_bf16 v[50:53], v[150:153], v[210:213], v[50:53]
	v_mfma_f32_16x16x32_bf16 v[38:41], v[142:145], v[218:221], v[38:41]
	v_mfma_f32_16x16x32_bf16 v[34:37], v[150:153], v[218:221], v[34:37]
	v_mfma_f32_16x16x32_bf16 v[22:25], v[142:145], v[234:237], v[22:25]
	v_mfma_f32_16x16x32_bf16 v[18:21], v[150:153], v[234:237], v[18:21]
	v_mfma_f32_16x16x32_bf16 v[62:65], v[154:157], v[190:193], v[62:65]
	v_mfma_f32_16x16x32_bf16 v[58:61], v[162:165], v[190:193], v[58:61]
	v_mfma_f32_16x16x32_bf16 v[46:49], v[154:157], v[198:201], v[46:49]
	v_mfma_f32_16x16x32_bf16 v[42:45], v[162:165], v[198:201], v[42:45]
	v_mfma_f32_16x16x32_bf16 v[30:33], v[154:157], v[214:217], v[30:33]
	v_mfma_f32_16x16x32_bf16 v[26:29], v[162:165], v[214:217], v[26:29]
	v_mfma_f32_16x16x32_bf16 v[14:17], v[154:157], v[222:225], v[14:17]
	v_mfma_f32_16x16x32_bf16 v[10:13], v[162:165], v[222:225], v[10:13]
	v_mfma_f32_16x16x32_bf16 v[62:65], v[158:161], v[194:197], v[62:65]
	v_mfma_f32_16x16x32_bf16 v[58:61], v[166:169], v[194:197], v[58:61]
	v_mfma_f32_16x16x32_bf16 v[46:49], v[158:161], v[210:213], v[46:49]
	v_mfma_f32_16x16x32_bf16 v[42:45], v[166:169], v[210:213], v[42:45]
	v_mfma_f32_16x16x32_bf16 v[30:33], v[158:161], v[218:221], v[30:33]
	v_mfma_f32_16x16x32_bf16 v[26:29], v[166:169], v[218:221], v[26:29]
	v_mfma_f32_16x16x32_bf16 v[14:17], v[158:161], v[234:237], v[14:17]
	v_mfma_f32_16x16x32_bf16 v[10:13], v[166:169], v[234:237], v[10:13]
	s_setprio 0
	s_barrier
	s_add_i32 s5, s5, 2
	s_add_u32 s8, s8, 0x100
	s_addc_u32 s9, s9, 0
	s_add_u32 s38, s38, 0x100
	s_addc_u32 s4, s4, 0
	s_cmp_gt_u32 s5, 13
	s_cbranch_scc0 .LBB0_90

; #define PG8_STAGE(bufoff, gbase, voff) do { _Pragma("unroll") for (int _i = 0; _i < 2; ++_i) \
;         __builtin_amdgcn_global_load_lds((const unsigned*)((const char*)(gbase) + (voff)[_i]), (PG8_LAS unsigned*)(lds + (bufoff) + ldsw + _i * 8192), 16, 0, 0); } while (0)
; #define PG8_LDA(dst, b, h) do { _Pragma("unroll") for (int m = 0; m < 4; ++m) _Pragma("unroll") for (int k = 0; k < 2; ++k) dst[m][k] = *(const PG8_LAS bf16x8*)(lds + PG8_SA(b, h) + aoff + m * 2048 + k * 1024); } while (0)
; #define PG8_LDB(dst, b, h) do { _Pragma("unroll") for (int n = 0; n < 2; ++n) _Pragma("unroll") for (int k = 0; k < 2; ++k) dst[n][k] = *(const PG8_LAS bf16x8*)(lds + PG8_SB(b, h) + boff + n * 2048 + k * 1024); } while (0)
; #define PG8_MMA(ai, bj, At, Bt) do { __builtin_amdgcn_s_setprio(1); _Pragma("unroll") for (int m = 0; m < 4; ++m) _Pragma("unroll") for (int n = 0; n < 2; ++n) _Pragma("unroll") for (int k = 0; k < 2; ++k) \
;         acc[ai][bj][m][n] = __builtin_amdgcn_mfma_f32_16x16x32_bf16(Bt[n][k], At[m][k], acc[ai][bj][m][n], 0, 0, 0); __builtin_amdgcn_s_setprio(0); } while (0)
; #define PG8_WAIT_V(n) asm volatile("s_waitcnt vmcnt(" #n ")" ::: "memory")
; #define PG8_WAIT_L(n) asm volatile("s_waitcnt lgkmcnt(" #n ")" ::: "memory")
; #define PG8_BAR __builtin_amdgcn_s_barrier()
; template <class Epi, class Sched, bool ALIGN_EPI = false, bool SP2 = false>
; __device__ __forceinline__ void gemm_phase(PG8_LAS unsigned char* lds, const Gemm g, const Sched& S, const Epi& E, const int wave_id) {
;     ...
;             const char* a1 = cA + (size_t)(t + 1) * kstep;
;             const char* a2 = last ? nA : cA + (size_t)(t + 2) * kstep; const char* b2 = last ? nB : cB + (size_t)(t + 2) * kstep;
;             const char* a3 = a2 + kstep; const char* b3 = b2 + kstep;
;             if (last && has_next) S.a_ready(nxt);
;             if constexpr (SP2) {
;             PG8_LDB(B0, 0, 0); PG8_LDB(B1, 0, 1); PG8_SCHED; PG8_LDA(At, 0, 0); PG8_STAGE(PG8_SA(1, 1), a1 + hstepA, voffA);
;             PG8_WAIT_V(8); PG8_WAIT_L(0); PG8_BAR; PG8_MMA(0, 0, At, B0); PG8_MMA(0, 1, At, B1); PG8_BAR; PG8_SCHED;
;             PG8_LDA(At, 0, 1); PG8_STAGE(PG8_SB(0, 0), b2, voffB); PG8_STAGE(PG8_SB(0, 1), b2 + hstepB, voffB); PG8_STAGE(PG8_SA(0, 0), a2, voffA);
;             PG8_WAIT_V(8); PG8_WAIT_L(0); PG8_BAR; PG8_MMA(1, 0, At, B0); PG8_MMA(1, 1, At, B1); PG8_BAR; PG8_SCHED;
.LBB0_189:
	s_add_u32 s10, s12, 0x100
	s_addc_u32 s11, s13, 0
	s_add_i32 s39, 0, 0x10000
	s_cmp_eq_u32 vcc_lo, 28
	s_cselect_b32 s31, s25, s11
	s_cselect_b32 s30, s24, s10
	v_add_u32_e32 v0, s39, v206
	s_cselect_b32 s29, s23, s91
	s_cselect_b32 s28, s87, s38
	s_add_i32 vcc_hi, 0, 0x14000
	ds_read_b128 v[122:125], v0
	ds_read_b128 v[134:137], v0 offset:1024
	ds_read_b128 v[138:141], v0 offset:2048
	ds_read_b128 v[142:145], v0 offset:3072
	v_add_u32_e32 v0, vcc_hi, v206
	ds_read_b128 v[146:149], v0
	ds_read_b128 v[150:153], v0 offset:1024
	ds_read_b128 v[154:157], v0 offset:2048
	ds_read_b128 v[158:161], v0 offset:3072
	v_lshl_add_u64 v[222:223], s[12:13], 0, v[178:179]
	s_add_i32 m0, s17, 0xc000
	ds_read_b128 v[182:185], v212
	ds_read_b128 v[186:189], v212 offset:1024
	ds_read_b128 v[190:193], v212 offset:2048
	ds_read_b128 v[194:197], v212 offset:3072
	ds_read_b128 v[198:201], v212 offset:4096
	ds_read_b128 v[202:205], v212 offset:5120
	ds_read_b128 v[214:217], v212 offset:6144
	ds_read_b128 v[218:221], v212 offset:7168
	global_load_lds_dwordx4 v[222:223], off
	v_lshl_add_u64 v[222:223], s[12:13], 0, v[180:181]
	s_add_i32 m0, s17, 0xe000
	s_nop 0
	global_load_lds_dwordx4 v[222:223], off
	s_waitcnt vmcnt(8)
	s_waitcnt lgkmcnt(0)
	s_setprio 1
	s_barrier
	v_mfma_f32_16x16x32_bf16 v[130:133], v[122:125], v[182:185], v[130:133]
	v_mfma_f32_16x16x32_bf16 v[126:129], v[138:141], v[182:185], v[126:129]
	v_mfma_f32_16x16x32_bf16 v[110:113], v[122:125], v[190:193], v[110:113]
	v_mfma_f32_16x16x32_bf16 v[106:109], v[138:141], v[190:193], v[106:109]
	v_mfma_f32_16x16x32_bf16 v[94:97], v[122:125], v[198:201], v[94:97]
	v_mfma_f32_16x16x32_bf16 v[90:93], v[138:141], v[198:201], v[90:93]
	v_mfma_f32_16x16x32_bf16 v[78:81], v[122:125], v[214:217], v[78:81]
	v_mfma_f32_16x16x32_bf16 v[74:77], v[138:141], v[214:217], v[74:77]
	v_mfma_f32_16x16x32_bf16 v[130:133], v[134:137], v[186:189], v[130:133]
	v_mfma_f32_16x16x32_bf16 v[126:129], v[142:145], v[186:189], v[126:129]
	v_mfma_f32_16x16x32_bf16 v[110:113], v[134:137], v[194:197], v[110:113]
	v_mfma_f32_16x16x32_bf16 v[106:109], v[142:145], v[194:197], v[106:109]
	v_mfma_f32_16x16x32_bf16 v[94:97], v[134:137], v[202:205], v[94:97]
	v_mfma_f32_16x16x32_bf16 v[90:93], v[142:145], v[202:205], v[90:93]
	v_mfma_f32_16x16x32_bf16 v[78:81], v[134:137], v[218:221], v[78:81]
	v_mfma_f32_16x16x32_bf16 v[74:77], v[142:145], v[218:221], v[74:77]
	v_mfma_f32_16x16x32_bf16 v[118:121], v[146:149], v[182:185], v[118:121]
	v_mfma_f32_16x16x32_bf16 v[114:117], v[154:157], v[182:185], v[114:117]
	v_mfma_f32_16x16x32_bf16 v[102:105], v[146:149], v[190:193], v[102:105]
	v_mfma_f32_16x16x32_bf16 v[98:101], v[154:157], v[190:193], v[98:101]
	v_mfma_f32_16x16x32_bf16 v[86:89], v[146:149], v[198:201], v[86:89]
	v_mfma_f32_16x16x32_bf16 v[82:85], v[154:157], v[198:201], v[82:85]
	v_mfma_f32_16x16x32_bf16 v[70:73], v[146:149], v[214:217], v[70:73]
	v_mfma_f32_16x16x32_bf16 v[66:69], v[154:157], v[214:217], v[66:69]
	v_mfma_f32_16x16x32_bf16 v[118:121], v[150:153], v[186:189], v[118:121]
	v_mfma_f32_16x16x32_bf16 v[114:117], v[158:161], v[186:189], v[114:117]
	v_mfma_f32_16x16x32_bf16 v[102:105], v[150:153], v[194:197], v[102:105]
	v_mfma_f32_16x16x32_bf16 v[98:101], v[158:161], v[194:197], v[98:101]
	v_mfma_f32_16x16x32_bf16 v[86:89], v[150:153], v[202:205], v[86:89]
	v_mfma_f32_16x16x32_bf16 v[82:85], v[158:161], v[202:205], v[82:85]
	v_mfma_f32_16x16x32_bf16 v[70:73], v[150:153], v[218:221], v[70:73]
	v_mfma_f32_16x16x32_bf16 v[66:69], v[158:161], v[218:221], v[66:69]
	s_setprio 0
	s_barrier
	s_add_i32 s12, s39, s35
	v_lshl_add_u64 v[222:223], s[28:29], 0, v[164:165]
	s_mov_b32 m0, s12
	ds_read_b128 v[182:185], v212 offset:16384
	ds_read_b128 v[186:189], v212 offset:17408
	ds_read_b128 v[190:193], v212 offset:18432
	ds_read_b128 v[194:197], v212 offset:19456
	ds_read_b128 v[198:201], v212 offset:20480
	ds_read_b128 v[202:205], v212 offset:21504
	ds_read_b128 v[214:217], v212 offset:22528
	ds_read_b128 v[218:221], v212 offset:23552
	global_load_lds_dwordx4 v[222:223], off
	s_add_i32 m0, s12, 0x2000
	s_add_u32 s12, s28, 0x80000
	v_lshl_add_u64 v[224:225], s[28:29], 0, v[168:169]
	s_addc_u32 s13, s29, 0
	s_add_i32 s39, vcc_hi, s35
	global_load_lds_dwordx4 v[224:225], off
	v_lshl_add_u64 v[234:235], s[12:13], 0, v[164:165]
	s_mov_b32 m0, s39
	v_lshl_add_u64 v[236:237], s[30:31], 0, v[166:167]
	global_load_lds_dwordx4 v[234:235], off
	v_lshl_add_u64 v[234:235], s[12:13], 0, v[168:169]
	s_add_i32 m0, s39, 0x2000
	s_nop 0
	global_load_lds_dwordx4 v[234:235], off
	v_lshl_add_u64 v[234:235], s[30:31], 0, v[162:163]
	s_mov_b32 m0, s17
	s_nop 0
	global_load_lds_dwordx4 v[234:235], off
	s_mov_b32 m0, s36
	s_nop 0
	global_load_lds_dwordx4 v[236:237], off
	s_waitcnt vmcnt(8)
	s_waitcnt lgkmcnt(0)
	s_setprio 1
	s_barrier
; #define PG8_STAGE(bufoff, gbase, voff) do { _Pragma("unroll") for (int _i = 0; _i < 2; ++_i) \
;         __builtin_amdgcn_global_load_lds((const unsigned*)((const char*)(gbase) + (voff)[_i]), (PG8_LAS unsigned*)(lds + (bufoff) + ldsw + _i * 8192), 16, 0, 0); } while (0)
; #define PG8_LDA(dst, b, h) do { _Pragma("unroll") for (int m = 0; m < 4; ++m) _Pragma("unroll") for (int k = 0; k < 2; ++k) dst[m][k] = *(const PG8_LAS bf16x8*)(lds + PG8_SA(b, h) + aoff + m * 2048 + k * 1024); } while (0)
; #define PG8_LDB(dst, b, h) do { _Pragma("unroll") for (int n = 0; n < 2; ++n) _Pragma("unroll") for (int k = 0; k < 2; ++k) dst[n][k] = *(const PG8_LAS bf16x8*)(lds + PG8_SB(b, h) + boff + n * 2048 + k * 1024); } while (0)
; #define PG8_MMA(ai, bj, At, Bt) do { __builtin_amdgcn_s_setprio(1); _Pragma("unroll") for (int m = 0; m < 4; ++m) _Pragma("unroll") for (int n = 0; n < 2; ++n) _Pragma("unroll") for (int k = 0; k < 2; ++k) \
;         acc[ai][bj][m][n] = __builtin_amdgcn_mfma_f32_16x16x32_bf16(Bt[n][k], At[m][k], acc[ai][bj][m][n], 0, 0, 0); __builtin_amdgcn_s_setprio(0); } while (0)
; #define PG8_WAIT_V(n) asm volatile("s_waitcnt vmcnt(" #n ")" ::: "memory")
; #define PG8_WAIT_L(n) asm volatile("s_waitcnt lgkmcnt(" #n ")" ::: "memory")
; #define PG8_BAR __builtin_amdgcn_s_barrier()
; #define PG8_SCHED __builtin_amdgcn_sched_barrier(0)
; template <class Epi, class Sched, bool ALIGN_EPI = false, bool SP2 = false>
; __device__ __forceinline__ void gemm_phase(PG8_LAS unsigned char* lds, const Gemm g, const Sched& S, const Epi& E, const int wave_id) {
;     ...
;             PG8_WAIT_V(8); PG8_WAIT_L(0); PG8_BAR; PG8_MMA(1, 0, At, B0); PG8_MMA(1, 1, At, B1); PG8_BAR; PG8_SCHED;
;             PG8_LDB(B0, 1, 0); PG8_LDB(B1, 1, 1); PG8_SCHED; PG8_LDA(At, 1, 0); PG8_STAGE(PG8_SA(0, 1), a2 + hstepA, voffA);
;             PG8_WAIT_V(8); PG8_WAIT_L(0); PG8_BAR; PG8_MMA(0, 0, At, B0); PG8_MMA(0, 1, At, B1); PG8_BAR; PG8_SCHED;
	v_mfma_f32_16x16x32_bf16 v[62:65], v[122:125], v[182:185], v[62:65]
	v_mfma_f32_16x16x32_bf16 v[58:61], v[138:141], v[182:185], v[58:61]
	v_mfma_f32_16x16x32_bf16 v[46:49], v[122:125], v[190:193], v[46:49]
	v_mfma_f32_16x16x32_bf16 v[42:45], v[138:141], v[190:193], v[42:45]
	v_mfma_f32_16x16x32_bf16 v[30:33], v[122:125], v[198:201], v[30:33]
	v_mfma_f32_16x16x32_bf16 v[26:29], v[138:141], v[198:201], v[26:29]
	v_mfma_f32_16x16x32_bf16 v[14:17], v[122:125], v[214:217], v[14:17]
	v_mfma_f32_16x16x32_bf16 v[10:13], v[138:141], v[214:217], v[10:13]
	v_mfma_f32_16x16x32_bf16 v[62:65], v[134:137], v[186:189], v[62:65]
	v_mfma_f32_16x16x32_bf16 v[58:61], v[142:145], v[186:189], v[58:61]
	v_mfma_f32_16x16x32_bf16 v[46:49], v[134:137], v[194:197], v[46:49]
	v_mfma_f32_16x16x32_bf16 v[42:45], v[142:145], v[194:197], v[42:45]
	v_mfma_f32_16x16x32_bf16 v[30:33], v[134:137], v[202:205], v[30:33]
	v_mfma_f32_16x16x32_bf16 v[26:29], v[142:145], v[202:205], v[26:29]
	v_mfma_f32_16x16x32_bf16 v[14:17], v[134:137], v[218:221], v[14:17]
	v_mfma_f32_16x16x32_bf16 v[10:13], v[142:145], v[218:221], v[10:13]
	v_mfma_f32_16x16x32_bf16 v[54:57], v[146:149], v[182:185], v[54:57]
	v_mfma_f32_16x16x32_bf16 v[50:53], v[154:157], v[182:185], v[50:53]
	v_mfma_f32_16x16x32_bf16 v[38:41], v[146:149], v[190:193], v[38:41]
	v_mfma_f32_16x16x32_bf16 v[34:37], v[154:157], v[190:193], v[34:37]
	v_mfma_f32_16x16x32_bf16 v[22:25], v[146:149], v[198:201], v[22:25]
	v_mfma_f32_16x16x32_bf16 v[18:21], v[154:157], v[198:201], v[18:21]
	v_mfma_f32_16x16x32_bf16 v[6:9], v[146:149], v[214:217], v[6:9]
	v_mfma_f32_16x16x32_bf16 v[2:5], v[154:157], v[214:217], v[2:5]
	v_mfma_f32_16x16x32_bf16 v[54:57], v[150:153], v[186:189], v[54:57]
	v_mfma_f32_16x16x32_bf16 v[50:53], v[158:161], v[186:189], v[50:53]
	v_mfma_f32_16x16x32_bf16 v[38:41], v[150:153], v[194:197], v[38:41]
	v_mfma_f32_16x16x32_bf16 v[34:37], v[158:161], v[194:197], v[34:37]
	v_mfma_f32_16x16x32_bf16 v[22:25], v[150:153], v[202:205], v[22:25]
	v_mfma_f32_16x16x32_bf16 v[18:21], v[158:161], v[202:205], v[18:21]
	v_mfma_f32_16x16x32_bf16 v[6:9], v[150:153], v[218:221], v[6:9]
	v_mfma_f32_16x16x32_bf16 v[2:5], v[158:161], v[218:221], v[2:5]
	s_setprio 0
	s_barrier
	s_add_i32 s39, 0, 0x18000
	v_add_u32_e32 v0, s39, v206
	s_add_i32 vcc_hi, 0, 0x1c000
	ds_read_b128 v[122:125], v0
	ds_read_b128 v[134:137], v0 offset:1024
	ds_read_b128 v[138:141], v0 offset:2048
	ds_read_b128 v[142:145], v0 offset:3072
	v_add_u32_e32 v0, vcc_hi, v206
	ds_read_b128 v[146:149], v0
	ds_read_b128 v[150:153], v0 offset:1024
	ds_read_b128 v[154:157], v0 offset:2048
	ds_read_b128 v[158:161], v0 offset:3072
	s_add_u32 s12, s30, 0x180000
	s_addc_u32 s13, s31, 0
	s_mov_b32 m0, s37
	v_lshl_add_u64 v[240:241], s[12:13], 0, v[162:163]
	ds_read_b128 v[182:185], v212 offset:32768
	ds_read_b128 v[186:189], v212 offset:33792
	ds_read_b128 v[190:193], v212 offset:34816
	ds_read_b128 v[194:197], v212 offset:35840
	ds_read_b128 v[198:201], v212 offset:36864
	ds_read_b128 v[202:205], v212 offset:37888
	ds_read_b128 v[214:217], v212 offset:38912
	ds_read_b128 v[218:221], v212 offset:39936
	global_load_lds_dwordx4 v[240:241], off
	v_lshl_add_u64 v[240:241], s[12:13], 0, v[166:167]
	s_mov_b32 m0, s76
	s_nop 0
	global_load_lds_dwordx4 v[240:241], off
	s_waitcnt vmcnt(8)
	s_waitcnt lgkmcnt(0)
	s_setprio 1
	s_barrier
	v_mfma_f32_16x16x32_bf16 v[130:133], v[122:125], v[182:185], v[130:133]
	v_mfma_f32_16x16x32_bf16 v[126:129], v[138:141], v[182:185], v[126:129]
	v_mfma_f32_16x16x32_bf16 v[110:113], v[122:125], v[190:193], v[110:113]
	v_mfma_f32_16x16x32_bf16 v[106:109], v[138:141], v[190:193], v[106:109]
	v_mfma_f32_16x16x32_bf16 v[94:97], v[122:125], v[198:201], v[94:97]
	v_mfma_f32_16x16x32_bf16 v[90:93], v[138:141], v[198:201], v[90:93]
	v_mfma_f32_16x16x32_bf16 v[78:81], v[122:125], v[214:217], v[78:81]
	v_mfma_f32_16x16x32_bf16 v[74:77], v[138:141], v[214:217], v[74:77]
	v_mfma_f32_16x16x32_bf16 v[130:133], v[134:137], v[186:189], v[130:133]
	v_mfma_f32_16x16x32_bf16 v[126:129], v[142:145], v[186:189], v[126:129]
	v_mfma_f32_16x16x32_bf16 v[110:113], v[134:137], v[194:197], v[110:113]
	v_mfma_f32_16x16x32_bf16 v[106:109], v[142:145], v[194:197], v[106:109]
	v_mfma_f32_16x16x32_bf16 v[94:97], v[134:137], v[202:205], v[94:97]
	v_mfma_f32_16x16x32_bf16 v[90:93], v[142:145], v[202:205], v[90:93]
	v_mfma_f32_16x16x32_bf16 v[78:81], v[134:137], v[218:221], v[78:81]
	v_mfma_f32_16x16x32_bf16 v[74:77], v[142:145], v[218:221], v[74:77]
	v_mfma_f32_16x16x32_bf16 v[118:121], v[146:149], v[182:185], v[118:121]
	v_mfma_f32_16x16x32_bf16 v[114:117], v[154:157], v[182:185], v[114:117]
	v_mfma_f32_16x16x32_bf16 v[102:105], v[146:149], v[190:193], v[102:105]
	v_mfma_f32_16x16x32_bf16 v[98:101], v[154:157], v[190:193], v[98:101]
	v_mfma_f32_16x16x32_bf16 v[86:89], v[146:149], v[198:201], v[86:89]
	v_mfma_f32_16x16x32_bf16 v[82:85], v[154:157], v[198:201], v[82:85]
	v_mfma_f32_16x16x32_bf16 v[70:73], v[146:149], v[214:217], v[70:73]
	v_mfma_f32_16x16x32_bf16 v[66:69], v[154:157], v[214:217], v[66:69]
	v_mfma_f32_16x16x32_bf16 v[118:121], v[150:153], v[186:189], v[118:121]
	v_mfma_f32_16x16x32_bf16 v[114:117], v[158:161], v[186:189], v[114:117]
	v_mfma_f32_16x16x32_bf16 v[102:105], v[150:153], v[194:197], v[102:105]
	v_mfma_f32_16x16x32_bf16 v[98:101], v[158:161], v[194:197], v[98:101]
	v_mfma_f32_16x16x32_bf16 v[86:89], v[150:153], v[202:205], v[86:89]
	v_mfma_f32_16x16x32_bf16 v[82:85], v[158:161], v[202:205], v[82:85]
	v_mfma_f32_16x16x32_bf16 v[70:73], v[150:153], v[218:221], v[70:73]
	v_mfma_f32_16x16x32_bf16 v[66:69], v[158:161], v[218:221], v[66:69]
	s_setprio 0
	s_barrier
; #define PG8_STAGE(bufoff, gbase, voff) do { _Pragma("unroll") for (int _i = 0; _i < 2; ++_i) \
;         __builtin_amdgcn_global_load_lds((const unsigned*)((const char*)(gbase) + (voff)[_i]), (PG8_LAS unsigned*)(lds + (bufoff) + ldsw + _i * 8192), 16, 0, 0); } while (0)
; #define PG8_LDA(dst, b, h) do { _Pragma("unroll") for (int m = 0; m < 4; ++m) _Pragma("unroll") for (int k = 0; k < 2; ++k) dst[m][k] = *(const PG8_LAS bf16x8*)(lds + PG8_SA(b, h) + aoff + m * 2048 + k * 1024); } while (0)
; #define PG8_MMA(ai, bj, At, Bt) do { __builtin_amdgcn_s_setprio(1); _Pragma("unroll") for (int m = 0; m < 4; ++m) _Pragma("unroll") for (int n = 0; n < 2; ++n) _Pragma("unroll") for (int k = 0; k < 2; ++k) \
;         acc[ai][bj][m][n] = __builtin_amdgcn_mfma_f32_16x16x32_bf16(Bt[n][k], At[m][k], acc[ai][bj][m][n], 0, 0, 0); __builtin_amdgcn_s_setprio(0); } while (0)
; #define PG8_WAIT_V(n) asm volatile("s_waitcnt vmcnt(" #n ")" ::: "memory")
; #define PG8_WAIT_L(n) asm volatile("s_waitcnt lgkmcnt(" #n ")" ::: "memory")
; #define PG8_BAR __builtin_amdgcn_s_barrier()
; #define PG8_SCHED __builtin_amdgcn_sched_barrier(0)
; template <class Epi, class Sched, bool ALIGN_EPI = false, bool SP2 = false>
; __device__ __forceinline__ void gemm_phase(PG8_LAS unsigned char* lds, const Gemm g, const Sched& S, const Epi& E, const int wave_id) {
;     ...
;         for (int t = 0; t < nt; t += 2) {
;     ...
;             PG8_LDA(At, 1, 1); PG8_STAGE(PG8_SB(1, 0), b3, voffB); PG8_STAGE(PG8_SB(1, 1), b3 + hstepB, voffB); PG8_STAGE(PG8_SA(1, 0), a3, voffA);
;             PG8_WAIT_V(8); PG8_WAIT_L(0); PG8_BAR; PG8_MMA(1, 0, At, B0); PG8_MMA(1, 1, At, B1); PG8_BAR; PG8_SCHED;
	s_add_i32 s12, s39, s35
	v_lshl_add_u64 v[222:223], v[222:223], 0, s[62:63]
	s_mov_b32 m0, s12
	ds_read_b128 v[182:185], v212 offset:49152
	ds_read_b128 v[186:189], v212 offset:50176
	ds_read_b128 v[190:193], v212 offset:51200
	ds_read_b128 v[194:197], v212 offset:52224
	ds_read_b128 v[198:201], v212 offset:53248
	ds_read_b128 v[202:205], v212 offset:54272
	ds_read_b128 v[214:217], v212 offset:55296
	ds_read_b128 v[218:221], v212 offset:56320
	global_load_lds_dwordx4 v[222:223], off
	s_add_i32 m0, s12, 0x2000
	s_add_u32 s12, s28, 0x80080
	v_lshl_add_u64 v[222:223], v[224:225], 0, s[62:63]
	s_addc_u32 s13, s29, 0
	s_add_i32 s28, vcc_hi, s35
	global_load_lds_dwordx4 v[222:223], off
	v_lshl_add_u64 v[222:223], s[12:13], 0, v[164:165]
	s_mov_b32 m0, s28
	s_nop 0
	global_load_lds_dwordx4 v[222:223], off
	v_lshl_add_u64 v[222:223], s[12:13], 0, v[168:169]
	s_add_i32 m0, s28, 0x2000
	s_nop 0
	global_load_lds_dwordx4 v[222:223], off
	v_lshl_add_u64 v[222:223], v[234:235], 0, s[62:63]
	s_mov_b32 m0, s80
	s_nop 0
	global_load_lds_dwordx4 v[222:223], off
	v_lshl_add_u64 v[222:223], v[236:237], 0, s[62:63]
	s_mov_b32 m0, s81
	s_nop 0
	global_load_lds_dwordx4 v[222:223], off
	s_waitcnt vmcnt(8)
	s_waitcnt lgkmcnt(0)
	s_setprio 1
	s_barrier
	v_mfma_f32_16x16x32_bf16 v[62:65], v[122:125], v[182:185], v[62:65]
	v_mfma_f32_16x16x32_bf16 v[58:61], v[138:141], v[182:185], v[58:61]
	v_mfma_f32_16x16x32_bf16 v[46:49], v[122:125], v[190:193], v[46:49]
	v_mfma_f32_16x16x32_bf16 v[42:45], v[138:141], v[190:193], v[42:45]
	v_mfma_f32_16x16x32_bf16 v[30:33], v[122:125], v[198:201], v[30:33]
	v_mfma_f32_16x16x32_bf16 v[26:29], v[138:141], v[198:201], v[26:29]
	v_mfma_f32_16x16x32_bf16 v[14:17], v[122:125], v[214:217], v[14:17]
	v_mfma_f32_16x16x32_bf16 v[10:13], v[138:141], v[214:217], v[10:13]
	v_mfma_f32_16x16x32_bf16 v[62:65], v[134:137], v[186:189], v[62:65]
	v_mfma_f32_16x16x32_bf16 v[58:61], v[142:145], v[186:189], v[58:61]
	v_mfma_f32_16x16x32_bf16 v[46:49], v[134:137], v[194:197], v[46:49]
	v_mfma_f32_16x16x32_bf16 v[42:45], v[142:145], v[194:197], v[42:45]
	v_mfma_f32_16x16x32_bf16 v[30:33], v[134:137], v[202:205], v[30:33]
	v_mfma_f32_16x16x32_bf16 v[26:29], v[142:145], v[202:205], v[26:29]
	v_mfma_f32_16x16x32_bf16 v[14:17], v[134:137], v[218:221], v[14:17]
	v_mfma_f32_16x16x32_bf16 v[10:13], v[142:145], v[218:221], v[10:13]
	v_mfma_f32_16x16x32_bf16 v[54:57], v[146:149], v[182:185], v[54:57]
	v_mfma_f32_16x16x32_bf16 v[50:53], v[154:157], v[182:185], v[50:53]
	v_mfma_f32_16x16x32_bf16 v[38:41], v[146:149], v[190:193], v[38:41]
	v_mfma_f32_16x16x32_bf16 v[34:37], v[154:157], v[190:193], v[34:37]
	v_mfma_f32_16x16x32_bf16 v[22:25], v[146:149], v[198:201], v[22:25]
	v_mfma_f32_16x16x32_bf16 v[18:21], v[154:157], v[198:201], v[18:21]
	v_mfma_f32_16x16x32_bf16 v[6:9], v[146:149], v[214:217], v[6:9]
	v_mfma_f32_16x16x32_bf16 v[2:5], v[154:157], v[214:217], v[2:5]
	v_mfma_f32_16x16x32_bf16 v[54:57], v[150:153], v[186:189], v[54:57]
	v_mfma_f32_16x16x32_bf16 v[50:53], v[158:161], v[186:189], v[50:53]
	v_mfma_f32_16x16x32_bf16 v[38:41], v[150:153], v[194:197], v[38:41]
	v_mfma_f32_16x16x32_bf16 v[34:37], v[158:161], v[194:197], v[34:37]
	v_mfma_f32_16x16x32_bf16 v[22:25], v[150:153], v[202:205], v[22:25]
	v_mfma_f32_16x16x32_bf16 v[18:21], v[158:161], v[202:205], v[18:21]
	v_mfma_f32_16x16x32_bf16 v[6:9], v[150:153], v[218:221], v[6:9]
	v_mfma_f32_16x16x32_bf16 v[2:5], v[158:161], v[218:221], v[2:5]
	s_setprio 0
	s_barrier
	s_add_i32 vcc_lo, vcc_lo, 2
	s_add_u32 s38, s38, 0x100
	s_addc_u32 s91, s91, 0
	s_cmp_gt_u32 vcc_lo, 29
	s_mov_b64 s[12:13], s[10:11]
	s_cbranch_scc0 .LBB0_189
	s_and_b64 vcc, exec, s[20:21]
	s_cbranch_vccz .LBB0_192
	s_barrier

; #define PG8_STAGE(bufoff, gbase, voff) do { _Pragma("unroll") for (int _i = 0; _i < 2; ++_i) \
;         __builtin_amdgcn_global_load_lds((const unsigned*)((const char*)(gbase) + (voff)[_i]), (PG8_LAS unsigned*)(lds + (bufoff) + ldsw + _i * 8192), 16, 0, 0); } while (0)
; #define PG8_LDA(dst, b, h) do { _Pragma("unroll") for (int m = 0; m < 4; ++m) _Pragma("unroll") for (int k = 0; k < 2; ++k) dst[m][k] = *(const PG8_LAS bf16x8*)(lds + PG8_SA(b, h) + aoff + m * 2048 + k * 1024); } while (0)
; #define PG8_LDB(dst, b, h) do { _Pragma("unroll") for (int n = 0; n < 2; ++n) _Pragma("unroll") for (int k = 0; k < 2; ++k) dst[n][k] = *(const PG8_LAS bf16x8*)(lds + PG8_SB(b, h) + boff + n * 2048 + k * 1024); } while (0)
; #define PG8_MMA(ai, bj, At, Bt) do { __builtin_amdgcn_s_setprio(1); _Pragma("unroll") for (int m = 0; m < 4; ++m) _Pragma("unroll") for (int n = 0; n < 2; ++n) _Pragma("unroll") for (int k = 0; k < 2; ++k) \
;         acc[ai][bj][m][n] = __builtin_amdgcn_mfma_f32_16x16x32_bf16(Bt[n][k], At[m][k], acc[ai][bj][m][n], 0, 0, 0); __builtin_amdgcn_s_setprio(0); } while (0)
; #define PG8_WAIT_V(n) asm volatile("s_waitcnt vmcnt(" #n ")" ::: "memory")
; #define PG8_WAIT_L(n) asm volatile("s_waitcnt lgkmcnt(" #n ")" ::: "memory")
; #define PG8_BAR __builtin_amdgcn_s_barrier()
; template <class Epi, class Sched, bool ALIGN_EPI = false, bool SP2 = false>
; __device__ __forceinline__ void gemm_phase(PG8_LAS unsigned char* lds, const Gemm g, const Sched& S, const Epi& E, const int wave_id) {
;     ...
;             const char* a1 = cA + (size_t)(t + 1) * kstep;
;             const char* a2 = last ? nA : cA + (size_t)(t + 2) * kstep; const char* b2 = last ? nB : cB + (size_t)(t + 2) * kstep;
;             const char* a3 = a2 + kstep; const char* b3 = b2 + kstep;
;             if (last && has_next) S.a_ready(nxt);
;             if constexpr (SP2) {
;             PG8_LDB(B0, 0, 0); PG8_LDB(B1, 0, 1); PG8_SCHED; PG8_LDA(At, 0, 0); PG8_STAGE(PG8_SA(1, 1), a1 + hstepA, voffA);
;             PG8_WAIT_V(8); PG8_WAIT_L(0); PG8_BAR; PG8_MMA(0, 0, At, B0); PG8_MMA(0, 1, At, B1); PG8_BAR; PG8_SCHED;
;             PG8_LDA(At, 0, 1); PG8_STAGE(PG8_SB(0, 0), b2, voffB); PG8_STAGE(PG8_SB(0, 1), b2 + hstepB, voffB); PG8_STAGE(PG8_SA(0, 0), a2, voffA);
;             PG8_WAIT_V(8); PG8_WAIT_L(0); PG8_BAR; PG8_MMA(1, 0, At, B0); PG8_MMA(1, 1, At, B1); PG8_BAR; PG8_SCHED;
.LBB0_297:
	s_add_u32 s12, s10, 0xfffc0080
	s_addc_u32 s13, s11, -1
	s_add_i32 s20, 0, 0x10000
	s_cmp_eq_u32 vcc_lo, 12
	s_cselect_b32 s35, s15, s13
	s_cselect_b32 s34, s27, s12
	v_add_u32_e32 v0, s20, v206
	s_cselect_b32 s13, s25, s38
	s_cselect_b32 s12, s36, s37
	s_add_i32 vcc_hi, 0, 0x14000
	ds_read_b128 v[122:125], v0
	ds_read_b128 v[134:137], v0 offset:1024
	ds_read_b128 v[138:141], v0 offset:2048
	ds_read_b128 v[142:145], v0 offset:3072
	v_add_u32_e32 v0, vcc_hi, v206
	ds_read_b128 v[146:149], v0
	ds_read_b128 v[150:153], v0 offset:1024
	ds_read_b128 v[154:157], v0 offset:2048
	ds_read_b128 v[158:161], v0 offset:3072
	v_lshl_add_u64 v[222:223], s[10:11], 0, v[178:179]
	s_add_i32 m0, s17, 0xc000
	ds_read_b128 v[182:185], v212
	ds_read_b128 v[186:189], v212 offset:1024
	ds_read_b128 v[190:193], v212 offset:2048
	ds_read_b128 v[194:197], v212 offset:3072
	ds_read_b128 v[198:201], v212 offset:4096
	ds_read_b128 v[202:205], v212 offset:5120
	ds_read_b128 v[214:217], v212 offset:6144
	ds_read_b128 v[218:221], v212 offset:7168
	global_load_lds_dwordx4 v[222:223], off
	v_lshl_add_u64 v[222:223], s[10:11], 0, v[180:181]
	s_add_i32 m0, s17, 0xe000
	s_nop 0
	global_load_lds_dwordx4 v[222:223], off
	s_waitcnt vmcnt(8)
	s_waitcnt lgkmcnt(0)
	s_setprio 1
	s_barrier
	v_mfma_f32_16x16x32_bf16 v[130:133], v[122:125], v[182:185], v[130:133]
	v_mfma_f32_16x16x32_bf16 v[126:129], v[138:141], v[182:185], v[126:129]
	v_mfma_f32_16x16x32_bf16 v[110:113], v[122:125], v[190:193], v[110:113]
	v_mfma_f32_16x16x32_bf16 v[106:109], v[138:141], v[190:193], v[106:109]
	v_mfma_f32_16x16x32_bf16 v[94:97], v[122:125], v[198:201], v[94:97]
	v_mfma_f32_16x16x32_bf16 v[90:93], v[138:141], v[198:201], v[90:93]
	v_mfma_f32_16x16x32_bf16 v[78:81], v[122:125], v[214:217], v[78:81]
	v_mfma_f32_16x16x32_bf16 v[74:77], v[138:141], v[214:217], v[74:77]
	v_mfma_f32_16x16x32_bf16 v[130:133], v[134:137], v[186:189], v[130:133]
	v_mfma_f32_16x16x32_bf16 v[126:129], v[142:145], v[186:189], v[126:129]
	v_mfma_f32_16x16x32_bf16 v[110:113], v[134:137], v[194:197], v[110:113]
	v_mfma_f32_16x16x32_bf16 v[106:109], v[142:145], v[194:197], v[106:109]
	v_mfma_f32_16x16x32_bf16 v[94:97], v[134:137], v[202:205], v[94:97]
	v_mfma_f32_16x16x32_bf16 v[90:93], v[142:145], v[202:205], v[90:93]
	v_mfma_f32_16x16x32_bf16 v[78:81], v[134:137], v[218:221], v[78:81]
	v_mfma_f32_16x16x32_bf16 v[74:77], v[142:145], v[218:221], v[74:77]
	v_mfma_f32_16x16x32_bf16 v[118:121], v[146:149], v[182:185], v[118:121]
	v_mfma_f32_16x16x32_bf16 v[114:117], v[154:157], v[182:185], v[114:117]
	v_mfma_f32_16x16x32_bf16 v[102:105], v[146:149], v[190:193], v[102:105]
	v_mfma_f32_16x16x32_bf16 v[98:101], v[154:157], v[190:193], v[98:101]
	v_mfma_f32_16x16x32_bf16 v[86:89], v[146:149], v[198:201], v[86:89]
	v_mfma_f32_16x16x32_bf16 v[82:85], v[154:157], v[198:201], v[82:85]
	v_mfma_f32_16x16x32_bf16 v[70:73], v[146:149], v[214:217], v[70:73]
	v_mfma_f32_16x16x32_bf16 v[66:69], v[154:157], v[214:217], v[66:69]
	v_mfma_f32_16x16x32_bf16 v[118:121], v[150:153], v[186:189], v[118:121]
	v_mfma_f32_16x16x32_bf16 v[114:117], v[158:161], v[186:189], v[114:117]
	v_mfma_f32_16x16x32_bf16 v[102:105], v[150:153], v[194:197], v[102:105]
	v_mfma_f32_16x16x32_bf16 v[98:101], v[158:161], v[194:197], v[98:101]
	v_mfma_f32_16x16x32_bf16 v[86:89], v[150:153], v[202:205], v[86:89]
	v_mfma_f32_16x16x32_bf16 v[82:85], v[158:161], v[202:205], v[82:85]
	v_mfma_f32_16x16x32_bf16 v[70:73], v[150:153], v[218:221], v[70:73]
	v_mfma_f32_16x16x32_bf16 v[66:69], v[158:161], v[218:221], v[66:69]
	s_setprio 0
	s_barrier
	s_add_i32 s20, s20, s76
	v_lshl_add_u64 v[222:223], s[12:13], 0, v[164:165]
	s_mov_b32 m0, s20
	ds_read_b128 v[182:185], v212 offset:16384
	ds_read_b128 v[186:189], v212 offset:17408
	ds_read_b128 v[190:193], v212 offset:18432
	ds_read_b128 v[194:197], v212 offset:19456
	ds_read_b128 v[198:201], v212 offset:20480
	ds_read_b128 v[202:205], v212 offset:21504
	ds_read_b128 v[214:217], v212 offset:22528
	ds_read_b128 v[218:221], v212 offset:23552
	global_load_lds_dwordx4 v[222:223], off
	s_add_i32 m0, s20, 0x2000
	s_add_u32 s20, s12, 0x40000
	v_lshl_add_u64 v[224:225], s[12:13], 0, v[168:169]
	s_addc_u32 s21, s13, 0
	s_add_i32 vcc_hi, vcc_hi, s76
	global_load_lds_dwordx4 v[224:225], off
	v_lshl_add_u64 v[234:235], s[20:21], 0, v[164:165]
	s_mov_b32 m0, vcc_hi
	v_lshl_add_u64 v[236:237], s[34:35], 0, v[166:167]
	global_load_lds_dwordx4 v[234:235], off
	v_lshl_add_u64 v[234:235], s[20:21], 0, v[168:169]
	s_add_i32 m0, vcc_hi, 0x2000
	s_nop 0
	global_load_lds_dwordx4 v[234:235], off
	v_lshl_add_u64 v[234:235], s[34:35], 0, v[162:163]
	s_mov_b32 m0, s17
	s_nop 0
	global_load_lds_dwordx4 v[234:235], off
	s_mov_b32 m0, s19
	s_nop 0
	global_load_lds_dwordx4 v[236:237], off
	s_waitcnt vmcnt(8)
	s_waitcnt lgkmcnt(0)
	s_setprio 1
	s_barrier
; #define PG8_STAGE(bufoff, gbase, voff) do { _Pragma("unroll") for (int _i = 0; _i < 2; ++_i) \
;         __builtin_amdgcn_global_load_lds((const unsigned*)((const char*)(gbase) + (voff)[_i]), (PG8_LAS unsigned*)(lds + (bufoff) + ldsw + _i * 8192), 16, 0, 0); } while (0)
; #define PG8_LDA(dst, b, h) do { _Pragma("unroll") for (int m = 0; m < 4; ++m) _Pragma("unroll") for (int k = 0; k < 2; ++k) dst[m][k] = *(const PG8_LAS bf16x8*)(lds + PG8_SA(b, h) + aoff + m * 2048 + k * 1024); } while (0)
; #define PG8_LDB(dst, b, h) do { _Pragma("unroll") for (int n = 0; n < 2; ++n) _Pragma("unroll") for (int k = 0; k < 2; ++k) dst[n][k] = *(const PG8_LAS bf16x8*)(lds + PG8_SB(b, h) + boff + n * 2048 + k * 1024); } while (0)
; #define PG8_MMA(ai, bj, At, Bt) do { __builtin_amdgcn_s_setprio(1); _Pragma("unroll") for (int m = 0; m < 4; ++m) _Pragma("unroll") for (int n = 0; n < 2; ++n) _Pragma("unroll") for (int k = 0; k < 2; ++k) \
;         acc[ai][bj][m][n] = __builtin_amdgcn_mfma_f32_16x16x32_bf16(Bt[n][k], At[m][k], acc[ai][bj][m][n], 0, 0, 0); __builtin_amdgcn_s_setprio(0); } while (0)
; #define PG8_WAIT_V(n) asm volatile("s_waitcnt vmcnt(" #n ")" ::: "memory")
; #define PG8_WAIT_L(n) asm volatile("s_waitcnt lgkmcnt(" #n ")" ::: "memory")
; #define PG8_BAR __builtin_amdgcn_s_barrier()
; #define PG8_SCHED __builtin_amdgcn_sched_barrier(0)
; template <class Epi, class Sched, bool ALIGN_EPI = false, bool SP2 = false>
; __device__ __forceinline__ void gemm_phase(PG8_LAS unsigned char* lds, const Gemm g, const Sched& S, const Epi& E, const int wave_id) {
;     ...
;             PG8_WAIT_V(8); PG8_WAIT_L(0); PG8_BAR; PG8_MMA(1, 0, At, B0); PG8_MMA(1, 1, At, B1); PG8_BAR; PG8_SCHED;
;             PG8_LDB(B0, 1, 0); PG8_LDB(B1, 1, 1); PG8_SCHED; PG8_LDA(At, 1, 0); PG8_STAGE(PG8_SA(0, 1), a2 + hstepA, voffA);
;             PG8_WAIT_V(8); PG8_WAIT_L(0); PG8_BAR; PG8_MMA(0, 0, At, B0); PG8_MMA(0, 1, At, B1); PG8_BAR; PG8_SCHED;
	v_mfma_f32_16x16x32_bf16 v[62:65], v[122:125], v[182:185], v[62:65]
	v_mfma_f32_16x16x32_bf16 v[58:61], v[138:141], v[182:185], v[58:61]
	v_mfma_f32_16x16x32_bf16 v[46:49], v[122:125], v[190:193], v[46:49]
	v_mfma_f32_16x16x32_bf16 v[42:45], v[138:141], v[190:193], v[42:45]
	v_mfma_f32_16x16x32_bf16 v[30:33], v[122:125], v[198:201], v[30:33]
	v_mfma_f32_16x16x32_bf16 v[26:29], v[138:141], v[198:201], v[26:29]
	v_mfma_f32_16x16x32_bf16 v[14:17], v[122:125], v[214:217], v[14:17]
	v_mfma_f32_16x16x32_bf16 v[10:13], v[138:141], v[214:217], v[10:13]
	v_mfma_f32_16x16x32_bf16 v[62:65], v[134:137], v[186:189], v[62:65]
	v_mfma_f32_16x16x32_bf16 v[58:61], v[142:145], v[186:189], v[58:61]
	v_mfma_f32_16x16x32_bf16 v[46:49], v[134:137], v[194:197], v[46:49]
	v_mfma_f32_16x16x32_bf16 v[42:45], v[142:145], v[194:197], v[42:45]
	v_mfma_f32_16x16x32_bf16 v[30:33], v[134:137], v[202:205], v[30:33]
	v_mfma_f32_16x16x32_bf16 v[26:29], v[142:145], v[202:205], v[26:29]
	v_mfma_f32_16x16x32_bf16 v[14:17], v[134:137], v[218:221], v[14:17]
	v_mfma_f32_16x16x32_bf16 v[10:13], v[142:145], v[218:221], v[10:13]
	v_mfma_f32_16x16x32_bf16 v[54:57], v[146:149], v[182:185], v[54:57]
	v_mfma_f32_16x16x32_bf16 v[50:53], v[154:157], v[182:185], v[50:53]
	v_mfma_f32_16x16x32_bf16 v[38:41], v[146:149], v[190:193], v[38:41]
	v_mfma_f32_16x16x32_bf16 v[34:37], v[154:157], v[190:193], v[34:37]
	v_mfma_f32_16x16x32_bf16 v[22:25], v[146:149], v[198:201], v[22:25]
	v_mfma_f32_16x16x32_bf16 v[18:21], v[154:157], v[198:201], v[18:21]
	v_mfma_f32_16x16x32_bf16 v[6:9], v[146:149], v[214:217], v[6:9]
	v_mfma_f32_16x16x32_bf16 v[2:5], v[154:157], v[214:217], v[2:5]
	v_mfma_f32_16x16x32_bf16 v[54:57], v[150:153], v[186:189], v[54:57]
	v_mfma_f32_16x16x32_bf16 v[50:53], v[158:161], v[186:189], v[50:53]
	v_mfma_f32_16x16x32_bf16 v[38:41], v[150:153], v[194:197], v[38:41]
	v_mfma_f32_16x16x32_bf16 v[34:37], v[158:161], v[194:197], v[34:37]
	v_mfma_f32_16x16x32_bf16 v[22:25], v[150:153], v[202:205], v[22:25]
	v_mfma_f32_16x16x32_bf16 v[18:21], v[158:161], v[202:205], v[18:21]
	v_mfma_f32_16x16x32_bf16 v[6:9], v[150:153], v[218:221], v[6:9]
	v_mfma_f32_16x16x32_bf16 v[2:5], v[158:161], v[218:221], v[2:5]
	s_setprio 0
	s_barrier
	s_add_i32 vcc_hi, 0, 0x18000
	v_add_u32_e32 v0, vcc_hi, v206
	s_add_i32 s39, 0, 0x1c000
	ds_read_b128 v[122:125], v0
	ds_read_b128 v[134:137], v0 offset:1024
	ds_read_b128 v[138:141], v0 offset:2048
	ds_read_b128 v[142:145], v0 offset:3072
	v_add_u32_e32 v0, s39, v206
	ds_read_b128 v[146:149], v0
	ds_read_b128 v[150:153], v0 offset:1024
	ds_read_b128 v[154:157], v0 offset:2048
	ds_read_b128 v[158:161], v0 offset:3072
	s_add_u32 s20, s34, 0x40000
	s_addc_u32 s21, s35, 0
	s_mov_b32 m0, s77
	v_lshl_add_u64 v[240:241], s[20:21], 0, v[162:163]
	ds_read_b128 v[182:185], v212 offset:32768
	ds_read_b128 v[186:189], v212 offset:33792
	ds_read_b128 v[190:193], v212 offset:34816
	ds_read_b128 v[194:197], v212 offset:35840
	ds_read_b128 v[198:201], v212 offset:36864
	ds_read_b128 v[202:205], v212 offset:37888
	ds_read_b128 v[214:217], v212 offset:38912
	ds_read_b128 v[218:221], v212 offset:39936
	global_load_lds_dwordx4 v[240:241], off
	v_lshl_add_u64 v[240:241], s[20:21], 0, v[166:167]
	s_mov_b32 m0, s80
	s_nop 0
	global_load_lds_dwordx4 v[240:241], off
	s_waitcnt vmcnt(8)
	s_waitcnt lgkmcnt(0)
	s_setprio 1
	s_barrier
	v_mfma_f32_16x16x32_bf16 v[130:133], v[122:125], v[182:185], v[130:133]
	v_mfma_f32_16x16x32_bf16 v[126:129], v[138:141], v[182:185], v[126:129]
	v_mfma_f32_16x16x32_bf16 v[110:113], v[122:125], v[190:193], v[110:113]
	v_mfma_f32_16x16x32_bf16 v[106:109], v[138:141], v[190:193], v[106:109]
	v_mfma_f32_16x16x32_bf16 v[94:97], v[122:125], v[198:201], v[94:97]
	v_mfma_f32_16x16x32_bf16 v[90:93], v[138:141], v[198:201], v[90:93]
	v_mfma_f32_16x16x32_bf16 v[78:81], v[122:125], v[214:217], v[78:81]
	v_mfma_f32_16x16x32_bf16 v[74:77], v[138:141], v[214:217], v[74:77]
	v_mfma_f32_16x16x32_bf16 v[130:133], v[134:137], v[186:189], v[130:133]
	v_mfma_f32_16x16x32_bf16 v[126:129], v[142:145], v[186:189], v[126:129]
	v_mfma_f32_16x16x32_bf16 v[110:113], v[134:137], v[194:197], v[110:113]
	v_mfma_f32_16x16x32_bf16 v[106:109], v[142:145], v[194:197], v[106:109]
	v_mfma_f32_16x16x32_bf16 v[94:97], v[134:137], v[202:205], v[94:97]
	v_mfma_f32_16x16x32_bf16 v[90:93], v[142:145], v[202:205], v[90:93]
	v_mfma_f32_16x16x32_bf16 v[78:81], v[134:137], v[218:221], v[78:81]
	v_mfma_f32_16x16x32_bf16 v[74:77], v[142:145], v[218:221], v[74:77]
	v_mfma_f32_16x16x32_bf16 v[118:121], v[146:149], v[182:185], v[118:121]
	v_mfma_f32_16x16x32_bf16 v[114:117], v[154:157], v[182:185], v[114:117]
	v_mfma_f32_16x16x32_bf16 v[102:105], v[146:149], v[190:193], v[102:105]
	v_mfma_f32_16x16x32_bf16 v[98:101], v[154:157], v[190:193], v[98:101]
	v_mfma_f32_16x16x32_bf16 v[86:89], v[146:149], v[198:201], v[86:89]
	v_mfma_f32_16x16x32_bf16 v[82:85], v[154:157], v[198:201], v[82:85]
	v_mfma_f32_16x16x32_bf16 v[70:73], v[146:149], v[214:217], v[70:73]
	v_mfma_f32_16x16x32_bf16 v[66:69], v[154:157], v[214:217], v[66:69]
	v_mfma_f32_16x16x32_bf16 v[118:121], v[150:153], v[186:189], v[118:121]
	v_mfma_f32_16x16x32_bf16 v[114:117], v[158:161], v[186:189], v[114:117]
	v_mfma_f32_16x16x32_bf16 v[102:105], v[150:153], v[194:197], v[102:105]
	v_mfma_f32_16x16x32_bf16 v[98:101], v[158:161], v[194:197], v[98:101]
	v_mfma_f32_16x16x32_bf16 v[86:89], v[150:153], v[202:205], v[86:89]
	v_mfma_f32_16x16x32_bf16 v[82:85], v[158:161], v[202:205], v[82:85]
	v_mfma_f32_16x16x32_bf16 v[70:73], v[150:153], v[218:221], v[70:73]
	v_mfma_f32_16x16x32_bf16 v[66:69], v[158:161], v[218:221], v[66:69]
	s_setprio 0
	s_barrier
; #define PG8_STAGE(bufoff, gbase, voff) do { _Pragma("unroll") for (int _i = 0; _i < 2; ++_i) \
;         __builtin_amdgcn_global_load_lds((const unsigned*)((const char*)(gbase) + (voff)[_i]), (PG8_LAS unsigned*)(lds + (bufoff) + ldsw + _i * 8192), 16, 0, 0); } while (0)
; #define PG8_LDA(dst, b, h) do { _Pragma("unroll") for (int m = 0; m < 4; ++m) _Pragma("unroll") for (int k = 0; k < 2; ++k) dst[m][k] = *(const PG8_LAS bf16x8*)(lds + PG8_SA(b, h) + aoff + m * 2048 + k * 1024); } while (0)
; #define PG8_MMA(ai, bj, At, Bt) do { __builtin_amdgcn_s_setprio(1); _Pragma("unroll") for (int m = 0; m < 4; ++m) _Pragma("unroll") for (int n = 0; n < 2; ++n) _Pragma("unroll") for (int k = 0; k < 2; ++k) \
;         acc[ai][bj][m][n] = __builtin_amdgcn_mfma_f32_16x16x32_bf16(Bt[n][k], At[m][k], acc[ai][bj][m][n], 0, 0, 0); __builtin_amdgcn_s_setprio(0); } while (0)
; #define PG8_WAIT_V(n) asm volatile("s_waitcnt vmcnt(" #n ")" ::: "memory")
; #define PG8_WAIT_L(n) asm volatile("s_waitcnt lgkmcnt(" #n ")" ::: "memory")
; #define PG8_BAR __builtin_amdgcn_s_barrier()
; #define PG8_SCHED __builtin_amdgcn_sched_barrier(0)
; template <class Epi, class Sched, bool ALIGN_EPI = false, bool SP2 = false>
; __device__ __forceinline__ void gemm_phase(PG8_LAS unsigned char* lds, const Gemm g, const Sched& S, const Epi& E, const int wave_id) {
;     ...
;         for (int t = 0; t < nt; t += 2) {
;     ...
;             PG8_LDA(At, 1, 1); PG8_STAGE(PG8_SB(1, 0), b3, voffB); PG8_STAGE(PG8_SB(1, 1), b3 + hstepB, voffB); PG8_STAGE(PG8_SA(1, 0), a3, voffA);
;             PG8_WAIT_V(8); PG8_WAIT_L(0); PG8_BAR; PG8_MMA(1, 0, At, B0); PG8_MMA(1, 1, At, B1); PG8_BAR; PG8_SCHED;
	s_add_i32 s20, vcc_hi, s76
	v_lshl_add_u64 v[222:223], v[222:223], 0, s[62:63]
	s_mov_b32 m0, s20
	ds_read_b128 v[182:185], v212 offset:49152
	ds_read_b128 v[186:189], v212 offset:50176
	ds_read_b128 v[190:193], v212 offset:51200
	ds_read_b128 v[194:197], v212 offset:52224
	ds_read_b128 v[198:201], v212 offset:53248
	ds_read_b128 v[202:205], v212 offset:54272
	ds_read_b128 v[214:217], v212 offset:55296
	ds_read_b128 v[218:221], v212 offset:56320
	global_load_lds_dwordx4 v[222:223], off
	s_add_i32 m0, s20, 0x2000
	s_add_u32 s12, s12, 0x40080
	v_lshl_add_u64 v[222:223], v[224:225], 0, s[62:63]
	s_addc_u32 s13, s13, 0
	s_add_i32 s20, s39, s76
	global_load_lds_dwordx4 v[222:223], off
	v_lshl_add_u64 v[222:223], s[12:13], 0, v[164:165]
	s_mov_b32 m0, s20
	s_nop 0
	global_load_lds_dwordx4 v[222:223], off
	v_lshl_add_u64 v[222:223], s[12:13], 0, v[168:169]
	s_add_i32 m0, s20, 0x2000
	s_nop 0
	global_load_lds_dwordx4 v[222:223], off
	v_lshl_add_u64 v[222:223], v[234:235], 0, s[62:63]
	s_mov_b32 m0, s82
	s_nop 0
	global_load_lds_dwordx4 v[222:223], off
	v_lshl_add_u64 v[222:223], v[236:237], 0, s[62:63]
	s_mov_b32 m0, s83
	s_nop 0
	global_load_lds_dwordx4 v[222:223], off
	s_waitcnt vmcnt(8)
	s_waitcnt lgkmcnt(0)
	s_setprio 1
	s_barrier
	v_mfma_f32_16x16x32_bf16 v[62:65], v[122:125], v[182:185], v[62:65]
	v_mfma_f32_16x16x32_bf16 v[58:61], v[138:141], v[182:185], v[58:61]
	v_mfma_f32_16x16x32_bf16 v[46:49], v[122:125], v[190:193], v[46:49]
	v_mfma_f32_16x16x32_bf16 v[42:45], v[138:141], v[190:193], v[42:45]
	v_mfma_f32_16x16x32_bf16 v[30:33], v[122:125], v[198:201], v[30:33]
	v_mfma_f32_16x16x32_bf16 v[26:29], v[138:141], v[198:201], v[26:29]
	v_mfma_f32_16x16x32_bf16 v[14:17], v[122:125], v[214:217], v[14:17]
	v_mfma_f32_16x16x32_bf16 v[10:13], v[138:141], v[214:217], v[10:13]
	v_mfma_f32_16x16x32_bf16 v[62:65], v[134:137], v[186:189], v[62:65]
	v_mfma_f32_16x16x32_bf16 v[58:61], v[142:145], v[186:189], v[58:61]
	v_mfma_f32_16x16x32_bf16 v[46:49], v[134:137], v[194:197], v[46:49]
	v_mfma_f32_16x16x32_bf16 v[42:45], v[142:145], v[194:197], v[42:45]
	v_mfma_f32_16x16x32_bf16 v[30:33], v[134:137], v[202:205], v[30:33]
	v_mfma_f32_16x16x32_bf16 v[26:29], v[142:145], v[202:205], v[26:29]
	v_mfma_f32_16x16x32_bf16 v[14:17], v[134:137], v[218:221], v[14:17]
	v_mfma_f32_16x16x32_bf16 v[10:13], v[142:145], v[218:221], v[10:13]
	v_mfma_f32_16x16x32_bf16 v[54:57], v[146:149], v[182:185], v[54:57]
	v_mfma_f32_16x16x32_bf16 v[50:53], v[154:157], v[182:185], v[50:53]
	v_mfma_f32_16x16x32_bf16 v[38:41], v[146:149], v[190:193], v[38:41]
	v_mfma_f32_16x16x32_bf16 v[34:37], v[154:157], v[190:193], v[34:37]
	v_mfma_f32_16x16x32_bf16 v[22:25], v[146:149], v[198:201], v[22:25]
	v_mfma_f32_16x16x32_bf16 v[18:21], v[154:157], v[198:201], v[18:21]
	v_mfma_f32_16x16x32_bf16 v[6:9], v[146:149], v[214:217], v[6:9]
	v_mfma_f32_16x16x32_bf16 v[2:5], v[154:157], v[214:217], v[2:5]
	v_mfma_f32_16x16x32_bf16 v[54:57], v[150:153], v[186:189], v[54:57]
	v_mfma_f32_16x16x32_bf16 v[50:53], v[158:161], v[186:189], v[50:53]
	v_mfma_f32_16x16x32_bf16 v[38:41], v[150:153], v[194:197], v[38:41]
	v_mfma_f32_16x16x32_bf16 v[34:37], v[158:161], v[194:197], v[34:37]
	v_mfma_f32_16x16x32_bf16 v[22:25], v[150:153], v[202:205], v[22:25]
	v_mfma_f32_16x16x32_bf16 v[18:21], v[158:161], v[202:205], v[18:21]
	v_mfma_f32_16x16x32_bf16 v[6:9], v[150:153], v[218:221], v[6:9]
	v_mfma_f32_16x16x32_bf16 v[2:5], v[158:161], v[218:221], v[2:5]
	s_setprio 0
	s_barrier
	s_add_i32 vcc_lo, vcc_lo, 2
	s_add_u32 s10, s10, 0x100
	s_addc_u32 s11, s11, 0
	s_add_u32 s37, s37, 0x100
	s_addc_u32 s38, s38, 0
	s_cmp_gt_u32 vcc_lo, 13
	s_cbranch_scc0 .LBB0_297
	s_and_b64 vcc, exec, s[22:23]
	s_cbranch_vccz .LBB0_300
	s_barrier

; #define PG8_STAGE(bufoff, gbase, voff) do { _Pragma("unroll") for (int _i = 0; _i < 2; ++_i) \
;         __builtin_amdgcn_global_load_lds((const unsigned*)((const char*)(gbase) + (voff)[_i]), (PG8_LAS unsigned*)(lds + (bufoff) + ldsw + _i * 8192), 16, 0, 0); } while (0)
; #define PG8_LDA(dst, b, h) do { _Pragma("unroll") for (int m = 0; m < 4; ++m) _Pragma("unroll") for (int k = 0; k < 2; ++k) dst[m][k] = *(const PG8_LAS bf16x8*)(lds + PG8_SA(b, h) + aoff + m * 2048 + k * 1024); } while (0)
; #define PG8_MMA(ai, bj, At, Bt) do { __builtin_amdgcn_s_setprio(1); _Pragma("unroll") for (int m = 0; m < 4; ++m) _Pragma("unroll") for (int n = 0; n < 2; ++n) _Pragma("unroll") for (int k = 0; k < 2; ++k) \
;         acc[ai][bj][m][n] = __builtin_amdgcn_mfma_f32_16x16x32_bf16(Bt[n][k], At[m][k], acc[ai][bj][m][n], 0, 0, 0); __builtin_amdgcn_s_setprio(0); } while (0)
; #define PG8_WAIT_V(n) asm volatile("s_waitcnt vmcnt(" #n ")" ::: "memory")
; #define PG8_WAIT_L(n) asm volatile("s_waitcnt lgkmcnt(" #n ")" ::: "memory")
; #define PG8_BAR __builtin_amdgcn_s_barrier()
; #define PG8_SCHED __builtin_amdgcn_sched_barrier(0)
; template <class Epi, class Sched, bool ALIGN_EPI = false, bool SP2 = false>
; __device__ __forceinline__ void gemm_phase(PG8_LAS unsigned char* lds, const Gemm g, const Sched& S, const Epi& E, const int wave_id) {
;     ...
;             PG8_WAIT_V(8); PG8_WAIT_L(0); PG8_BAR; PG8_MMA(0, 0, At, B0); PG8_MMA(0, 1, At, B1); PG8_BAR; PG8_SCHED;
;             PG8_LDA(At, 0, 1); PG8_STAGE(PG8_SB(0, 0), b2, voffB); PG8_STAGE(PG8_SB(0, 1), b2 + hstepB, voffB); PG8_STAGE(PG8_SA(0, 0), a2, voffA);
;             PG8_WAIT_V(8); PG8_WAIT_L(0); PG8_BAR; PG8_MMA(1, 0, At, B0); PG8_MMA(1, 1, At, B1); PG8_BAR; PG8_SCHED;
.Lrw_3:
	s_waitcnt lgkmcnt(0)
	s_setprio 1
	s_barrier
	v_mfma_f32_16x16x32_bf16 v[134:137], v[138:141], v[190:193], v[134:137]
	v_mfma_f32_16x16x32_bf16 v[130:133], v[146:149], v[190:193], v[130:133]
	v_mfma_f32_16x16x32_bf16 v[122:125], v[138:141], v[198:201], v[122:125]
	v_mfma_f32_16x16x32_bf16 v[114:117], v[146:149], v[198:201], v[114:117]
	v_mfma_f32_16x16x32_bf16 v[106:109], v[138:141], v[216:219], v[106:109]
	v_mfma_f32_16x16x32_bf16 v[98:101], v[146:149], v[216:219], v[98:101]
	v_mfma_f32_16x16x32_bf16 v[90:93], v[138:141], v[240:243], v[90:93]
	v_mfma_f32_16x16x32_bf16 v[82:85], v[146:149], v[240:243], v[82:85]
	v_mfma_f32_16x16x32_bf16 v[134:137], v[142:145], v[194:197], v[134:137]
	v_mfma_f32_16x16x32_bf16 v[130:133], v[150:153], v[194:197], v[130:133]
	v_mfma_f32_16x16x32_bf16 v[122:125], v[142:145], v[202:205], v[122:125]
	v_mfma_f32_16x16x32_bf16 v[114:117], v[150:153], v[202:205], v[114:117]
	v_mfma_f32_16x16x32_bf16 v[106:109], v[142:145], v[220:223], v[106:109]
	v_mfma_f32_16x16x32_bf16 v[98:101], v[150:153], v[220:223], v[98:101]
	v_mfma_f32_16x16x32_bf16 v[90:93], v[142:145], v[244:247], v[90:93]
	v_mfma_f32_16x16x32_bf16 v[82:85], v[150:153], v[244:247], v[82:85]
	v_mfma_f32_16x16x32_bf16 v[126:129], v[154:157], v[190:193], v[126:129]
	v_mfma_f32_16x16x32_bf16 v[118:121], v[162:165], v[190:193], v[118:121]
	v_mfma_f32_16x16x32_bf16 v[110:113], v[154:157], v[198:201], v[110:113]
	v_mfma_f32_16x16x32_bf16 v[102:105], v[162:165], v[198:201], v[102:105]
	v_mfma_f32_16x16x32_bf16 v[94:97], v[154:157], v[216:219], v[94:97]
	v_mfma_f32_16x16x32_bf16 v[86:89], v[162:165], v[216:219], v[86:89]
	v_mfma_f32_16x16x32_bf16 v[78:81], v[154:157], v[240:243], v[78:81]
	v_mfma_f32_16x16x32_bf16 v[74:77], v[162:165], v[240:243], v[74:77]
	v_mfma_f32_16x16x32_bf16 v[126:129], v[158:161], v[194:197], v[126:129]
	v_mfma_f32_16x16x32_bf16 v[118:121], v[166:169], v[194:197], v[118:121]
	v_mfma_f32_16x16x32_bf16 v[110:113], v[158:161], v[202:205], v[110:113]
	v_mfma_f32_16x16x32_bf16 v[102:105], v[166:169], v[202:205], v[102:105]
	v_mfma_f32_16x16x32_bf16 v[94:97], v[158:161], v[220:223], v[94:97]
	v_mfma_f32_16x16x32_bf16 v[86:89], v[166:169], v[220:223], v[86:89]
	v_mfma_f32_16x16x32_bf16 v[78:81], v[158:161], v[244:247], v[78:81]
	v_mfma_f32_16x16x32_bf16 v[74:77], v[166:169], v[244:247], v[74:77]
	s_setprio 0
	s_barrier
	s_add_i32 s0, s35, s23
	v_lshl_add_u64 v[206:207], s[26:27], 0, v[180:181]
	s_mov_b32 m0, s0
	ds_read_b128 v[190:193], v215 offset:16384
	ds_read_b128 v[194:197], v215 offset:17408
	ds_read_b128 v[198:201], v215 offset:18432
	ds_read_b128 v[202:205], v215 offset:19456
	ds_read_b128 v[216:219], v215 offset:20480
	ds_read_b128 v[220:223], v215 offset:21504
	ds_read_b128 v[240:243], v215 offset:22528
	ds_read_b128 v[244:247], v215 offset:23552
	global_load_lds_dwordx4 v[206:207], off
	s_add_i32 m0, s0, 0x2000
	s_add_u32 s0, s26, 0x40000
	v_lshl_add_u64 v[224:225], s[26:27], 0, v[184:185]
	s_addc_u32 s1, s27, 0
	s_add_i32 s35, s36, s23
	global_load_lds_dwordx4 v[224:225], off
	v_lshl_add_u64 v[234:235], s[0:1], 0, v[180:181]
	s_mov_b32 m0, s35
	v_lshl_add_u64 v[236:237], s[28:29], 0, v[182:183]
	global_load_lds_dwordx4 v[234:235], off
	v_lshl_add_u64 v[234:235], s[0:1], 0, v[184:185]
	s_add_i32 m0, s35, 0x2000
	s_nop 0
	global_load_lds_dwordx4 v[234:235], off
	v_lshl_add_u64 v[234:235], s[28:29], 0, v[178:179]
	s_mov_b32 m0, s25
	s_nop 0
	global_load_lds_dwordx4 v[234:235], off
	s_mov_b32 m0, s30
	s_nop 0
	global_load_lds_dwordx4 v[236:237], off
	s_waitcnt vmcnt(24)
	s_cmp_eq_u32 s98, 1
	s_cbranch_scc1 .Lrw_4
	s_waitcnt vmcnt(8)
.Lrw_4:
	s_mov_b32 s98, 0
	s_waitcnt lgkmcnt(0)
	s_setprio 1
	s_barrier
	v_mfma_f32_16x16x32_bf16 v[70:73], v[138:141], v[190:193], v[70:73]
	v_mfma_f32_16x16x32_bf16 v[66:69], v[146:149], v[190:193], v[66:69]
	v_mfma_f32_16x16x32_bf16 v[58:61], v[138:141], v[198:201], v[58:61]
	v_mfma_f32_16x16x32_bf16 v[50:53], v[146:149], v[198:201], v[50:53]
	v_mfma_f32_16x16x32_bf16 v[42:45], v[138:141], v[216:219], v[42:45]
	v_mfma_f32_16x16x32_bf16 v[34:37], v[146:149], v[216:219], v[34:37]
	v_mfma_f32_16x16x32_bf16 v[26:29], v[138:141], v[240:243], v[26:29]
	v_mfma_f32_16x16x32_bf16 v[18:21], v[146:149], v[240:243], v[18:21]
	v_mfma_f32_16x16x32_bf16 v[70:73], v[142:145], v[194:197], v[70:73]
	v_mfma_f32_16x16x32_bf16 v[66:69], v[150:153], v[194:197], v[66:69]
	v_mfma_f32_16x16x32_bf16 v[58:61], v[142:145], v[202:205], v[58:61]
	v_mfma_f32_16x16x32_bf16 v[50:53], v[150:153], v[202:205], v[50:53]
	v_mfma_f32_16x16x32_bf16 v[42:45], v[142:145], v[220:223], v[42:45]
	v_mfma_f32_16x16x32_bf16 v[34:37], v[150:153], v[220:223], v[34:37]
	v_mfma_f32_16x16x32_bf16 v[26:29], v[142:145], v[244:247], v[26:29]
	v_mfma_f32_16x16x32_bf16 v[18:21], v[150:153], v[244:247], v[18:21]
	v_mfma_f32_16x16x32_bf16 v[62:65], v[154:157], v[190:193], v[62:65]
	v_mfma_f32_16x16x32_bf16 v[54:57], v[162:165], v[190:193], v[54:57]
	v_mfma_f32_16x16x32_bf16 v[46:49], v[154:157], v[198:201], v[46:49]
	v_mfma_f32_16x16x32_bf16 v[38:41], v[162:165], v[198:201], v[38:41]
	v_mfma_f32_16x16x32_bf16 v[30:33], v[154:157], v[216:219], v[30:33]
	v_mfma_f32_16x16x32_bf16 v[22:25], v[162:165], v[216:219], v[22:25]
	v_mfma_f32_16x16x32_bf16 v[14:17], v[154:157], v[240:243], v[14:17]
	v_mfma_f32_16x16x32_bf16 v[10:13], v[162:165], v[240:243], v[10:13]
	v_mfma_f32_16x16x32_bf16 v[62:65], v[158:161], v[194:197], v[62:65]
	v_mfma_f32_16x16x32_bf16 v[54:57], v[166:169], v[194:197], v[54:57]
	v_mfma_f32_16x16x32_bf16 v[46:49], v[158:161], v[202:205], v[46:49]
	v_mfma_f32_16x16x32_bf16 v[38:41], v[166:169], v[202:205], v[38:41]
	v_mfma_f32_16x16x32_bf16 v[30:33], v[158:161], v[220:223], v[30:33]
	v_mfma_f32_16x16x32_bf16 v[22:25], v[166:169], v[220:223], v[22:25]
	v_mfma_f32_16x16x32_bf16 v[14:17], v[158:161], v[244:247], v[14:17]
	v_mfma_f32_16x16x32_bf16 v[10:13], v[166:169], v[244:247], v[10:13]
	s_setprio 0
	s_barrier
; #define PG8_STAGE(bufoff, gbase, voff) do { _Pragma("unroll") for (int _i = 0; _i < 2; ++_i) \
;         __builtin_amdgcn_global_load_lds((const unsigned*)((const char*)(gbase) + (voff)[_i]), (PG8_LAS unsigned*)(lds + (bufoff) + ldsw + _i * 8192), 16, 0, 0); } while (0)
; #define PG8_LDA(dst, b, h) do { _Pragma("unroll") for (int m = 0; m < 4; ++m) _Pragma("unroll") for (int k = 0; k < 2; ++k) dst[m][k] = *(const PG8_LAS bf16x8*)(lds + PG8_SA(b, h) + aoff + m * 2048 + k * 1024); } while (0)
; #define PG8_LDB(dst, b, h) do { _Pragma("unroll") for (int n = 0; n < 2; ++n) _Pragma("unroll") for (int k = 0; k < 2; ++k) dst[n][k] = *(const PG8_LAS bf16x8*)(lds + PG8_SB(b, h) + boff + n * 2048 + k * 1024); } while (0)
; #define PG8_MMA(ai, bj, At, Bt) do { __builtin_amdgcn_s_setprio(1); _Pragma("unroll") for (int m = 0; m < 4; ++m) _Pragma("unroll") for (int n = 0; n < 2; ++n) _Pragma("unroll") for (int k = 0; k < 2; ++k) \
;         acc[ai][bj][m][n] = __builtin_amdgcn_mfma_f32_16x16x32_bf16(Bt[n][k], At[m][k], acc[ai][bj][m][n], 0, 0, 0); __builtin_amdgcn_s_setprio(0); } while (0)
; #define PG8_WAIT_V(n) asm volatile("s_waitcnt vmcnt(" #n ")" ::: "memory")
; #define PG8_WAIT_L(n) asm volatile("s_waitcnt lgkmcnt(" #n ")" ::: "memory")
; #define PG8_BAR __builtin_amdgcn_s_barrier()
; #define PG8_SCHED __builtin_amdgcn_sched_barrier(0)
; template <class Epi, class Sched, bool ALIGN_EPI = false, bool SP2 = false>
; __device__ __forceinline__ void gemm_phase(PG8_LAS unsigned char* lds, const Gemm g, const Sched& S, const Epi& E, const int wave_id) {
;     ...
;             PG8_LDB(B0, 1, 0); PG8_LDB(B1, 1, 1); PG8_SCHED; PG8_LDA(At, 1, 0); PG8_STAGE(PG8_SA(0, 1), a2 + hstepA, voffA);
;             PG8_WAIT_V(8); PG8_WAIT_L(0); PG8_BAR; PG8_MMA(0, 0, At, B0); PG8_MMA(0, 1, At, B1); PG8_BAR; PG8_SCHED;
	s_add_i32 s35, 0, 0x18000
	v_add_u32_e32 v0, s35, v210
	s_add_i32 s36, 0, 0x1c000
	ds_read_b128 v[138:141], v0
	ds_read_b128 v[142:145], v0 offset:1024
	ds_read_b128 v[146:149], v0 offset:2048
	ds_read_b128 v[150:153], v0 offset:3072
	v_add_u32_e32 v0, s36, v210
	ds_read_b128 v[154:157], v0
	ds_read_b128 v[158:161], v0 offset:1024
	ds_read_b128 v[162:165], v0 offset:2048
	ds_read_b128 v[166:169], v0 offset:3072
	s_add_u32 s0, s28, 0x40000
	s_addc_u32 s1, s29, 0
	s_mov_b32 m0, s31
	v_lshl_add_u64 v[248:249], s[0:1], 0, v[178:179]
	ds_read_b128 v[190:193], v215 offset:32768
	ds_read_b128 v[194:197], v215 offset:33792
	ds_read_b128 v[198:201], v215 offset:34816
	ds_read_b128 v[202:205], v215 offset:35840
	ds_read_b128 v[216:219], v215 offset:36864
	ds_read_b128 v[220:223], v215 offset:37888
	ds_read_b128 v[240:243], v215 offset:38912
	ds_read_b128 v[244:247], v215 offset:39936
	global_load_lds_dwordx4 v[248:249], off
	v_lshl_add_u64 v[248:249], s[0:1], 0, v[182:183]
	s_mov_b32 m0, s34
	s_nop 0
	global_load_lds_dwordx4 v[248:249], off
	s_waitcnt vmcnt(8)
	s_waitcnt lgkmcnt(0)
	s_setprio 1
	s_barrier
	v_mfma_f32_16x16x32_bf16 v[134:137], v[138:141], v[190:193], v[134:137]
	v_mfma_f32_16x16x32_bf16 v[130:133], v[146:149], v[190:193], v[130:133]
	v_mfma_f32_16x16x32_bf16 v[122:125], v[138:141], v[198:201], v[122:125]
	v_mfma_f32_16x16x32_bf16 v[114:117], v[146:149], v[198:201], v[114:117]
	v_mfma_f32_16x16x32_bf16 v[106:109], v[138:141], v[216:219], v[106:109]
	v_mfma_f32_16x16x32_bf16 v[98:101], v[146:149], v[216:219], v[98:101]
	v_mfma_f32_16x16x32_bf16 v[90:93], v[138:141], v[240:243], v[90:93]
	v_mfma_f32_16x16x32_bf16 v[82:85], v[146:149], v[240:243], v[82:85]
	v_mfma_f32_16x16x32_bf16 v[134:137], v[142:145], v[194:197], v[134:137]
	v_mfma_f32_16x16x32_bf16 v[130:133], v[150:153], v[194:197], v[130:133]
	v_mfma_f32_16x16x32_bf16 v[122:125], v[142:145], v[202:205], v[122:125]
	v_mfma_f32_16x16x32_bf16 v[114:117], v[150:153], v[202:205], v[114:117]
	v_mfma_f32_16x16x32_bf16 v[106:109], v[142:145], v[220:223], v[106:109]
	v_mfma_f32_16x16x32_bf16 v[98:101], v[150:153], v[220:223], v[98:101]
	v_mfma_f32_16x16x32_bf16 v[90:93], v[142:145], v[244:247], v[90:93]
	v_mfma_f32_16x16x32_bf16 v[82:85], v[150:153], v[244:247], v[82:85]
	v_mfma_f32_16x16x32_bf16 v[126:129], v[154:157], v[190:193], v[126:129]
	v_mfma_f32_16x16x32_bf16 v[118:121], v[162:165], v[190:193], v[118:121]
	v_mfma_f32_16x16x32_bf16 v[110:113], v[154:157], v[198:201], v[110:113]
	v_mfma_f32_16x16x32_bf16 v[102:105], v[162:165], v[198:201], v[102:105]
	v_mfma_f32_16x16x32_bf16 v[94:97], v[154:157], v[216:219], v[94:97]
	v_mfma_f32_16x16x32_bf16 v[86:89], v[162:165], v[216:219], v[86:89]
	v_mfma_f32_16x16x32_bf16 v[78:81], v[154:157], v[240:243], v[78:81]
	v_mfma_f32_16x16x32_bf16 v[74:77], v[162:165], v[240:243], v[74:77]
	v_mfma_f32_16x16x32_bf16 v[126:129], v[158:161], v[194:197], v[126:129]
	v_mfma_f32_16x16x32_bf16 v[118:121], v[166:169], v[194:197], v[118:121]
	v_mfma_f32_16x16x32_bf16 v[110:113], v[158:161], v[202:205], v[110:113]
	v_mfma_f32_16x16x32_bf16 v[102:105], v[166:169], v[202:205], v[102:105]
	v_mfma_f32_16x16x32_bf16 v[94:97], v[158:161], v[220:223], v[94:97]
	v_mfma_f32_16x16x32_bf16 v[86:89], v[166:169], v[220:223], v[86:89]
	v_mfma_f32_16x16x32_bf16 v[78:81], v[158:161], v[244:247], v[78:81]
	v_mfma_f32_16x16x32_bf16 v[74:77], v[166:169], v[244:247], v[74:77]
	s_setprio 0
	s_barrier
; #define PG8_STAGE(bufoff, gbase, voff) do { _Pragma("unroll") for (int _i = 0; _i < 2; ++_i) \
;         __builtin_amdgcn_global_load_lds((const unsigned*)((const char*)(gbase) + (voff)[_i]), (PG8_LAS unsigned*)(lds + (bufoff) + ldsw + _i * 8192), 16, 0, 0); } while (0)
; #define PG8_LDA(dst, b, h) do { _Pragma("unroll") for (int m = 0; m < 4; ++m) _Pragma("unroll") for (int k = 0; k < 2; ++k) dst[m][k] = *(const PG8_LAS bf16x8*)(lds + PG8_SA(b, h) + aoff + m * 2048 + k * 1024); } while (0)
; #define PG8_MMA(ai, bj, At, Bt) do { __builtin_amdgcn_s_setprio(1); _Pragma("unroll") for (int m = 0; m < 4; ++m) _Pragma("unroll") for (int n = 0; n < 2; ++n) _Pragma("unroll") for (int k = 0; k < 2; ++k) \
;         acc[ai][bj][m][n] = __builtin_amdgcn_mfma_f32_16x16x32_bf16(Bt[n][k], At[m][k], acc[ai][bj][m][n], 0, 0, 0); __builtin_amdgcn_s_setprio(0); } while (0)
; #define PG8_WAIT_V(n) asm volatile("s_waitcnt vmcnt(" #n ")" ::: "memory")
; #define PG8_WAIT_L(n) asm volatile("s_waitcnt lgkmcnt(" #n ")" ::: "memory")
; #define PG8_BAR __builtin_amdgcn_s_barrier()
; #define PG8_SCHED __builtin_amdgcn_sched_barrier(0)
; template <class Epi, class Sched, bool ALIGN_EPI = false, bool SP2 = false>
; __device__ __forceinline__ void gemm_phase(PG8_LAS unsigned char* lds, const Gemm g, const Sched& S, const Epi& E, const int wave_id) {
;     ...
;         for (int t = 0; t < nt; t += 2) {
;     ...
;             PG8_LDA(At, 1, 1); PG8_STAGE(PG8_SB(1, 0), b3, voffB); PG8_STAGE(PG8_SB(1, 1), b3 + hstepB, voffB); PG8_STAGE(PG8_SA(1, 0), a3, voffA);
;             PG8_WAIT_V(8); PG8_WAIT_L(0); PG8_BAR; PG8_MMA(1, 0, At, B0); PG8_MMA(1, 1, At, B1); PG8_BAR; PG8_SCHED;
	s_add_i32 s0, s35, s23
	v_lshl_add_u64 v[206:207], v[206:207], 0, s[62:63]
	s_mov_b32 m0, s0
	ds_read_b128 v[190:193], v215 offset:49152
	ds_read_b128 v[194:197], v215 offset:50176
	ds_read_b128 v[198:201], v215 offset:51200
	ds_read_b128 v[202:205], v215 offset:52224
	ds_read_b128 v[216:219], v215 offset:53248
	ds_read_b128 v[220:223], v215 offset:54272
	ds_read_b128 v[240:243], v215 offset:55296
	ds_read_b128 v[244:247], v215 offset:56320
	global_load_lds_dwordx4 v[206:207], off
	s_add_i32 m0, s0, 0x2000
	s_add_u32 s0, s26, 0x40080
	v_lshl_add_u64 v[206:207], v[224:225], 0, s[62:63]
	s_addc_u32 s1, s27, 0
	s_add_i32 s26, s36, s23
	global_load_lds_dwordx4 v[206:207], off
	v_lshl_add_u64 v[206:207], s[0:1], 0, v[180:181]
	s_mov_b32 m0, s26
	s_nop 0
	global_load_lds_dwordx4 v[206:207], off
	v_lshl_add_u64 v[206:207], s[0:1], 0, v[184:185]
	s_add_i32 m0, s26, 0x2000
	s_nop 0
	global_load_lds_dwordx4 v[206:207], off
	v_lshl_add_u64 v[206:207], v[234:235], 0, s[62:63]
	s_mov_b32 m0, s44
	s_nop 0
	global_load_lds_dwordx4 v[206:207], off
	v_lshl_add_u64 v[206:207], v[236:237], 0, s[62:63]
	s_mov_b32 m0, s45
	s_nop 0
	global_load_lds_dwordx4 v[206:207], off
	s_waitcnt vmcnt(8)
	s_waitcnt lgkmcnt(0)
	s_setprio 1
	s_barrier
	v_mfma_f32_16x16x32_bf16 v[70:73], v[138:141], v[190:193], v[70:73]
	v_mfma_f32_16x16x32_bf16 v[66:69], v[146:149], v[190:193], v[66:69]
	v_mfma_f32_16x16x32_bf16 v[58:61], v[138:141], v[198:201], v[58:61]
	v_mfma_f32_16x16x32_bf16 v[50:53], v[146:149], v[198:201], v[50:53]
	v_mfma_f32_16x16x32_bf16 v[42:45], v[138:141], v[216:219], v[42:45]
	v_mfma_f32_16x16x32_bf16 v[34:37], v[146:149], v[216:219], v[34:37]
	v_mfma_f32_16x16x32_bf16 v[26:29], v[138:141], v[240:243], v[26:29]
	v_mfma_f32_16x16x32_bf16 v[18:21], v[146:149], v[240:243], v[18:21]
	v_mfma_f32_16x16x32_bf16 v[70:73], v[142:145], v[194:197], v[70:73]
	v_mfma_f32_16x16x32_bf16 v[66:69], v[150:153], v[194:197], v[66:69]
	v_mfma_f32_16x16x32_bf16 v[58:61], v[142:145], v[202:205], v[58:61]
	v_mfma_f32_16x16x32_bf16 v[50:53], v[150:153], v[202:205], v[50:53]
	v_mfma_f32_16x16x32_bf16 v[42:45], v[142:145], v[220:223], v[42:45]
	v_mfma_f32_16x16x32_bf16 v[34:37], v[150:153], v[220:223], v[34:37]
	v_mfma_f32_16x16x32_bf16 v[26:29], v[142:145], v[244:247], v[26:29]
	v_mfma_f32_16x16x32_bf16 v[18:21], v[150:153], v[244:247], v[18:21]
	v_mfma_f32_16x16x32_bf16 v[62:65], v[154:157], v[190:193], v[62:65]
	v_mfma_f32_16x16x32_bf16 v[54:57], v[162:165], v[190:193], v[54:57]
	v_mfma_f32_16x16x32_bf16 v[46:49], v[154:157], v[198:201], v[46:49]
	v_mfma_f32_16x16x32_bf16 v[38:41], v[162:165], v[198:201], v[38:41]
	v_mfma_f32_16x16x32_bf16 v[30:33], v[154:157], v[216:219], v[30:33]
	v_mfma_f32_16x16x32_bf16 v[22:25], v[162:165], v[216:219], v[22:25]
	v_mfma_f32_16x16x32_bf16 v[14:17], v[154:157], v[240:243], v[14:17]
	v_mfma_f32_16x16x32_bf16 v[10:13], v[162:165], v[240:243], v[10:13]
	v_mfma_f32_16x16x32_bf16 v[62:65], v[158:161], v[194:197], v[62:65]
	v_mfma_f32_16x16x32_bf16 v[54:57], v[166:169], v[194:197], v[54:57]
	v_mfma_f32_16x16x32_bf16 v[46:49], v[158:161], v[202:205], v[46:49]
	v_mfma_f32_16x16x32_bf16 v[38:41], v[166:169], v[202:205], v[38:41]
	v_mfma_f32_16x16x32_bf16 v[30:33], v[158:161], v[220:223], v[30:33]
	v_mfma_f32_16x16x32_bf16 v[22:25], v[166:169], v[220:223], v[22:25]
	v_mfma_f32_16x16x32_bf16 v[14:17], v[158:161], v[244:247], v[14:17]
	v_mfma_f32_16x16x32_bf16 v[10:13], v[166:169], v[244:247], v[10:13]
	s_setprio 0
	s_barrier
	s_add_i32 s5, s5, 2
	s_add_u32 s8, s8, 0x100
	s_addc_u32 s9, s9, 0
	s_add_u32 vcc_hi, vcc_hi, 0x100
	s_addc_u32 s4, s4, 0
	s_cmp_gt_u32 s5, 13
	s_cbranch_scc0 .LBB0_576

; #define PG8_STAGE(bufoff, gbase, voff) do { _Pragma("unroll") for (int _i = 0; _i < 2; ++_i) \
;         __builtin_amdgcn_global_load_lds((const unsigned*)((const char*)(gbase) + (voff)[_i]), (PG8_LAS unsigned*)(lds + (bufoff) + ldsw + _i * 8192), 16, 0, 0); } while (0)
; #define PG8_LDA(dst, b, h) do { _Pragma("unroll") for (int m = 0; m < 4; ++m) _Pragma("unroll") for (int k = 0; k < 2; ++k) dst[m][k] = *(const PG8_LAS bf16x8*)(lds + PG8_SA(b, h) + aoff + m * 2048 + k * 1024); } while (0)
; #define PG8_MMA(ai, bj, At, Bt) do { __builtin_amdgcn_s_setprio(1); _Pragma("unroll") for (int m = 0; m < 4; ++m) _Pragma("unroll") for (int n = 0; n < 2; ++n) _Pragma("unroll") for (int k = 0; k < 2; ++k) \
;         acc[ai][bj][m][n] = __builtin_amdgcn_mfma_f32_16x16x32_bf16(Bt[n][k], At[m][k], acc[ai][bj][m][n], 0, 0, 0); __builtin_amdgcn_s_setprio(0); } while (0)
; #define PG8_WAIT_V(n) asm volatile("s_waitcnt vmcnt(" #n ")" ::: "memory")
; #define PG8_WAIT_L(n) asm volatile("s_waitcnt lgkmcnt(" #n ")" ::: "memory")
; #define PG8_BAR __builtin_amdgcn_s_barrier()
; #define PG8_SCHED __builtin_amdgcn_sched_barrier(0)
; template <class Epi, class Sched, bool ALIGN_EPI = false, bool SP2 = false>
; __device__ __forceinline__ void gemm_phase(PG8_LAS unsigned char* lds, const Gemm g, const Sched& S, const Epi& E, const int wave_id) {
;     ...
;             PG8_WAIT_V(8); PG8_WAIT_L(0); PG8_BAR; PG8_MMA(0, 0, At, B0); PG8_MMA(0, 1, At, B1); PG8_BAR; PG8_SCHED;
;             PG8_LDA(At, 0, 1); PG8_STAGE(PG8_SB(0, 0), b2, voffB); PG8_STAGE(PG8_SB(0, 1), b2 + hstepB, voffB); PG8_STAGE(PG8_SA(0, 0), a2, voffA);
;             PG8_WAIT_V(8); PG8_WAIT_L(0); PG8_BAR; PG8_MMA(1, 0, At, B0); PG8_MMA(1, 1, At, B1); PG8_BAR; PG8_SCHED;
.Lrw_5:
	s_waitcnt lgkmcnt(0)
	s_setprio 1
	s_barrier
	v_mfma_f32_16x16x32_bf16 v[166:169], v[114:117], v[190:193], v[166:169]
	v_mfma_f32_16x16x32_bf16 v[162:165], v[122:125], v[190:193], v[162:165]
	v_mfma_f32_16x16x32_bf16 v[134:137], v[114:117], v[202:205], v[134:137]
	v_mfma_f32_16x16x32_bf16 v[126:129], v[122:125], v[202:205], v[126:129]
	v_mfma_f32_16x16x32_bf16 v[102:105], v[114:117], v[210:213], v[102:105]
	v_mfma_f32_16x16x32_bf16 v[98:101], v[122:125], v[210:213], v[98:101]
	v_mfma_f32_16x16x32_bf16 v[86:89], v[114:117], v[218:221], v[86:89]
	v_mfma_f32_16x16x32_bf16 v[82:85], v[122:125], v[218:221], v[82:85]
	v_mfma_f32_16x16x32_bf16 v[166:169], v[118:121], v[194:197], v[166:169]
	v_mfma_f32_16x16x32_bf16 v[162:165], v[130:133], v[194:197], v[162:165]
	v_mfma_f32_16x16x32_bf16 v[134:137], v[118:121], v[206:209], v[134:137]
	v_mfma_f32_16x16x32_bf16 v[126:129], v[130:133], v[206:209], v[126:129]
	v_mfma_f32_16x16x32_bf16 v[102:105], v[118:121], v[214:217], v[102:105]
	v_mfma_f32_16x16x32_bf16 v[98:101], v[130:133], v[214:217], v[98:101]
	v_mfma_f32_16x16x32_bf16 v[86:89], v[118:121], v[222:225], v[86:89]
	v_mfma_f32_16x16x32_bf16 v[82:85], v[130:133], v[222:225], v[82:85]
	v_mfma_f32_16x16x32_bf16 v[158:161], v[138:141], v[190:193], v[158:161]
	v_mfma_f32_16x16x32_bf16 v[146:149], v[150:153], v[190:193], v[146:149]
	v_mfma_f32_16x16x32_bf16 v[110:113], v[138:141], v[202:205], v[110:113]
	v_mfma_f32_16x16x32_bf16 v[106:109], v[150:153], v[202:205], v[106:109]
	v_mfma_f32_16x16x32_bf16 v[94:97], v[138:141], v[210:213], v[94:97]
	v_mfma_f32_16x16x32_bf16 v[90:93], v[150:153], v[210:213], v[90:93]
	v_mfma_f32_16x16x32_bf16 v[78:81], v[138:141], v[218:221], v[78:81]
	v_mfma_f32_16x16x32_bf16 v[74:77], v[150:153], v[218:221], v[74:77]
	v_mfma_f32_16x16x32_bf16 v[158:161], v[142:145], v[194:197], v[158:161]
	v_mfma_f32_16x16x32_bf16 v[146:149], v[154:157], v[194:197], v[146:149]
	v_mfma_f32_16x16x32_bf16 v[110:113], v[142:145], v[206:209], v[110:113]
	v_mfma_f32_16x16x32_bf16 v[106:109], v[154:157], v[206:209], v[106:109]
	v_mfma_f32_16x16x32_bf16 v[94:97], v[142:145], v[214:217], v[94:97]
	v_mfma_f32_16x16x32_bf16 v[90:93], v[154:157], v[214:217], v[90:93]
	v_mfma_f32_16x16x32_bf16 v[78:81], v[142:145], v[222:225], v[78:81]
	v_mfma_f32_16x16x32_bf16 v[74:77], v[154:157], v[222:225], v[74:77]
	s_setprio 0
	s_barrier
	s_add_i32 s1, s38, s23
	v_lshl_add_u64 v[198:199], s[26:27], 0, v[180:181]
	s_mov_b32 m0, s1
	ds_read_b128 v[190:193], v245 offset:16384
	ds_read_b128 v[194:197], v245 offset:17408
	ds_read_b128 v[202:205], v245 offset:18432
	ds_read_b128 v[206:209], v245 offset:19456
	ds_read_b128 v[210:213], v245 offset:20480
	ds_read_b128 v[214:217], v245 offset:21504
	ds_read_b128 v[218:221], v245 offset:22528
	ds_read_b128 v[222:225], v245 offset:23552
	global_load_lds_dwordx4 v[198:199], off
	s_add_i32 m0, s1, 0x2000
	s_add_u32 s38, s26, 0x40000
	v_lshl_add_u64 v[234:235], s[26:27], 0, v[184:185]
	s_addc_u32 s39, s27, 0
	s_add_i32 s0, s0, s23
	global_load_lds_dwordx4 v[234:235], off
	v_lshl_add_u64 v[236:237], s[38:39], 0, v[180:181]
	s_mov_b32 m0, s0
	v_lshl_add_u64 v[246:247], s[28:29], 0, v[182:183]
	global_load_lds_dwordx4 v[236:237], off
	v_lshl_add_u64 v[236:237], s[38:39], 0, v[184:185]
	s_add_i32 m0, s0, 0x2000
	s_nop 0
	global_load_lds_dwordx4 v[236:237], off
	v_lshl_add_u64 v[236:237], s[28:29], 0, v[178:179]
	s_mov_b32 m0, s30
	s_nop 0
	global_load_lds_dwordx4 v[236:237], off
	s_mov_b32 m0, s31
	s_nop 0
	global_load_lds_dwordx4 v[246:247], off
	s_waitcnt vmcnt(24)
	s_cmp_eq_u32 s98, 1
	s_cbranch_scc1 .Lrw_6
	s_waitcnt vmcnt(8)
.Lrw_6:
	s_mov_b32 s98, 0
	s_waitcnt lgkmcnt(0)
	s_setprio 1
	s_barrier
	v_mfma_f32_16x16x32_bf16 v[70:73], v[114:117], v[190:193], v[70:73]
	v_mfma_f32_16x16x32_bf16 v[66:69], v[122:125], v[190:193], v[66:69]
	v_mfma_f32_16x16x32_bf16 v[54:57], v[114:117], v[202:205], v[54:57]
	v_mfma_f32_16x16x32_bf16 v[50:53], v[122:125], v[202:205], v[50:53]
	v_mfma_f32_16x16x32_bf16 v[38:41], v[114:117], v[210:213], v[38:41]
	v_mfma_f32_16x16x32_bf16 v[34:37], v[122:125], v[210:213], v[34:37]
	v_mfma_f32_16x16x32_bf16 v[22:25], v[114:117], v[218:221], v[22:25]
	v_mfma_f32_16x16x32_bf16 v[18:21], v[122:125], v[218:221], v[18:21]
	v_mfma_f32_16x16x32_bf16 v[70:73], v[118:121], v[194:197], v[70:73]
	v_mfma_f32_16x16x32_bf16 v[66:69], v[130:133], v[194:197], v[66:69]
	v_mfma_f32_16x16x32_bf16 v[54:57], v[118:121], v[206:209], v[54:57]
	v_mfma_f32_16x16x32_bf16 v[50:53], v[130:133], v[206:209], v[50:53]
	v_mfma_f32_16x16x32_bf16 v[38:41], v[118:121], v[214:217], v[38:41]
	v_mfma_f32_16x16x32_bf16 v[34:37], v[130:133], v[214:217], v[34:37]
	v_mfma_f32_16x16x32_bf16 v[22:25], v[118:121], v[222:225], v[22:25]
	v_mfma_f32_16x16x32_bf16 v[18:21], v[130:133], v[222:225], v[18:21]
	v_mfma_f32_16x16x32_bf16 v[62:65], v[138:141], v[190:193], v[62:65]
	v_mfma_f32_16x16x32_bf16 v[58:61], v[150:153], v[190:193], v[58:61]
	v_mfma_f32_16x16x32_bf16 v[46:49], v[138:141], v[202:205], v[46:49]
	v_mfma_f32_16x16x32_bf16 v[42:45], v[150:153], v[202:205], v[42:45]
	v_mfma_f32_16x16x32_bf16 v[30:33], v[138:141], v[210:213], v[30:33]
	v_mfma_f32_16x16x32_bf16 v[26:29], v[150:153], v[210:213], v[26:29]
	v_mfma_f32_16x16x32_bf16 v[14:17], v[138:141], v[218:221], v[14:17]
	v_mfma_f32_16x16x32_bf16 v[10:13], v[150:153], v[218:221], v[10:13]
	v_mfma_f32_16x16x32_bf16 v[62:65], v[142:145], v[194:197], v[62:65]
	v_mfma_f32_16x16x32_bf16 v[58:61], v[154:157], v[194:197], v[58:61]
	v_mfma_f32_16x16x32_bf16 v[46:49], v[142:145], v[206:209], v[46:49]
	v_mfma_f32_16x16x32_bf16 v[42:45], v[154:157], v[206:209], v[42:45]
	v_mfma_f32_16x16x32_bf16 v[30:33], v[142:145], v[214:217], v[30:33]
	v_mfma_f32_16x16x32_bf16 v[26:29], v[154:157], v[214:217], v[26:29]
	v_mfma_f32_16x16x32_bf16 v[14:17], v[142:145], v[222:225], v[14:17]
	v_mfma_f32_16x16x32_bf16 v[10:13], v[154:157], v[222:225], v[10:13]
	s_setprio 0
	s_barrier
; #define PG8_STAGE(bufoff, gbase, voff) do { _Pragma("unroll") for (int _i = 0; _i < 2; ++_i) \
;         __builtin_amdgcn_global_load_lds((const unsigned*)((const char*)(gbase) + (voff)[_i]), (PG8_LAS unsigned*)(lds + (bufoff) + ldsw + _i * 8192), 16, 0, 0); } while (0)
; #define PG8_LDA(dst, b, h) do { _Pragma("unroll") for (int m = 0; m < 4; ++m) _Pragma("unroll") for (int k = 0; k < 2; ++k) dst[m][k] = *(const PG8_LAS bf16x8*)(lds + PG8_SA(b, h) + aoff + m * 2048 + k * 1024); } while (0)
; #define PG8_LDB(dst, b, h) do { _Pragma("unroll") for (int n = 0; n < 2; ++n) _Pragma("unroll") for (int k = 0; k < 2; ++k) dst[n][k] = *(const PG8_LAS bf16x8*)(lds + PG8_SB(b, h) + boff + n * 2048 + k * 1024); } while (0)
; #define PG8_MMA(ai, bj, At, Bt) do { __builtin_amdgcn_s_setprio(1); _Pragma("unroll") for (int m = 0; m < 4; ++m) _Pragma("unroll") for (int n = 0; n < 2; ++n) _Pragma("unroll") for (int k = 0; k < 2; ++k) \
;         acc[ai][bj][m][n] = __builtin_amdgcn_mfma_f32_16x16x32_bf16(Bt[n][k], At[m][k], acc[ai][bj][m][n], 0, 0, 0); __builtin_amdgcn_s_setprio(0); } while (0)
; #define PG8_WAIT_V(n) asm volatile("s_waitcnt vmcnt(" #n ")" ::: "memory")
; #define PG8_WAIT_L(n) asm volatile("s_waitcnt lgkmcnt(" #n ")" ::: "memory")
; #define PG8_BAR __builtin_amdgcn_s_barrier()
; #define PG8_SCHED __builtin_amdgcn_sched_barrier(0)
; template <class Epi, class Sched, bool ALIGN_EPI = false, bool SP2 = false>
; __device__ __forceinline__ void gemm_phase(PG8_LAS unsigned char* lds, const Gemm g, const Sched& S, const Epi& E, const int wave_id) {
;     ...
;             PG8_LDB(B0, 1, 0); PG8_LDB(B1, 1, 1); PG8_SCHED; PG8_LDA(At, 1, 0); PG8_STAGE(PG8_SA(0, 1), a2 + hstepA, voffA);
;             PG8_WAIT_V(8); PG8_WAIT_L(0); PG8_BAR; PG8_MMA(0, 0, At, B0); PG8_MMA(0, 1, At, B1); PG8_BAR; PG8_SCHED;
	s_add_i32 s0, 0, 0x18000
	v_add_u32_e32 v0, s0, v240
	s_add_i32 s1, 0, 0x1c000
	ds_read_b128 v[114:117], v0
	ds_read_b128 v[118:121], v0 offset:1024
	ds_read_b128 v[122:125], v0 offset:2048
	ds_read_b128 v[130:133], v0 offset:3072
	v_add_u32_e32 v0, s1, v240
	ds_read_b128 v[138:141], v0
	ds_read_b128 v[142:145], v0 offset:1024
	ds_read_b128 v[150:153], v0 offset:2048
	ds_read_b128 v[154:157], v0 offset:3072
	s_add_u32 s28, s28, 0x40000
	s_addc_u32 s29, s29, 0
	s_mov_b32 m0, s34
	v_lshl_add_u64 v[248:249], s[28:29], 0, v[178:179]
	ds_read_b128 v[190:193], v245 offset:32768
	ds_read_b128 v[194:197], v245 offset:33792
	ds_read_b128 v[202:205], v245 offset:34816
	ds_read_b128 v[206:209], v245 offset:35840
	ds_read_b128 v[210:213], v245 offset:36864
	ds_read_b128 v[214:217], v245 offset:37888
	ds_read_b128 v[218:221], v245 offset:38912
	ds_read_b128 v[222:225], v245 offset:39936
	global_load_lds_dwordx4 v[248:249], off
	v_lshl_add_u64 v[248:249], s[28:29], 0, v[182:183]
	s_mov_b32 m0, s35
	s_nop 0
	global_load_lds_dwordx4 v[248:249], off
	s_waitcnt vmcnt(8)
	s_waitcnt lgkmcnt(0)
	s_setprio 1
	s_barrier
	v_mfma_f32_16x16x32_bf16 v[166:169], v[114:117], v[190:193], v[166:169]
	v_mfma_f32_16x16x32_bf16 v[162:165], v[122:125], v[190:193], v[162:165]
	v_mfma_f32_16x16x32_bf16 v[134:137], v[114:117], v[202:205], v[134:137]
	v_mfma_f32_16x16x32_bf16 v[126:129], v[122:125], v[202:205], v[126:129]
	v_mfma_f32_16x16x32_bf16 v[102:105], v[114:117], v[210:213], v[102:105]
	v_mfma_f32_16x16x32_bf16 v[98:101], v[122:125], v[210:213], v[98:101]
	v_mfma_f32_16x16x32_bf16 v[86:89], v[114:117], v[218:221], v[86:89]
	v_mfma_f32_16x16x32_bf16 v[82:85], v[122:125], v[218:221], v[82:85]
	v_mfma_f32_16x16x32_bf16 v[166:169], v[118:121], v[194:197], v[166:169]
	v_mfma_f32_16x16x32_bf16 v[162:165], v[130:133], v[194:197], v[162:165]
	v_mfma_f32_16x16x32_bf16 v[134:137], v[118:121], v[206:209], v[134:137]
	v_mfma_f32_16x16x32_bf16 v[126:129], v[130:133], v[206:209], v[126:129]
	v_mfma_f32_16x16x32_bf16 v[102:105], v[118:121], v[214:217], v[102:105]
	v_mfma_f32_16x16x32_bf16 v[98:101], v[130:133], v[214:217], v[98:101]
	v_mfma_f32_16x16x32_bf16 v[86:89], v[118:121], v[222:225], v[86:89]
	v_mfma_f32_16x16x32_bf16 v[82:85], v[130:133], v[222:225], v[82:85]
	v_mfma_f32_16x16x32_bf16 v[158:161], v[138:141], v[190:193], v[158:161]
	v_mfma_f32_16x16x32_bf16 v[146:149], v[150:153], v[190:193], v[146:149]
	v_mfma_f32_16x16x32_bf16 v[110:113], v[138:141], v[202:205], v[110:113]
	v_mfma_f32_16x16x32_bf16 v[106:109], v[150:153], v[202:205], v[106:109]
	v_mfma_f32_16x16x32_bf16 v[94:97], v[138:141], v[210:213], v[94:97]
	v_mfma_f32_16x16x32_bf16 v[90:93], v[150:153], v[210:213], v[90:93]
	v_mfma_f32_16x16x32_bf16 v[78:81], v[138:141], v[218:221], v[78:81]
	v_mfma_f32_16x16x32_bf16 v[74:77], v[150:153], v[218:221], v[74:77]
	v_mfma_f32_16x16x32_bf16 v[158:161], v[142:145], v[194:197], v[158:161]
	v_mfma_f32_16x16x32_bf16 v[146:149], v[154:157], v[194:197], v[146:149]
	v_mfma_f32_16x16x32_bf16 v[110:113], v[142:145], v[206:209], v[110:113]
	v_mfma_f32_16x16x32_bf16 v[106:109], v[154:157], v[206:209], v[106:109]
	v_mfma_f32_16x16x32_bf16 v[94:97], v[142:145], v[214:217], v[94:97]
	v_mfma_f32_16x16x32_bf16 v[90:93], v[154:157], v[214:217], v[90:93]
	v_mfma_f32_16x16x32_bf16 v[78:81], v[142:145], v[222:225], v[78:81]
	v_mfma_f32_16x16x32_bf16 v[74:77], v[154:157], v[222:225], v[74:77]
	s_setprio 0
	s_barrier
; #define PG8_STAGE(bufoff, gbase, voff) do { _Pragma("unroll") for (int _i = 0; _i < 2; ++_i) \
;         __builtin_amdgcn_global_load_lds((const unsigned*)((const char*)(gbase) + (voff)[_i]), (PG8_LAS unsigned*)(lds + (bufoff) + ldsw + _i * 8192), 16, 0, 0); } while (0)
; #define PG8_LDA(dst, b, h) do { _Pragma("unroll") for (int m = 0; m < 4; ++m) _Pragma("unroll") for (int k = 0; k < 2; ++k) dst[m][k] = *(const PG8_LAS bf16x8*)(lds + PG8_SA(b, h) + aoff + m * 2048 + k * 1024); } while (0)
; #define PG8_MMA(ai, bj, At, Bt) do { __builtin_amdgcn_s_setprio(1); _Pragma("unroll") for (int m = 0; m < 4; ++m) _Pragma("unroll") for (int n = 0; n < 2; ++n) _Pragma("unroll") for (int k = 0; k < 2; ++k) \
;         acc[ai][bj][m][n] = __builtin_amdgcn_mfma_f32_16x16x32_bf16(Bt[n][k], At[m][k], acc[ai][bj][m][n], 0, 0, 0); __builtin_amdgcn_s_setprio(0); } while (0)
; #define PG8_WAIT_V(n) asm volatile("s_waitcnt vmcnt(" #n ")" ::: "memory")
; #define PG8_WAIT_L(n) asm volatile("s_waitcnt lgkmcnt(" #n ")" ::: "memory")
; #define PG8_BAR __builtin_amdgcn_s_barrier()
; #define PG8_SCHED __builtin_amdgcn_sched_barrier(0)
; template <class Epi, class Sched, bool ALIGN_EPI = false, bool SP2 = false>
; __device__ __forceinline__ void gemm_phase(PG8_LAS unsigned char* lds, const Gemm g, const Sched& S, const Epi& E, const int wave_id) {
;     ...
;         for (int t = 0; t < nt; t += 2) {
;     ...
;             PG8_LDA(At, 1, 1); PG8_STAGE(PG8_SB(1, 0), b3, voffB); PG8_STAGE(PG8_SB(1, 1), b3 + hstepB, voffB); PG8_STAGE(PG8_SA(1, 0), a3, voffA);
;             PG8_WAIT_V(8); PG8_WAIT_L(0); PG8_BAR; PG8_MMA(1, 0, At, B0); PG8_MMA(1, 1, At, B1); PG8_BAR; PG8_SCHED;
	s_add_i32 s0, s0, s23
	v_lshl_add_u64 v[198:199], v[198:199], 0, s[62:63]
	s_mov_b32 m0, s0
	ds_read_b128 v[190:193], v245 offset:49152
	ds_read_b128 v[194:197], v245 offset:50176
	ds_read_b128 v[202:205], v245 offset:51200
	ds_read_b128 v[206:209], v245 offset:52224
	ds_read_b128 v[210:213], v245 offset:53248
	ds_read_b128 v[214:217], v245 offset:54272
	ds_read_b128 v[218:221], v245 offset:55296
	ds_read_b128 v[222:225], v245 offset:56320
	global_load_lds_dwordx4 v[198:199], off
	s_add_i32 m0, s0, 0x2000
	s_add_u32 s26, s26, 0x40080
	v_lshl_add_u64 v[198:199], v[234:235], 0, s[62:63]
	s_addc_u32 s27, s27, 0
	s_add_i32 s0, s1, s23
	global_load_lds_dwordx4 v[198:199], off
	v_lshl_add_u64 v[198:199], s[26:27], 0, v[180:181]
	s_mov_b32 m0, s0
	s_nop 0
	global_load_lds_dwordx4 v[198:199], off
	v_lshl_add_u64 v[198:199], s[26:27], 0, v[184:185]
	s_add_i32 m0, s0, 0x2000
	s_nop 0
	global_load_lds_dwordx4 v[198:199], off
	v_lshl_add_u64 v[198:199], v[236:237], 0, s[62:63]
	s_mov_b32 m0, s45
	s_nop 0
	global_load_lds_dwordx4 v[198:199], off
	v_lshl_add_u64 v[198:199], v[246:247], 0, s[62:63]
	s_mov_b32 m0, s76
	s_nop 0
	global_load_lds_dwordx4 v[198:199], off
	s_waitcnt vmcnt(8)
	s_waitcnt lgkmcnt(0)
	s_setprio 1
	s_barrier
	v_mfma_f32_16x16x32_bf16 v[70:73], v[114:117], v[190:193], v[70:73]
	v_mfma_f32_16x16x32_bf16 v[66:69], v[122:125], v[190:193], v[66:69]
	v_mfma_f32_16x16x32_bf16 v[54:57], v[114:117], v[202:205], v[54:57]
	v_mfma_f32_16x16x32_bf16 v[50:53], v[122:125], v[202:205], v[50:53]
	v_mfma_f32_16x16x32_bf16 v[38:41], v[114:117], v[210:213], v[38:41]
	v_mfma_f32_16x16x32_bf16 v[34:37], v[122:125], v[210:213], v[34:37]
	v_mfma_f32_16x16x32_bf16 v[22:25], v[114:117], v[218:221], v[22:25]
	v_mfma_f32_16x16x32_bf16 v[18:21], v[122:125], v[218:221], v[18:21]
	v_mfma_f32_16x16x32_bf16 v[70:73], v[118:121], v[194:197], v[70:73]
	v_mfma_f32_16x16x32_bf16 v[66:69], v[130:133], v[194:197], v[66:69]
	v_mfma_f32_16x16x32_bf16 v[54:57], v[118:121], v[206:209], v[54:57]
	v_mfma_f32_16x16x32_bf16 v[50:53], v[130:133], v[206:209], v[50:53]
	v_mfma_f32_16x16x32_bf16 v[38:41], v[118:121], v[214:217], v[38:41]
	v_mfma_f32_16x16x32_bf16 v[34:37], v[130:133], v[214:217], v[34:37]
	v_mfma_f32_16x16x32_bf16 v[22:25], v[118:121], v[222:225], v[22:25]
	v_mfma_f32_16x16x32_bf16 v[18:21], v[130:133], v[222:225], v[18:21]
	v_mfma_f32_16x16x32_bf16 v[62:65], v[138:141], v[190:193], v[62:65]
	v_mfma_f32_16x16x32_bf16 v[58:61], v[150:153], v[190:193], v[58:61]
	v_mfma_f32_16x16x32_bf16 v[46:49], v[138:141], v[202:205], v[46:49]
	v_mfma_f32_16x16x32_bf16 v[42:45], v[150:153], v[202:205], v[42:45]
	v_mfma_f32_16x16x32_bf16 v[30:33], v[138:141], v[210:213], v[30:33]
	v_mfma_f32_16x16x32_bf16 v[26:29], v[150:153], v[210:213], v[26:29]
	v_mfma_f32_16x16x32_bf16 v[14:17], v[138:141], v[218:221], v[14:17]
	v_mfma_f32_16x16x32_bf16 v[10:13], v[150:153], v[218:221], v[10:13]
	v_mfma_f32_16x16x32_bf16 v[62:65], v[142:145], v[194:197], v[62:65]
	v_mfma_f32_16x16x32_bf16 v[58:61], v[154:157], v[194:197], v[58:61]
	v_mfma_f32_16x16x32_bf16 v[46:49], v[142:145], v[206:209], v[46:49]
	v_mfma_f32_16x16x32_bf16 v[42:45], v[154:157], v[206:209], v[42:45]
	v_mfma_f32_16x16x32_bf16 v[30:33], v[142:145], v[214:217], v[30:33]
	v_mfma_f32_16x16x32_bf16 v[26:29], v[154:157], v[214:217], v[26:29]
	v_mfma_f32_16x16x32_bf16 v[14:17], v[142:145], v[222:225], v[14:17]
	v_mfma_f32_16x16x32_bf16 v[10:13], v[154:157], v[222:225], v[10:13]
	s_setprio 0
	s_barrier
	s_add_i32 s37, s37, 2
	s_add_u32 s8, s8, 0x100
	s_addc_u32 s9, s9, 0
	s_add_u32 vcc_lo, vcc_lo, 0x100
	s_addc_u32 vcc_hi, vcc_hi, 0
	s_cmp_gt_u32 s37, 13
	s_cbranch_scc0 .LBB0_627
	s_and_b64 vcc, exec, s[12:13]
	s_cbranch_vccz .LBB0_630
	s_barrier
